# GEMM K-loops: all per-segment s_setprio toggles deleted (static priority 0 everywhere)
# speedup vs baseline: 1.0038x; 1.0038x over previous
; #define PG8_STAGE(bufoff, gbase, voff) do { _Pragma("unroll") for (int _i = 0; _i < 2; ++_i) \
;         __builtin_amdgcn_global_load_lds((const unsigned*)((const char*)(gbase) + (voff)[_i]), (PG8_LAS unsigned*)(lds + (bufoff) + ldsw + _i * 8192), 16, 0, 0); } while (0)
; #define PG8_LDA(dst, b, h) do { _Pragma("unroll") for (int m = 0; m < 4; ++m) _Pragma("unroll") for (int k = 0; k < 2; ++k) dst[m][k] = *(const PG8_LAS bf16x8*)(lds + PG8_SA(b, h) + aoff + m * 2048 + k * 1024); } while (0)
; #define PG8_LDB(dst, b, h) do { _Pragma("unroll") for (int n = 0; n < 2; ++n) _Pragma("unroll") for (int k = 0; k < 2; ++k) dst[n][k] = *(const PG8_LAS bf16x8*)(lds + PG8_SB(b, h) + boff + n * 2048 + k * 1024); } while (0)
; #define PG8_MMA(ai, bj, At, Bt) do { __builtin_amdgcn_s_setprio(1); _Pragma("unroll") for (int m = 0; m < 4; ++m) _Pragma("unroll") for (int n = 0; n < 2; ++n) _Pragma("unroll") for (int k = 0; k < 2; ++k) \
;         acc[ai][bj][m][n] = __builtin_amdgcn_mfma_f32_16x16x32_bf16(Bt[n][k], At[m][k], acc[ai][bj][m][n], 0, 0, 0); __builtin_amdgcn_s_setprio(0); } while (0)
; #define PG8_WAIT_V(n) asm volatile("s_waitcnt vmcnt(" #n ")" ::: "memory")
; #define PG8_BAR __builtin_amdgcn_s_barrier()
; template <class Epi, class Sched, bool ALIGN_EPI = false, bool SP2 = false>
; __device__ __forceinline__ void gemm_phase(PG8_LAS unsigned char* lds, const Gemm g, const Sched& S, const Epi& E) {
;     ...
;         for (int t = 0; t < nt; t += 2) {
;             const bool last = (t == nt - 2);
;             const char* a1 = cA + (size_t)(t + 1) * kstep;
;             const char* a2 = last ? nA : cA + (size_t)(t + 2) * kstep; const char* b2 = last ? nB : cB + (size_t)(t + 2) * kstep;
;             const char* a3 = a2 + kstep; const char* b3 = b2 + kstep;
;             if (last && has_next) S.a_ready(nxt);
;             if constexpr (SP2) {
;             PG8_LDB(B0, 0, 0); PG8_LDB(B1, 0, 1); PG8_SCHED; PG8_LDA(At, 0, 0); PG8_STAGE(PG8_SA(1, 1), a1 + hstepA, voffA);
;             PG8_WAIT_V(8); PG8_WAIT_L(0); PG8_BAR; PG8_MMA(0, 0, At, B0); PG8_MMA(0, 1, At, B1); PG8_BAR; PG8_SCHED;
;             PG8_LDA(At, 0, 1); PG8_STAGE(PG8_SB(0, 0), b2, voffB); PG8_STAGE(PG8_SB(0, 1), b2 + hstepB, voffB); PG8_STAGE(PG8_SA(0, 0), a2, voffA);
;             PG8_WAIT_V(8); PG8_WAIT_L(0); PG8_BAR; PG8_MMA(1, 0, At, B0); PG8_MMA(1, 1, At, B1); PG8_BAR; PG8_SCHED;
.LBB0_163:
	ds_read_b128 v[0:3], v143
	ds_read_b128 v[4:7], v143 offset:1024
	ds_read_b128 v[8:11], v143 offset:2048
	ds_read_b128 v[12:15], v143 offset:3072
	ds_read_b128 v[16:19], v144
	ds_read_b128 v[20:23], v144 offset:1024
	ds_read_b128 v[24:27], v144 offset:2048
	ds_read_b128 v[28:31], v144 offset:3072
	s_ashr_i32 s31, s30, 31
	s_lshl_b64 s[34:35], s[30:31], 17
	s_add_u32 s34, s54, s34
	s_addc_u32 s35, s55, s35
	s_and_b64 s[36:37], s[0:1], exec
	s_cselect_b32 s51, s35, s39
	s_cselect_b32 s50, s34, s38
	s_ashr_i32 s29, s28, 31
	s_lshl_b64 s[36:37], s[28:29], 17
	s_add_u32 s36, s2, s36
	s_addc_u32 s37, s3, s37
	s_and_b64 s[44:45], s[0:1], exec
	s_cselect_b32 s47, s37, s41
	s_cselect_b32 s46, s36, s40
	s_add_u32 s44, s38, 0x10080
	s_addc_u32 s45, s39, 0
	s_add_i32 s63, s9, 0xc000
	v_lshl_add_u64 v[64:65], s[44:45], 0, v[128:129]
	s_mov_b32 m0, s63
	s_add_i32 s29, s9, 0xe000
	ds_read_b128 v[32:35], v145
	ds_read_b128 v[36:39], v145 offset:1024
	ds_read_b128 v[40:43], v145 offset:2048
	ds_read_b128 v[44:47], v145 offset:3072
	ds_read_b128 v[48:51], v145 offset:4096
	ds_read_b128 v[52:55], v145 offset:5120
	ds_read_b128 v[56:59], v145 offset:6144
	ds_read_b128 v[60:63], v145 offset:7168
	global_load_lds_dwordx4 v[64:65], off
	v_lshl_add_u64 v[64:65], s[44:45], 0, v[132:133]
	s_mov_b32 m0, s29
	s_nop 0
	global_load_lds_dwordx4 v[64:65], off
	s_waitcnt vmcnt(8)
	s_waitcnt lgkmcnt(0)
	s_barrier
	s_waitcnt lgkmcnt(0)
	v_mfma_f32_16x16x32_bf16 v[64:67], v[0:3], v[32:35], 0
	v_mfma_f32_16x16x32_bf16 v[68:71], v[8:11], v[32:35], 0
	v_mfma_f32_16x16x32_bf16 v[72:75], v[0:3], v[40:43], 0
	v_mfma_f32_16x16x32_bf16 v[76:79], v[8:11], v[40:43], 0
	v_mfma_f32_16x16x32_bf16 v[80:83], v[0:3], v[48:51], 0
	v_mfma_f32_16x16x32_bf16 v[84:87], v[8:11], v[48:51], 0
	v_mfma_f32_16x16x32_bf16 v[88:91], v[0:3], v[56:59], 0
	v_mfma_f32_16x16x32_bf16 v[92:95], v[8:11], v[56:59], 0
	v_mfma_f32_16x16x32_bf16 v[64:67], v[4:7], v[36:39], v[64:67]
	v_mfma_f32_16x16x32_bf16 v[68:71], v[12:15], v[36:39], v[68:71]
	v_mfma_f32_16x16x32_bf16 v[72:75], v[4:7], v[44:47], v[72:75]
	v_mfma_f32_16x16x32_bf16 v[76:79], v[12:15], v[44:47], v[76:79]
	v_mfma_f32_16x16x32_bf16 v[80:83], v[4:7], v[52:55], v[80:83]
	v_mfma_f32_16x16x32_bf16 v[84:87], v[12:15], v[52:55], v[84:87]
	v_mfma_f32_16x16x32_bf16 v[88:91], v[4:7], v[60:63], v[88:91]
	v_mfma_f32_16x16x32_bf16 v[92:95], v[12:15], v[60:63], v[92:95]
	v_mfma_f32_16x16x32_bf16 v[96:99], v[16:19], v[32:35], 0
	v_mfma_f32_16x16x32_bf16 v[32:35], v[24:27], v[32:35], 0
	v_mfma_f32_16x16x32_bf16 v[96:99], v[20:23], v[36:39], v[96:99]
	v_mfma_f32_16x16x32_bf16 v[32:35], v[28:31], v[36:39], v[32:35]
	v_mfma_f32_16x16x32_bf16 v[36:39], v[16:19], v[40:43], 0
	v_mfma_f32_16x16x32_bf16 v[40:43], v[24:27], v[40:43], 0
	v_mfma_f32_16x16x32_bf16 v[36:39], v[20:23], v[44:47], v[36:39]
	v_mfma_f32_16x16x32_bf16 v[40:43], v[28:31], v[44:47], v[40:43]
	v_mfma_f32_16x16x32_bf16 v[44:47], v[16:19], v[48:51], 0
	v_mfma_f32_16x16x32_bf16 v[48:51], v[24:27], v[48:51], 0
	v_mfma_f32_16x16x32_bf16 v[44:47], v[20:23], v[52:55], v[44:47]
	v_mfma_f32_16x16x32_bf16 v[48:51], v[28:31], v[52:55], v[48:51]
	v_mfma_f32_16x16x32_bf16 v[52:55], v[16:19], v[56:59], 0
	v_mfma_f32_16x16x32_bf16 v[56:59], v[24:27], v[56:59], 0
	v_mfma_f32_16x16x32_bf16 v[52:55], v[20:23], v[60:63], v[52:55]
	v_mfma_f32_16x16x32_bf16 v[56:59], v[28:31], v[60:63], v[56:59]
	s_barrier
	s_add_i32 s48, s59, s8
	v_lshl_add_u64 v[190:191], s[40:41], 0, v[130:131]
	s_add_i32 s31, s48, 0x2000
	v_lshl_add_u64 v[146:147], v[190:191], 0, s[22:23]
	s_mov_b32 m0, s48
	v_lshl_add_u64 v[216:217], s[40:41], 0, v[134:135]
	s_add_u32 s64, s40, 0x10100
	ds_read_b128 v[60:63], v145 offset:16384
	ds_read_b128 v[100:103], v145 offset:17408
	ds_read_b128 v[104:107], v145 offset:18432
	ds_read_b128 v[108:111], v145 offset:19456
	ds_read_b128 v[112:115], v145 offset:20480
	ds_read_b128 v[116:119], v145 offset:21504
	ds_read_b128 v[120:123], v145 offset:22528
	ds_read_b128 v[124:127], v145 offset:23552
	global_load_lds_dwordx4 v[146:147], off
	v_lshl_add_u64 v[146:147], v[216:217], 0, s[22:23]
	s_mov_b32 m0, s31
	s_addc_u32 s65, s41, 0
	s_add_i32 s44, s60, s8
	global_load_lds_dwordx4 v[146:147], off
	v_lshl_add_u64 v[146:147], s[64:65], 0, v[130:131]
	s_mov_b32 m0, s44
	s_add_i32 s45, s44, 0x2000
	global_load_lds_dwordx4 v[146:147], off
	v_lshl_add_u64 v[146:147], s[64:65], 0, v[134:135]
	s_mov_b32 m0, s45
	v_lshl_add_u64 v[218:219], s[38:39], 0, v[128:129]
	global_load_lds_dwordx4 v[146:147], off
	v_lshl_add_u64 v[146:147], v[218:219], 0, s[22:23]
	s_mov_b32 m0, s9
	v_lshl_add_u64 v[220:221], s[38:39], 0, v[132:133]
	global_load_lds_dwordx4 v[146:147], off
	v_lshl_add_u64 v[146:147], v[220:221], 0, s[22:23]
	s_mov_b32 m0, s27
	s_nop 0
	global_load_lds_dwordx4 v[146:147], off
	s_waitcnt vmcnt(8)
	s_waitcnt lgkmcnt(0)
	s_barrier
; #define PG8_STAGE(bufoff, gbase, voff) do { _Pragma("unroll") for (int _i = 0; _i < 2; ++_i) \
;         __builtin_amdgcn_global_load_lds((const unsigned*)((const char*)(gbase) + (voff)[_i]), (PG8_LAS unsigned*)(lds + (bufoff) + ldsw + _i * 8192), 16, 0, 0); } while (0)
; #define PG8_LDA(dst, b, h) do { _Pragma("unroll") for (int m = 0; m < 4; ++m) _Pragma("unroll") for (int k = 0; k < 2; ++k) dst[m][k] = *(const PG8_LAS bf16x8*)(lds + PG8_SA(b, h) + aoff + m * 2048 + k * 1024); } while (0)
; #define PG8_LDB(dst, b, h) do { _Pragma("unroll") for (int n = 0; n < 2; ++n) _Pragma("unroll") for (int k = 0; k < 2; ++k) dst[n][k] = *(const PG8_LAS bf16x8*)(lds + PG8_SB(b, h) + boff + n * 2048 + k * 1024); } while (0)
; #define PG8_MMA(ai, bj, At, Bt) do { __builtin_amdgcn_s_setprio(1); _Pragma("unroll") for (int m = 0; m < 4; ++m) _Pragma("unroll") for (int n = 0; n < 2; ++n) _Pragma("unroll") for (int k = 0; k < 2; ++k) \
;         acc[ai][bj][m][n] = __builtin_amdgcn_mfma_f32_16x16x32_bf16(Bt[n][k], At[m][k], acc[ai][bj][m][n], 0, 0, 0); __builtin_amdgcn_s_setprio(0); } while (0)
; #define PG8_WAIT_V(n) asm volatile("s_waitcnt vmcnt(" #n ")" ::: "memory")
; #define PG8_WAIT_L(n) asm volatile("s_waitcnt lgkmcnt(" #n ")" ::: "memory")
; #define PG8_BAR __builtin_amdgcn_s_barrier()
; #define PG8_SCHED __builtin_amdgcn_sched_barrier(0)
; template <class Epi, class Sched, bool ALIGN_EPI = false, bool SP2 = false>
; __device__ __forceinline__ void gemm_phase(PG8_LAS unsigned char* lds, const Gemm g, const Sched& S, const Epi& E) {
;     ...
;             PG8_WAIT_V(8); PG8_WAIT_L(0); PG8_BAR; PG8_MMA(1, 0, At, B0); PG8_MMA(1, 1, At, B1); PG8_BAR; PG8_SCHED;
;             PG8_LDB(B0, 1, 0); PG8_LDB(B1, 1, 1); PG8_SCHED; PG8_LDA(At, 1, 0); PG8_STAGE(PG8_SA(0, 1), a2 + hstepA, voffA);
;             PG8_WAIT_V(8); PG8_WAIT_L(0); PG8_BAR; PG8_MMA(0, 0, At, B0); PG8_MMA(0, 1, At, B1); PG8_BAR; PG8_SCHED;
	s_waitcnt lgkmcnt(0)
	v_mfma_f32_16x16x32_bf16 v[146:149], v[0:3], v[60:63], 0
	v_mfma_f32_16x16x32_bf16 v[154:157], v[0:3], v[104:107], 0
	v_mfma_f32_16x16x32_bf16 v[162:165], v[0:3], v[112:115], 0
	v_mfma_f32_16x16x32_bf16 v[0:3], v[0:3], v[120:123], 0
	v_mfma_f32_16x16x32_bf16 v[146:149], v[4:7], v[100:103], v[146:149]
	v_mfma_f32_16x16x32_bf16 v[154:157], v[4:7], v[108:111], v[154:157]
	v_mfma_f32_16x16x32_bf16 v[162:165], v[4:7], v[116:119], v[162:165]
	v_mfma_f32_16x16x32_bf16 v[0:3], v[4:7], v[124:127], v[0:3]
	v_mfma_f32_16x16x32_bf16 v[4:7], v[8:11], v[120:123], 0
	v_mfma_f32_16x16x32_bf16 v[150:153], v[8:11], v[60:63], 0
	v_mfma_f32_16x16x32_bf16 v[158:161], v[8:11], v[104:107], 0
	v_mfma_f32_16x16x32_bf16 v[166:169], v[8:11], v[112:115], 0
	v_mfma_f32_16x16x32_bf16 v[4:7], v[12:15], v[124:127], v[4:7]
	v_mfma_f32_16x16x32_bf16 v[150:153], v[12:15], v[100:103], v[150:153]
	v_mfma_f32_16x16x32_bf16 v[158:161], v[12:15], v[108:111], v[158:161]
	v_mfma_f32_16x16x32_bf16 v[166:169], v[12:15], v[116:119], v[166:169]
	v_mfma_f32_16x16x32_bf16 v[8:11], v[16:19], v[60:63], 0
	v_mfma_f32_16x16x32_bf16 v[12:15], v[24:27], v[60:63], 0
	v_mfma_f32_16x16x32_bf16 v[8:11], v[20:23], v[100:103], v[8:11]
	v_mfma_f32_16x16x32_bf16 v[12:15], v[28:31], v[100:103], v[12:15]
	v_mfma_f32_16x16x32_bf16 v[60:63], v[16:19], v[104:107], 0
	v_mfma_f32_16x16x32_bf16 v[100:103], v[24:27], v[104:107], 0
	v_mfma_f32_16x16x32_bf16 v[104:107], v[16:19], v[112:115], 0
	v_mfma_f32_16x16x32_bf16 v[16:19], v[16:19], v[120:123], 0
	v_mfma_f32_16x16x32_bf16 v[60:63], v[20:23], v[108:111], v[60:63]
	v_mfma_f32_16x16x32_bf16 v[100:103], v[28:31], v[108:111], v[100:103]
	v_mfma_f32_16x16x32_bf16 v[104:107], v[20:23], v[116:119], v[104:107]
	v_mfma_f32_16x16x32_bf16 v[108:111], v[24:27], v[112:115], 0
	v_mfma_f32_16x16x32_bf16 v[16:19], v[20:23], v[124:127], v[16:19]
	v_mfma_f32_16x16x32_bf16 v[20:23], v[24:27], v[120:123], 0
	v_mfma_f32_16x16x32_bf16 v[108:111], v[28:31], v[116:119], v[108:111]
	v_mfma_f32_16x16x32_bf16 v[20:23], v[28:31], v[124:127], v[20:23]
	s_barrier
	s_add_i32 s49, 0, 0x18000
	s_add_i32 s68, 0, 0x1c000
	v_add_u32_e32 v224, s49, v142
	v_add_u32_e32 v228, s68, v142
	ds_read_b128 v[24:27], v224
	ds_read_b128 v[28:31], v224 offset:1024
	ds_read_b128 v[112:115], v224 offset:2048
	ds_read_b128 v[116:119], v224 offset:3072
	ds_read_b128 v[120:123], v228
	ds_read_b128 v[124:127], v228 offset:1024
	ds_read_b128 v[170:173], v228 offset:2048
	ds_read_b128 v[174:177], v228 offset:3072
	s_add_u32 s64, s38, 0x10100
	s_addc_u32 s65, s39, 0
	s_mov_b32 m0, s33
	v_lshl_add_u64 v[222:223], s[64:65], 0, v[128:129]
	ds_read_b128 v[178:181], v145 offset:32768
	ds_read_b128 v[182:185], v145 offset:33792
	ds_read_b128 v[186:189], v145 offset:34816
	ds_read_b128 v[196:199], v145 offset:35840
	ds_read_b128 v[200:203], v145 offset:36864
	ds_read_b128 v[204:207], v145 offset:37888
	ds_read_b128 v[208:211], v145 offset:38912
	ds_read_b128 v[212:215], v145 offset:39936
	global_load_lds_dwordx4 v[222:223], off
	v_lshl_add_u64 v[222:223], s[64:65], 0, v[132:133]
	s_mov_b32 m0, s42
	s_nop 0
	global_load_lds_dwordx4 v[222:223], off
	s_waitcnt vmcnt(8)
	s_waitcnt lgkmcnt(0)
	s_barrier
	s_waitcnt lgkmcnt(0)
	v_mfma_f32_16x16x32_bf16 v[64:67], v[24:27], v[178:181], v[64:67]
	v_mfma_f32_16x16x32_bf16 v[68:71], v[112:115], v[178:181], v[68:71]
	v_mfma_f32_16x16x32_bf16 v[72:75], v[24:27], v[186:189], v[72:75]
	v_mfma_f32_16x16x32_bf16 v[76:79], v[112:115], v[186:189], v[76:79]
	v_mfma_f32_16x16x32_bf16 v[80:83], v[24:27], v[200:203], v[80:83]
	v_mfma_f32_16x16x32_bf16 v[84:87], v[112:115], v[200:203], v[84:87]
	v_mfma_f32_16x16x32_bf16 v[88:91], v[24:27], v[208:211], v[88:91]
	v_mfma_f32_16x16x32_bf16 v[92:95], v[112:115], v[208:211], v[92:95]
	v_mfma_f32_16x16x32_bf16 v[64:67], v[28:31], v[182:185], v[64:67]
	v_mfma_f32_16x16x32_bf16 v[68:71], v[116:119], v[182:185], v[68:71]
	v_mfma_f32_16x16x32_bf16 v[72:75], v[28:31], v[196:199], v[72:75]
	v_mfma_f32_16x16x32_bf16 v[76:79], v[116:119], v[196:199], v[76:79]
	v_mfma_f32_16x16x32_bf16 v[80:83], v[28:31], v[204:207], v[80:83]
	v_mfma_f32_16x16x32_bf16 v[84:87], v[116:119], v[204:207], v[84:87]
	v_mfma_f32_16x16x32_bf16 v[88:91], v[28:31], v[212:215], v[88:91]
	v_mfma_f32_16x16x32_bf16 v[92:95], v[116:119], v[212:215], v[92:95]
	v_mfma_f32_16x16x32_bf16 v[96:99], v[120:123], v[178:181], v[96:99]
	v_mfma_f32_16x16x32_bf16 v[32:35], v[170:173], v[178:181], v[32:35]
	v_mfma_f32_16x16x32_bf16 v[36:39], v[120:123], v[186:189], v[36:39]
	v_mfma_f32_16x16x32_bf16 v[40:43], v[170:173], v[186:189], v[40:43]
	v_mfma_f32_16x16x32_bf16 v[44:47], v[120:123], v[200:203], v[44:47]
	v_mfma_f32_16x16x32_bf16 v[48:51], v[170:173], v[200:203], v[48:51]
	v_mfma_f32_16x16x32_bf16 v[52:55], v[120:123], v[208:211], v[52:55]
	v_mfma_f32_16x16x32_bf16 v[56:59], v[170:173], v[208:211], v[56:59]
	v_mfma_f32_16x16x32_bf16 v[96:99], v[124:127], v[182:185], v[96:99]
	v_mfma_f32_16x16x32_bf16 v[32:35], v[174:177], v[182:185], v[32:35]
	v_mfma_f32_16x16x32_bf16 v[36:39], v[124:127], v[196:199], v[36:39]
	v_mfma_f32_16x16x32_bf16 v[40:43], v[174:177], v[196:199], v[40:43]
	v_mfma_f32_16x16x32_bf16 v[44:47], v[124:127], v[204:207], v[44:47]
	v_mfma_f32_16x16x32_bf16 v[48:51], v[174:177], v[204:207], v[48:51]
	v_mfma_f32_16x16x32_bf16 v[52:55], v[124:127], v[212:215], v[52:55]
	v_mfma_f32_16x16x32_bf16 v[56:59], v[174:177], v[212:215], v[56:59]
	s_barrier
; #define PG8_STAGE(bufoff, gbase, voff) do { _Pragma("unroll") for (int _i = 0; _i < 2; ++_i) \
;         __builtin_amdgcn_global_load_lds((const unsigned*)((const char*)(gbase) + (voff)[_i]), (PG8_LAS unsigned*)(lds + (bufoff) + ldsw + _i * 8192), 16, 0, 0); } while (0)
; #define PG8_LDA(dst, b, h) do { _Pragma("unroll") for (int m = 0; m < 4; ++m) _Pragma("unroll") for (int k = 0; k < 2; ++k) dst[m][k] = *(const PG8_LAS bf16x8*)(lds + PG8_SA(b, h) + aoff + m * 2048 + k * 1024); } while (0)
; #define PG8_LDB(dst, b, h) do { _Pragma("unroll") for (int n = 0; n < 2; ++n) _Pragma("unroll") for (int k = 0; k < 2; ++k) dst[n][k] = *(const PG8_LAS bf16x8*)(lds + PG8_SB(b, h) + boff + n * 2048 + k * 1024); } while (0)
; #define PG8_MMA(ai, bj, At, Bt) do { __builtin_amdgcn_s_setprio(1); _Pragma("unroll") for (int m = 0; m < 4; ++m) _Pragma("unroll") for (int n = 0; n < 2; ++n) _Pragma("unroll") for (int k = 0; k < 2; ++k) \
;         acc[ai][bj][m][n] = __builtin_amdgcn_mfma_f32_16x16x32_bf16(Bt[n][k], At[m][k], acc[ai][bj][m][n], 0, 0, 0); __builtin_amdgcn_s_setprio(0); } while (0)
; #define PG8_WAIT_V(n) asm volatile("s_waitcnt vmcnt(" #n ")" ::: "memory")
; template <class Epi, class Sched, bool ALIGN_EPI = false, bool SP2 = false>
; __device__ __forceinline__ void gemm_phase(PG8_LAS unsigned char* lds, const Gemm g, const Sched& S, const Epi& E) {
;     ...
;             PG8_LDB(B0, 0, 0); PG8_LDB(B1, 0, 1); PG8_SCHED; PG8_LDA(At, 0, 0); PG8_STAGE(PG8_SA(1, 1), a1 + hstepA, voffA);
;             PG8_WAIT_V(8); PG8_WAIT_L(0); PG8_BAR; PG8_MMA(0, 0, At, B0); PG8_MMA(0, 1, At, B1); PG8_BAR; PG8_SCHED;
;             PG8_LDA(At, 0, 1); PG8_STAGE(PG8_SB(0, 0), b2, voffB); PG8_STAGE(PG8_SB(0, 1), b2 + hstepB, voffB); PG8_STAGE(PG8_SA(0, 0), a2, voffA);
;             PG8_WAIT_V(8); PG8_WAIT_L(0); PG8_BAR; PG8_MMA(1, 0, At, B0); PG8_MMA(1, 1, At, B1); PG8_BAR; PG8_SCHED;
;             PG8_LDB(B0, 1, 0); PG8_LDB(B1, 1, 1); PG8_SCHED; PG8_LDA(At, 1, 0); PG8_STAGE(PG8_SA(0, 1), a2 + hstepA, voffA);
;             PG8_WAIT_V(8); PG8_WAIT_L(0); PG8_BAR; PG8_MMA(0, 0, At, B0); PG8_MMA(0, 1, At, B1); PG8_BAR; PG8_SCHED;
;             PG8_LDA(At, 1, 1); PG8_STAGE(PG8_SB(1, 0), b3, voffB); PG8_STAGE(PG8_SB(1, 1), b3 + hstepB, voffB); PG8_STAGE(PG8_SA(1, 0), a3, voffA);
;             PG8_WAIT_V(8); PG8_WAIT_L(0); PG8_BAR; PG8_MMA(1, 0, At, B0); PG8_MMA(1, 1, At, B1); PG8_BAR; PG8_SCHED;
	s_add_i32 s64, s49, s8
	s_add_i32 s49, s64, 0x2000
	v_lshl_add_u64 v[190:191], v[190:191], 0, s[24:25]
	s_mov_b32 m0, s64
	s_add_u32 s66, s40, 0x10180
	ds_read_b128 v[178:181], v145 offset:49152
	ds_read_b128 v[182:185], v145 offset:50176
	ds_read_b128 v[186:189], v145 offset:51200
	ds_read_b128 v[196:199], v145 offset:52224
	ds_read_b128 v[200:203], v145 offset:53248
	ds_read_b128 v[204:207], v145 offset:54272
	ds_read_b128 v[208:211], v145 offset:55296
	ds_read_b128 v[212:215], v145 offset:56320
	global_load_lds_dwordx4 v[190:191], off
	v_lshl_add_u64 v[190:191], v[216:217], 0, s[24:25]
	s_mov_b32 m0, s49
	s_addc_u32 s67, s41, 0
	s_add_i32 s40, s68, s8
	global_load_lds_dwordx4 v[190:191], off
	v_lshl_add_u64 v[190:191], s[66:67], 0, v[130:131]
	s_mov_b32 m0, s40
	s_add_i32 s41, s40, 0x2000
	global_load_lds_dwordx4 v[190:191], off
	v_lshl_add_u64 v[190:191], s[66:67], 0, v[134:135]
	s_mov_b32 m0, s41
	s_nop 0
	global_load_lds_dwordx4 v[190:191], off
	v_lshl_add_u64 v[190:191], v[218:219], 0, s[24:25]
	s_mov_b32 m0, s53
	s_nop 0
	global_load_lds_dwordx4 v[190:191], off
	v_lshl_add_u64 v[190:191], v[220:221], 0, s[24:25]
	s_mov_b32 m0, s56
	s_nop 0
	global_load_lds_dwordx4 v[190:191], off
	s_waitcnt vmcnt(8)
	s_waitcnt lgkmcnt(0)
	s_barrier
	s_waitcnt lgkmcnt(0)
	v_mfma_f32_16x16x32_bf16 v[0:3], v[24:27], v[208:211], v[0:3]
	v_mfma_f32_16x16x32_bf16 v[4:7], v[112:115], v[208:211], v[4:7]
	v_mfma_f32_16x16x32_bf16 v[146:149], v[24:27], v[178:181], v[146:149]
	v_mfma_f32_16x16x32_bf16 v[150:153], v[112:115], v[178:181], v[150:153]
	v_mfma_f32_16x16x32_bf16 v[154:157], v[24:27], v[186:189], v[154:157]
	v_mfma_f32_16x16x32_bf16 v[158:161], v[112:115], v[186:189], v[158:161]
	v_mfma_f32_16x16x32_bf16 v[162:165], v[24:27], v[200:203], v[162:165]
	v_mfma_f32_16x16x32_bf16 v[166:169], v[112:115], v[200:203], v[166:169]
	v_mfma_f32_16x16x32_bf16 v[0:3], v[28:31], v[212:215], v[0:3]
	v_mfma_f32_16x16x32_bf16 v[4:7], v[116:119], v[212:215], v[4:7]
	v_mfma_f32_16x16x32_bf16 v[146:149], v[28:31], v[182:185], v[146:149]
	v_mfma_f32_16x16x32_bf16 v[150:153], v[116:119], v[182:185], v[150:153]
	v_mfma_f32_16x16x32_bf16 v[154:157], v[28:31], v[196:199], v[154:157]
	v_mfma_f32_16x16x32_bf16 v[158:161], v[116:119], v[196:199], v[158:161]
	v_mfma_f32_16x16x32_bf16 v[162:165], v[28:31], v[204:207], v[162:165]
	v_mfma_f32_16x16x32_bf16 v[166:169], v[116:119], v[204:207], v[166:169]
	v_mfma_f32_16x16x32_bf16 v[8:11], v[120:123], v[178:181], v[8:11]
	v_mfma_f32_16x16x32_bf16 v[12:15], v[170:173], v[178:181], v[12:15]
	v_mfma_f32_16x16x32_bf16 v[24:27], v[120:123], v[186:189], v[60:63]
	v_mfma_f32_16x16x32_bf16 v[28:31], v[170:173], v[186:189], v[100:103]
	v_mfma_f32_16x16x32_bf16 v[60:63], v[120:123], v[200:203], v[104:107]
	v_mfma_f32_16x16x32_bf16 v[100:103], v[170:173], v[200:203], v[108:111]
	v_mfma_f32_16x16x32_bf16 v[16:19], v[120:123], v[208:211], v[16:19]
	v_mfma_f32_16x16x32_bf16 v[20:23], v[170:173], v[208:211], v[20:23]
	v_mfma_f32_16x16x32_bf16 v[8:11], v[124:127], v[182:185], v[8:11]
	v_mfma_f32_16x16x32_bf16 v[12:15], v[174:177], v[182:185], v[12:15]
	v_mfma_f32_16x16x32_bf16 v[24:27], v[124:127], v[196:199], v[24:27]
	v_mfma_f32_16x16x32_bf16 v[28:31], v[174:177], v[196:199], v[28:31]
	v_mfma_f32_16x16x32_bf16 v[60:63], v[124:127], v[204:207], v[60:63]
	v_mfma_f32_16x16x32_bf16 v[100:103], v[174:177], v[204:207], v[100:103]
	v_mfma_f32_16x16x32_bf16 v[16:19], v[124:127], v[212:215], v[16:19]
	v_mfma_f32_16x16x32_bf16 v[20:23], v[174:177], v[212:215], v[20:23]
	s_barrier
	ds_read_b128 v[104:107], v143
	ds_read_b128 v[108:111], v143 offset:1024
	ds_read_b128 v[112:115], v143 offset:2048
	ds_read_b128 v[116:119], v143 offset:3072
	ds_read_b128 v[120:123], v144
	ds_read_b128 v[124:127], v144 offset:1024
	ds_read_b128 v[170:173], v144 offset:2048
	ds_read_b128 v[174:177], v144 offset:3072
	s_add_u32 s38, s38, 0x10180
	s_addc_u32 s39, s39, 0
	s_mov_b32 m0, s63
	v_lshl_add_u64 v[190:191], s[38:39], 0, v[128:129]
	ds_read_b128 v[178:181], v145
	ds_read_b128 v[182:185], v145 offset:1024
	ds_read_b128 v[186:189], v145 offset:2048
	ds_read_b128 v[196:199], v145 offset:3072
	ds_read_b128 v[200:203], v145 offset:4096
	ds_read_b128 v[204:207], v145 offset:5120
	ds_read_b128 v[208:211], v145 offset:6144
	ds_read_b128 v[212:215], v145 offset:7168
	global_load_lds_dwordx4 v[190:191], off
	v_lshl_add_u64 v[190:191], s[38:39], 0, v[132:133]
	s_mov_b32 m0, s29
	s_nop 0
	global_load_lds_dwordx4 v[190:191], off
	s_waitcnt vmcnt(8)
	s_waitcnt lgkmcnt(0)
	s_barrier
; #define PG8_STAGE(bufoff, gbase, voff) do { _Pragma("unroll") for (int _i = 0; _i < 2; ++_i) \
;         __builtin_amdgcn_global_load_lds((const unsigned*)((const char*)(gbase) + (voff)[_i]), (PG8_LAS unsigned*)(lds + (bufoff) + ldsw + _i * 8192), 16, 0, 0); } while (0)
; #define PG8_LDA(dst, b, h) do { _Pragma("unroll") for (int m = 0; m < 4; ++m) _Pragma("unroll") for (int k = 0; k < 2; ++k) dst[m][k] = *(const PG8_LAS bf16x8*)(lds + PG8_SA(b, h) + aoff + m * 2048 + k * 1024); } while (0)
; #define PG8_MMA(ai, bj, At, Bt) do { __builtin_amdgcn_s_setprio(1); _Pragma("unroll") for (int m = 0; m < 4; ++m) _Pragma("unroll") for (int n = 0; n < 2; ++n) _Pragma("unroll") for (int k = 0; k < 2; ++k) \
;         acc[ai][bj][m][n] = __builtin_amdgcn_mfma_f32_16x16x32_bf16(Bt[n][k], At[m][k], acc[ai][bj][m][n], 0, 0, 0); __builtin_amdgcn_s_setprio(0); } while (0)
; #define PG8_WAIT_V(n) asm volatile("s_waitcnt vmcnt(" #n ")" ::: "memory")
; #define PG8_WAIT_L(n) asm volatile("s_waitcnt lgkmcnt(" #n ")" ::: "memory")
; #define PG8_BAR __builtin_amdgcn_s_barrier()
; #define PG8_SCHED __builtin_amdgcn_sched_barrier(0)
; template <class Epi, class Sched, bool ALIGN_EPI = false, bool SP2 = false>
; __device__ __forceinline__ void gemm_phase(PG8_LAS unsigned char* lds, const Gemm g, const Sched& S, const Epi& E) {
;     ...
;             PG8_WAIT_V(8); PG8_WAIT_L(0); PG8_BAR; PG8_MMA(0, 0, At, B0); PG8_MMA(0, 1, At, B1); PG8_BAR; PG8_SCHED;
;             PG8_LDA(At, 0, 1); PG8_STAGE(PG8_SB(0, 0), b2, voffB); PG8_STAGE(PG8_SB(0, 1), b2 + hstepB, voffB); PG8_STAGE(PG8_SA(0, 0), a2, voffA);
;             PG8_WAIT_V(8); PG8_WAIT_L(0); PG8_BAR; PG8_MMA(1, 0, At, B0); PG8_MMA(1, 1, At, B1); PG8_BAR; PG8_SCHED;
	s_waitcnt lgkmcnt(0)
	v_mfma_f32_16x16x32_bf16 v[64:67], v[104:107], v[178:181], v[64:67]
	v_mfma_f32_16x16x32_bf16 v[68:71], v[112:115], v[178:181], v[68:71]
	v_mfma_f32_16x16x32_bf16 v[72:75], v[104:107], v[186:189], v[72:75]
	v_mfma_f32_16x16x32_bf16 v[76:79], v[112:115], v[186:189], v[76:79]
	v_mfma_f32_16x16x32_bf16 v[80:83], v[104:107], v[200:203], v[80:83]
	v_mfma_f32_16x16x32_bf16 v[84:87], v[112:115], v[200:203], v[84:87]
	v_mfma_f32_16x16x32_bf16 v[88:91], v[104:107], v[208:211], v[88:91]
	v_mfma_f32_16x16x32_bf16 v[92:95], v[112:115], v[208:211], v[92:95]
	v_mfma_f32_16x16x32_bf16 v[64:67], v[108:111], v[182:185], v[64:67]
	v_mfma_f32_16x16x32_bf16 v[68:71], v[116:119], v[182:185], v[68:71]
	v_mfma_f32_16x16x32_bf16 v[72:75], v[108:111], v[196:199], v[72:75]
	v_mfma_f32_16x16x32_bf16 v[76:79], v[116:119], v[196:199], v[76:79]
	v_mfma_f32_16x16x32_bf16 v[80:83], v[108:111], v[204:207], v[80:83]
	v_mfma_f32_16x16x32_bf16 v[84:87], v[116:119], v[204:207], v[84:87]
	v_mfma_f32_16x16x32_bf16 v[88:91], v[108:111], v[212:215], v[88:91]
	v_mfma_f32_16x16x32_bf16 v[92:95], v[116:119], v[212:215], v[92:95]
	v_mfma_f32_16x16x32_bf16 v[32:35], v[170:173], v[178:181], v[32:35]
	v_mfma_f32_16x16x32_bf16 v[96:99], v[120:123], v[178:181], v[96:99]
	v_mfma_f32_16x16x32_bf16 v[178:181], v[174:177], v[182:185], v[32:35]
	v_mfma_f32_16x16x32_bf16 v[32:35], v[120:123], v[186:189], v[36:39]
	v_mfma_f32_16x16x32_bf16 v[216:219], v[124:127], v[182:185], v[96:99]
	v_mfma_f32_16x16x32_bf16 v[182:185], v[124:127], v[196:199], v[32:35]
	v_mfma_f32_16x16x32_bf16 v[32:35], v[170:173], v[186:189], v[40:43]
	v_mfma_f32_16x16x32_bf16 v[40:43], v[174:177], v[196:199], v[32:35]
	v_mfma_f32_16x16x32_bf16 v[32:35], v[120:123], v[200:203], v[44:47]
	v_mfma_f32_16x16x32_bf16 v[44:47], v[124:127], v[204:207], v[32:35]
	v_mfma_f32_16x16x32_bf16 v[32:35], v[170:173], v[200:203], v[48:51]
	v_mfma_f32_16x16x32_bf16 v[48:51], v[174:177], v[204:207], v[32:35]
	v_mfma_f32_16x16x32_bf16 v[32:35], v[120:123], v[208:211], v[52:55]
	v_mfma_f32_16x16x32_bf16 v[52:55], v[124:127], v[212:215], v[32:35]
	v_mfma_f32_16x16x32_bf16 v[32:35], v[170:173], v[208:211], v[56:59]
	v_mfma_f32_16x16x32_bf16 v[56:59], v[174:177], v[212:215], v[32:35]
	s_barrier
	s_mov_b32 m0, s48
	v_lshl_add_u64 v[190:191], s[46:47], 0, v[130:131]
	s_add_u32 s38, s46, 0x10000
	s_nop 1
	ds_read_b128 v[32:35], v145 offset:16384
	ds_read_b128 v[36:39], v145 offset:17408
	ds_read_b128 v[96:99], v145 offset:18432
	ds_read_b128 v[186:189], v145 offset:19456
	ds_read_b128 v[196:199], v145 offset:20480
	ds_read_b128 v[200:203], v145 offset:21504
	ds_read_b128 v[204:207], v145 offset:22528
	ds_read_b128 v[208:211], v145 offset:23552
	global_load_lds_dwordx4 v[190:191], off
	v_lshl_add_u64 v[252:253], s[46:47], 0, v[134:135]
	s_mov_b32 m0, s31
	s_addc_u32 s39, s47, 0
	global_load_lds_dwordx4 v[252:253], off
	v_lshl_add_u64 v[212:213], s[38:39], 0, v[130:131]
	s_mov_b32 m0, s44
	v_lshl_add_u64 v[194:195], s[50:51], 0, v[128:129]
	global_load_lds_dwordx4 v[212:213], off
	v_lshl_add_u64 v[212:213], s[38:39], 0, v[134:135]
	s_mov_b32 m0, s45
	v_lshl_add_u64 v[192:193], s[50:51], 0, v[132:133]
	global_load_lds_dwordx4 v[212:213], off
	s_mov_b32 m0, s9
	s_nop 0
	global_load_lds_dwordx4 v[194:195], off
	s_mov_b32 m0, s27
	s_nop 0
	global_load_lds_dwordx4 v[192:193], off
	s_waitcnt vmcnt(8)
	s_waitcnt lgkmcnt(0)
	s_barrier
	s_waitcnt lgkmcnt(0)
	v_mfma_f32_16x16x32_bf16 v[0:3], v[104:107], v[204:207], v[0:3]
	v_mfma_f32_16x16x32_bf16 v[4:7], v[112:115], v[204:207], v[4:7]
	v_mfma_f32_16x16x32_bf16 v[146:149], v[104:107], v[32:35], v[146:149]
	v_mfma_f32_16x16x32_bf16 v[150:153], v[112:115], v[32:35], v[150:153]
	v_mfma_f32_16x16x32_bf16 v[154:157], v[104:107], v[96:99], v[154:157]
	v_mfma_f32_16x16x32_bf16 v[158:161], v[112:115], v[96:99], v[158:161]
	v_mfma_f32_16x16x32_bf16 v[162:165], v[104:107], v[196:199], v[162:165]
	v_mfma_f32_16x16x32_bf16 v[166:169], v[112:115], v[196:199], v[166:169]
	v_mfma_f32_16x16x32_bf16 v[0:3], v[108:111], v[208:211], v[0:3]
	v_mfma_f32_16x16x32_bf16 v[4:7], v[116:119], v[208:211], v[4:7]
	v_mfma_f32_16x16x32_bf16 v[146:149], v[108:111], v[36:39], v[146:149]
	v_mfma_f32_16x16x32_bf16 v[150:153], v[116:119], v[36:39], v[150:153]
	v_mfma_f32_16x16x32_bf16 v[154:157], v[108:111], v[186:189], v[154:157]
	v_mfma_f32_16x16x32_bf16 v[158:161], v[116:119], v[186:189], v[158:161]
	v_mfma_f32_16x16x32_bf16 v[162:165], v[108:111], v[200:203], v[162:165]
	v_mfma_f32_16x16x32_bf16 v[166:169], v[116:119], v[200:203], v[166:169]
	v_mfma_f32_16x16x32_bf16 v[8:11], v[120:123], v[32:35], v[8:11]
	v_mfma_f32_16x16x32_bf16 v[12:15], v[170:173], v[32:35], v[12:15]
	v_mfma_f32_16x16x32_bf16 v[24:27], v[120:123], v[96:99], v[24:27]
	v_mfma_f32_16x16x32_bf16 v[28:31], v[170:173], v[96:99], v[28:31]
	v_mfma_f32_16x16x32_bf16 v[32:35], v[120:123], v[196:199], v[60:63]
	v_mfma_f32_16x16x32_bf16 v[24:27], v[124:127], v[186:189], v[24:27]
	v_mfma_f32_16x16x32_bf16 v[28:31], v[174:177], v[186:189], v[28:31]
	v_mfma_f32_16x16x32_bf16 v[186:189], v[124:127], v[200:203], v[32:35]
	v_mfma_f32_16x16x32_bf16 v[32:35], v[170:173], v[196:199], v[100:103]
	v_mfma_f32_16x16x32_bf16 v[16:19], v[120:123], v[204:207], v[16:19]
	v_mfma_f32_16x16x32_bf16 v[8:11], v[124:127], v[36:39], v[8:11]
	v_mfma_f32_16x16x32_bf16 v[12:15], v[174:177], v[36:39], v[12:15]
	v_mfma_f32_16x16x32_bf16 v[196:199], v[174:177], v[200:203], v[32:35]
	v_mfma_f32_16x16x32_bf16 v[200:203], v[124:127], v[208:211], v[16:19]
	v_mfma_f32_16x16x32_bf16 v[16:19], v[170:173], v[204:207], v[20:23]
	v_mfma_f32_16x16x32_bf16 v[170:173], v[174:177], v[208:211], v[16:19]
	s_barrier
; #define PG8_STAGE(bufoff, gbase, voff) do { _Pragma("unroll") for (int _i = 0; _i < 2; ++_i) \
;         __builtin_amdgcn_global_load_lds((const unsigned*)((const char*)(gbase) + (voff)[_i]), (PG8_LAS unsigned*)(lds + (bufoff) + ldsw + _i * 8192), 16, 0, 0); } while (0)
; #define PG8_LDA(dst, b, h) do { _Pragma("unroll") for (int m = 0; m < 4; ++m) _Pragma("unroll") for (int k = 0; k < 2; ++k) dst[m][k] = *(const PG8_LAS bf16x8*)(lds + PG8_SA(b, h) + aoff + m * 2048 + k * 1024); } while (0)
; #define PG8_LDB(dst, b, h) do { _Pragma("unroll") for (int n = 0; n < 2; ++n) _Pragma("unroll") for (int k = 0; k < 2; ++k) dst[n][k] = *(const PG8_LAS bf16x8*)(lds + PG8_SB(b, h) + boff + n * 2048 + k * 1024); } while (0)
; #define PG8_MMA(ai, bj, At, Bt) do { __builtin_amdgcn_s_setprio(1); _Pragma("unroll") for (int m = 0; m < 4; ++m) _Pragma("unroll") for (int n = 0; n < 2; ++n) _Pragma("unroll") for (int k = 0; k < 2; ++k) \
;         acc[ai][bj][m][n] = __builtin_amdgcn_mfma_f32_16x16x32_bf16(Bt[n][k], At[m][k], acc[ai][bj][m][n], 0, 0, 0); __builtin_amdgcn_s_setprio(0); } while (0)
; #define PG8_WAIT_V(n) asm volatile("s_waitcnt vmcnt(" #n ")" ::: "memory")
; #define PG8_WAIT_L(n) asm volatile("s_waitcnt lgkmcnt(" #n ")" ::: "memory")
; #define PG8_BAR __builtin_amdgcn_s_barrier()
; #define PG8_SCHED __builtin_amdgcn_sched_barrier(0)
; template <class Epi, class Sched, bool ALIGN_EPI = false, bool SP2 = false>
; __device__ __forceinline__ void gemm_phase(PG8_LAS unsigned char* lds, const Gemm g, const Sched& S, const Epi& E) {
;     ...
;             PG8_LDB(B0, 1, 0); PG8_LDB(B1, 1, 1); PG8_SCHED; PG8_LDA(At, 1, 0); PG8_STAGE(PG8_SA(0, 1), a2 + hstepA, voffA);
;             PG8_WAIT_V(8); PG8_WAIT_L(0); PG8_BAR; PG8_MMA(0, 0, At, B0); PG8_MMA(0, 1, At, B1); PG8_BAR; PG8_SCHED;
;             PG8_LDA(At, 1, 1); PG8_STAGE(PG8_SB(1, 0), b3, voffB); PG8_STAGE(PG8_SB(1, 1), b3 + hstepB, voffB); PG8_STAGE(PG8_SA(1, 0), a3, voffA);
;             PG8_WAIT_V(8); PG8_WAIT_L(0); PG8_BAR; PG8_MMA(1, 0, At, B0); PG8_MMA(1, 1, At, B1); PG8_BAR; PG8_SCHED;
	ds_read_b128 v[60:63], v224
	ds_read_b128 v[174:177], v224 offset:1024
	ds_read_b128 v[204:207], v224 offset:2048
	ds_read_b128 v[208:211], v224 offset:3072
	ds_read_b128 v[212:215], v228
	ds_read_b128 v[220:223], v228 offset:1024
	ds_read_b128 v[224:227], v228 offset:2048
	ds_read_b128 v[228:231], v228 offset:3072
	s_add_u32 s38, s50, 0x10000
	s_addc_u32 s39, s51, 0
	s_mov_b32 m0, s33
	v_lshl_add_u64 v[32:33], s[38:39], 0, v[128:129]
	ds_read_b128 v[16:19], v145 offset:32768
	ds_read_b128 v[20:23], v145 offset:33792
	ds_read_b128 v[108:111], v145 offset:34816
	ds_read_b128 v[232:235], v145 offset:35840
	ds_read_b128 v[236:239], v145 offset:36864
	ds_read_b128 v[240:243], v145 offset:37888
	ds_read_b128 v[244:247], v145 offset:38912
	ds_read_b128 v[248:251], v145 offset:39936
	global_load_lds_dwordx4 v[32:33], off
	v_lshl_add_u64 v[32:33], s[38:39], 0, v[132:133]
	s_mov_b32 m0, s42
	s_nop 0
	global_load_lds_dwordx4 v[32:33], off
	s_waitcnt vmcnt(8)
	s_waitcnt lgkmcnt(0)
	s_barrier
	s_waitcnt lgkmcnt(0)
	v_mfma_f32_16x16x32_bf16 v[32:35], v[60:63], v[16:19], v[64:67]
	v_mfma_f32_16x16x32_bf16 v[112:115], v[174:177], v[20:23], v[32:35]
	v_mfma_f32_16x16x32_bf16 v[32:35], v[204:207], v[16:19], v[68:71]
	v_mfma_f32_16x16x32_bf16 v[116:119], v[208:211], v[20:23], v[32:35]
	v_mfma_f32_16x16x32_bf16 v[32:35], v[60:63], v[108:111], v[72:75]
	v_mfma_f32_16x16x32_bf16 v[96:99], v[174:177], v[232:235], v[32:35]
	v_mfma_f32_16x16x32_bf16 v[32:35], v[204:207], v[108:111], v[76:79]
	v_mfma_f32_16x16x32_bf16 v[100:103], v[208:211], v[232:235], v[32:35]
	v_mfma_f32_16x16x32_bf16 v[32:35], v[60:63], v[236:239], v[80:83]
	v_mfma_f32_16x16x32_bf16 v[64:67], v[174:177], v[240:243], v[32:35]
	v_mfma_f32_16x16x32_bf16 v[32:35], v[204:207], v[236:239], v[84:87]
	v_mfma_f32_16x16x32_bf16 v[68:71], v[208:211], v[240:243], v[32:35]
	v_mfma_f32_16x16x32_bf16 v[32:35], v[60:63], v[244:247], v[88:91]
	v_mfma_f32_16x16x32_bf16 v[36:39], v[204:207], v[244:247], v[92:95]
	v_mfma_f32_16x16x32_bf16 v[32:35], v[174:177], v[248:251], v[32:35]
	v_mfma_f32_16x16x32_bf16 v[36:39], v[208:211], v[248:251], v[36:39]
	v_mfma_f32_16x16x32_bf16 v[72:75], v[212:215], v[16:19], v[216:219]
	v_mfma_f32_16x16x32_bf16 v[16:19], v[224:227], v[16:19], v[178:181]
	v_mfma_f32_16x16x32_bf16 v[124:127], v[228:231], v[20:23], v[16:19]
	v_mfma_f32_16x16x32_bf16 v[16:19], v[212:215], v[108:111], v[182:185]
	v_mfma_f32_16x16x32_bf16 v[104:107], v[220:223], v[232:235], v[16:19]
	v_mfma_f32_16x16x32_bf16 v[16:19], v[224:227], v[108:111], v[40:43]
	v_mfma_f32_16x16x32_bf16 v[108:111], v[228:231], v[232:235], v[16:19]
	v_mfma_f32_16x16x32_bf16 v[16:19], v[212:215], v[236:239], v[44:47]
	v_mfma_f32_16x16x32_bf16 v[120:123], v[220:223], v[20:23], v[72:75]
	v_mfma_f32_16x16x32_bf16 v[72:75], v[220:223], v[240:243], v[16:19]
	v_mfma_f32_16x16x32_bf16 v[16:19], v[224:227], v[236:239], v[48:51]
	v_mfma_f32_16x16x32_bf16 v[76:79], v[228:231], v[240:243], v[16:19]
	v_mfma_f32_16x16x32_bf16 v[16:19], v[212:215], v[244:247], v[52:55]
	v_mfma_f32_16x16x32_bf16 v[40:43], v[220:223], v[248:251], v[16:19]
	v_mfma_f32_16x16x32_bf16 v[16:19], v[224:227], v[244:247], v[56:59]
	v_mfma_f32_16x16x32_bf16 v[44:47], v[228:231], v[248:251], v[16:19]
	s_barrier
	s_mov_b32 m0, s64
	s_nop 3
	v_lshl_add_u64 v[16:17], v[190:191], 0, s[16:17]
	s_add_u32 s38, s46, 0x10080
	ds_read_b128 v[56:59], v145 offset:49152
	ds_read_b128 v[92:95], v145 offset:50176
	ds_read_b128 v[178:181], v145 offset:51200
	ds_read_b128 v[182:185], v145 offset:52224
	ds_read_b128 v[216:219], v145 offset:53248
	ds_read_b128 v[232:235], v145 offset:54272
	ds_read_b128 v[236:239], v145 offset:55296
	ds_read_b128 v[240:243], v145 offset:56320
	global_load_lds_dwordx4 v[16:17], off
	v_lshl_add_u64 v[16:17], v[252:253], 0, s[16:17]
	s_mov_b32 m0, s49
	s_addc_u32 s39, s47, 0
	global_load_lds_dwordx4 v[16:17], off
	v_lshl_add_u64 v[16:17], s[38:39], 0, v[130:131]
	s_mov_b32 m0, s40
	s_nop 0
	global_load_lds_dwordx4 v[16:17], off
	v_lshl_add_u64 v[16:17], s[38:39], 0, v[134:135]
	s_mov_b32 m0, s41
	s_nop 0
	global_load_lds_dwordx4 v[16:17], off
	v_lshl_add_u64 v[16:17], v[194:195], 0, s[16:17]
	s_mov_b32 m0, s53
	s_nop 0
	global_load_lds_dwordx4 v[16:17], off
	v_lshl_add_u64 v[16:17], v[192:193], 0, s[16:17]
	s_mov_b32 m0, s56
	s_nop 0
	global_load_lds_dwordx4 v[16:17], off
	s_waitcnt vmcnt(8)
	s_waitcnt lgkmcnt(0)
	s_barrier
	s_waitcnt lgkmcnt(0)
	v_mfma_f32_16x16x32_bf16 v[16:19], v[60:63], v[56:59], v[146:149]
	v_mfma_f32_16x16x32_bf16 v[80:83], v[174:177], v[92:95], v[16:19]
	v_mfma_f32_16x16x32_bf16 v[16:19], v[204:207], v[56:59], v[150:153]
	v_mfma_f32_16x16x32_bf16 v[84:87], v[208:211], v[92:95], v[16:19]
	v_mfma_f32_16x16x32_bf16 v[16:19], v[60:63], v[178:181], v[154:157]
	v_mfma_f32_16x16x32_bf16 v[48:51], v[174:177], v[182:185], v[16:19]
	v_mfma_f32_16x16x32_bf16 v[16:19], v[204:207], v[178:181], v[158:161]
	v_mfma_f32_16x16x32_bf16 v[52:55], v[208:211], v[182:185], v[16:19]
	v_mfma_f32_16x16x32_bf16 v[16:19], v[60:63], v[216:219], v[162:165]
	v_mfma_f32_16x16x32_bf16 v[20:23], v[204:207], v[216:219], v[166:169]
	v_mfma_f32_16x16x32_bf16 v[0:3], v[60:63], v[236:239], v[0:3]
	v_mfma_f32_16x16x32_bf16 v[4:7], v[204:207], v[236:239], v[4:7]
	v_mfma_f32_16x16x32_bf16 v[16:19], v[174:177], v[232:235], v[16:19]
	v_mfma_f32_16x16x32_bf16 v[20:23], v[208:211], v[232:235], v[20:23]
	v_mfma_f32_16x16x32_bf16 v[0:3], v[174:177], v[240:243], v[0:3]
	v_mfma_f32_16x16x32_bf16 v[4:7], v[208:211], v[240:243], v[4:7]
	v_mfma_f32_16x16x32_bf16 v[8:11], v[212:215], v[56:59], v[8:11]
	v_mfma_f32_16x16x32_bf16 v[88:91], v[220:223], v[92:95], v[8:11]
	v_mfma_f32_16x16x32_bf16 v[8:11], v[224:227], v[56:59], v[12:15]
	v_mfma_f32_16x16x32_bf16 v[92:95], v[228:231], v[92:95], v[8:11]
	v_mfma_f32_16x16x32_bf16 v[8:11], v[212:215], v[178:181], v[24:27]
	v_mfma_f32_16x16x32_bf16 v[56:59], v[220:223], v[182:185], v[8:11]
	v_mfma_f32_16x16x32_bf16 v[8:11], v[224:227], v[178:181], v[28:31]
	v_mfma_f32_16x16x32_bf16 v[60:63], v[228:231], v[182:185], v[8:11]
	v_mfma_f32_16x16x32_bf16 v[8:11], v[212:215], v[216:219], v[186:189]
	v_mfma_f32_16x16x32_bf16 v[24:27], v[220:223], v[232:235], v[8:11]
	v_mfma_f32_16x16x32_bf16 v[8:11], v[224:227], v[216:219], v[196:199]
	v_mfma_f32_16x16x32_bf16 v[28:31], v[228:231], v[232:235], v[8:11]
	v_mfma_f32_16x16x32_bf16 v[8:11], v[212:215], v[236:239], v[200:203]
	v_mfma_f32_16x16x32_bf16 v[12:15], v[224:227], v[236:239], v[170:173]
	v_mfma_f32_16x16x32_bf16 v[8:11], v[220:223], v[240:243], v[8:11]
	v_mfma_f32_16x16x32_bf16 v[12:15], v[228:231], v[240:243], v[12:15]
	s_barrier
	s_andn2_b64 vcc, exec, s[18:19]
	s_cbranch_vccnz .LBB0_165
	s_barrier

; #define PG8_STAGE(bufoff, gbase, voff) do { _Pragma("unroll") for (int _i = 0; _i < 2; ++_i) \
;         __builtin_amdgcn_global_load_lds((const unsigned*)((const char*)(gbase) + (voff)[_i]), (PG8_LAS unsigned*)(lds + (bufoff) + ldsw + _i * 8192), 16, 0, 0); } while (0)
; #define PG8_LDA(dst, b, h) do { _Pragma("unroll") for (int m = 0; m < 4; ++m) _Pragma("unroll") for (int k = 0; k < 2; ++k) dst[m][k] = *(const PG8_LAS bf16x8*)(lds + PG8_SA(b, h) + aoff + m * 2048 + k * 1024); } while (0)
; #define PG8_LDB(dst, b, h) do { _Pragma("unroll") for (int n = 0; n < 2; ++n) _Pragma("unroll") for (int k = 0; k < 2; ++k) dst[n][k] = *(const PG8_LAS bf16x8*)(lds + PG8_SB(b, h) + boff + n * 2048 + k * 1024); } while (0)
; #define PG8_MMA(ai, bj, At, Bt) do { __builtin_amdgcn_s_setprio(1); _Pragma("unroll") for (int m = 0; m < 4; ++m) _Pragma("unroll") for (int n = 0; n < 2; ++n) _Pragma("unroll") for (int k = 0; k < 2; ++k) \
;         acc[ai][bj][m][n] = __builtin_amdgcn_mfma_f32_16x16x32_bf16(Bt[n][k], At[m][k], acc[ai][bj][m][n], 0, 0, 0); __builtin_amdgcn_s_setprio(0); } while (0)
; #define PG8_WAIT_V(n) asm volatile("s_waitcnt vmcnt(" #n ")" ::: "memory")
; #define PG8_WAIT_L(n) asm volatile("s_waitcnt lgkmcnt(" #n ")" ::: "memory")
; #define PG8_BAR __builtin_amdgcn_s_barrier()
; #define PG8_SCHED __builtin_amdgcn_sched_barrier(0)
; template <class Epi, class Sched, bool ALIGN_EPI = false, bool SP2 = false>
; __device__ __forceinline__ void gemm_phase(PG8_LAS unsigned char* lds, const Gemm g, const Sched& S, const Epi& E) {
;     ...
;             const bool last = (t == nt - 2);
;             const char* a1 = cA + (size_t)(t + 1) * kstep;
;             const char* a2 = last ? nA : cA + (size_t)(t + 2) * kstep; const char* b2 = last ? nB : cB + (size_t)(t + 2) * kstep;
;             const char* a3 = a2 + kstep; const char* b3 = b2 + kstep;
;             if (last && has_next) S.a_ready(nxt);
;             if constexpr (SP2) {
;             PG8_LDB(B0, 0, 0); PG8_LDB(B1, 0, 1); PG8_SCHED; PG8_LDA(At, 0, 0); PG8_STAGE(PG8_SA(1, 1), a1 + hstepA, voffA);
;             PG8_WAIT_V(8); PG8_WAIT_L(0); PG8_BAR; PG8_MMA(0, 0, At, B0); PG8_MMA(0, 1, At, B1); PG8_BAR; PG8_SCHED;
;             PG8_LDA(At, 0, 1); PG8_STAGE(PG8_SB(0, 0), b2, voffB); PG8_STAGE(PG8_SB(0, 1), b2 + hstepB, voffB); PG8_STAGE(PG8_SA(0, 0), a2, voffA);
.LBB0_186:
	ds_read_b128 v[150:153], v147
	ds_read_b128 v[154:157], v147 offset:1024
	ds_read_b128 v[158:161], v147 offset:2048
	ds_read_b128 v[162:165], v147 offset:3072
	ds_read_b128 v[166:169], v148
	ds_read_b128 v[170:173], v148 offset:1024
	ds_read_b128 v[174:177], v148 offset:2048
	ds_read_b128 v[178:181], v148 offset:3072
	s_add_u32 s36, s34, 0xfffc0080
	s_addc_u32 s37, s35, -1
	s_cmp_eq_u32 s64, 12
	s_cselect_b32 s39, s27, s37
	s_cselect_b32 s38, s60, s36
	s_cselect_b32 s37, s25, s63
	s_cselect_b32 s36, s61, s62
	v_lshl_add_u64 v[190:191], s[34:35], 0, v[136:137]
	s_add_i32 m0, s8, 0xc000
	ds_read_b128 v[182:185], v149
	ds_read_b128 v[186:189], v149 offset:1024
	ds_read_b128 v[196:199], v149 offset:2048
	ds_read_b128 v[200:203], v149 offset:3072
	ds_read_b128 v[204:207], v149 offset:4096
	ds_read_b128 v[208:211], v149 offset:5120
	ds_read_b128 v[212:215], v149 offset:6144
	ds_read_b128 v[216:219], v149 offset:7168
	global_load_lds_dwordx4 v[190:191], off
	v_lshl_add_u64 v[190:191], s[34:35], 0, v[138:139]
	s_add_i32 m0, s8, 0xe000
	s_nop 0
	global_load_lds_dwordx4 v[190:191], off
	s_waitcnt vmcnt(8)
	s_waitcnt lgkmcnt(0)
	s_barrier
	s_waitcnt lgkmcnt(0)
	v_mfma_f32_16x16x32_bf16 v[124:127], v[150:153], v[182:185], v[124:127]
	v_mfma_f32_16x16x32_bf16 v[120:123], v[158:161], v[182:185], v[120:123]
	v_mfma_f32_16x16x32_bf16 v[116:119], v[150:153], v[196:199], v[116:119]
	v_mfma_f32_16x16x32_bf16 v[112:115], v[158:161], v[196:199], v[112:115]
	v_mfma_f32_16x16x32_bf16 v[100:103], v[150:153], v[204:207], v[100:103]
	v_mfma_f32_16x16x32_bf16 v[96:99], v[158:161], v[204:207], v[96:99]
	v_mfma_f32_16x16x32_bf16 v[84:87], v[150:153], v[212:215], v[84:87]
	v_mfma_f32_16x16x32_bf16 v[80:83], v[158:161], v[212:215], v[80:83]
	v_mfma_f32_16x16x32_bf16 v[124:127], v[154:157], v[186:189], v[124:127]
	v_mfma_f32_16x16x32_bf16 v[120:123], v[162:165], v[186:189], v[120:123]
	v_mfma_f32_16x16x32_bf16 v[116:119], v[154:157], v[200:203], v[116:119]
	v_mfma_f32_16x16x32_bf16 v[112:115], v[162:165], v[200:203], v[112:115]
	v_mfma_f32_16x16x32_bf16 v[100:103], v[154:157], v[208:211], v[100:103]
	v_mfma_f32_16x16x32_bf16 v[96:99], v[162:165], v[208:211], v[96:99]
	v_mfma_f32_16x16x32_bf16 v[84:87], v[154:157], v[216:219], v[84:87]
	v_mfma_f32_16x16x32_bf16 v[80:83], v[162:165], v[216:219], v[80:83]
	v_mfma_f32_16x16x32_bf16 v[108:111], v[166:169], v[182:185], v[108:111]
	v_mfma_f32_16x16x32_bf16 v[104:107], v[174:177], v[182:185], v[104:107]
	v_mfma_f32_16x16x32_bf16 v[92:95], v[166:169], v[196:199], v[92:95]
	v_mfma_f32_16x16x32_bf16 v[88:91], v[174:177], v[196:199], v[88:91]
	v_mfma_f32_16x16x32_bf16 v[76:79], v[166:169], v[204:207], v[76:79]
	v_mfma_f32_16x16x32_bf16 v[72:75], v[174:177], v[204:207], v[72:75]
	v_mfma_f32_16x16x32_bf16 v[68:71], v[166:169], v[212:215], v[68:71]
	v_mfma_f32_16x16x32_bf16 v[64:67], v[174:177], v[212:215], v[64:67]
	v_mfma_f32_16x16x32_bf16 v[108:111], v[170:173], v[186:189], v[108:111]
	v_mfma_f32_16x16x32_bf16 v[104:107], v[178:181], v[186:189], v[104:107]
	v_mfma_f32_16x16x32_bf16 v[92:95], v[170:173], v[200:203], v[92:95]
	v_mfma_f32_16x16x32_bf16 v[88:91], v[178:181], v[200:203], v[88:91]
	v_mfma_f32_16x16x32_bf16 v[76:79], v[170:173], v[208:211], v[76:79]
	v_mfma_f32_16x16x32_bf16 v[72:75], v[178:181], v[208:211], v[72:75]
	v_mfma_f32_16x16x32_bf16 v[68:71], v[170:173], v[216:219], v[68:71]
	v_mfma_f32_16x16x32_bf16 v[64:67], v[178:181], v[216:219], v[64:67]
	s_barrier
	s_add_i32 s44, s53, s3
	v_lshl_add_u64 v[190:191], s[36:37], 0, v[130:131]
	s_mov_b32 m0, s44
	ds_read_b128 v[182:185], v149 offset:16384
	ds_read_b128 v[186:189], v149 offset:17408
	ds_read_b128 v[196:199], v149 offset:18432
	ds_read_b128 v[200:203], v149 offset:19456
	ds_read_b128 v[204:207], v149 offset:20480
	ds_read_b128 v[208:211], v149 offset:21504
	ds_read_b128 v[212:215], v149 offset:22528
	ds_read_b128 v[216:219], v149 offset:23552
	global_load_lds_dwordx4 v[190:191], off
	s_add_i32 m0, s44, 0x2000
	s_add_u32 s44, s36, 0x40000
	v_lshl_add_u64 v[192:193], s[36:37], 0, v[134:135]
	s_addc_u32 s45, s37, 0
	s_add_i32 s48, s56, s3
	global_load_lds_dwordx4 v[192:193], off
	v_lshl_add_u64 v[194:195], s[44:45], 0, v[130:131]
	s_mov_b32 m0, s48
	v_lshl_add_u64 v[220:221], s[38:39], 0, v[132:133]
	global_load_lds_dwordx4 v[194:195], off
	v_lshl_add_u64 v[194:195], s[44:45], 0, v[134:135]
	s_add_i32 m0, s48, 0x2000
	s_nop 0
	global_load_lds_dwordx4 v[194:195], off
	v_lshl_add_u64 v[194:195], s[38:39], 0, v[128:129]
	s_mov_b32 m0, s8
	s_nop 0
	global_load_lds_dwordx4 v[194:195], off
	s_mov_b32 m0, s9
	s_nop 0
	global_load_lds_dwordx4 v[220:221], off
	s_waitcnt vmcnt(8)
	s_waitcnt lgkmcnt(0)
	s_barrier
; #define PG8_STAGE(bufoff, gbase, voff) do { _Pragma("unroll") for (int _i = 0; _i < 2; ++_i) \
;         __builtin_amdgcn_global_load_lds((const unsigned*)((const char*)(gbase) + (voff)[_i]), (PG8_LAS unsigned*)(lds + (bufoff) + ldsw + _i * 8192), 16, 0, 0); } while (0)
; #define PG8_LDA(dst, b, h) do { _Pragma("unroll") for (int m = 0; m < 4; ++m) _Pragma("unroll") for (int k = 0; k < 2; ++k) dst[m][k] = *(const PG8_LAS bf16x8*)(lds + PG8_SA(b, h) + aoff + m * 2048 + k * 1024); } while (0)
; #define PG8_LDB(dst, b, h) do { _Pragma("unroll") for (int n = 0; n < 2; ++n) _Pragma("unroll") for (int k = 0; k < 2; ++k) dst[n][k] = *(const PG8_LAS bf16x8*)(lds + PG8_SB(b, h) + boff + n * 2048 + k * 1024); } while (0)
; #define PG8_MMA(ai, bj, At, Bt) do { __builtin_amdgcn_s_setprio(1); _Pragma("unroll") for (int m = 0; m < 4; ++m) _Pragma("unroll") for (int n = 0; n < 2; ++n) _Pragma("unroll") for (int k = 0; k < 2; ++k) \
;         acc[ai][bj][m][n] = __builtin_amdgcn_mfma_f32_16x16x32_bf16(Bt[n][k], At[m][k], acc[ai][bj][m][n], 0, 0, 0); __builtin_amdgcn_s_setprio(0); } while (0)
; #define PG8_WAIT_V(n) asm volatile("s_waitcnt vmcnt(" #n ")" ::: "memory")
; #define PG8_WAIT_L(n) asm volatile("s_waitcnt lgkmcnt(" #n ")" ::: "memory")
; #define PG8_BAR __builtin_amdgcn_s_barrier()
; #define PG8_SCHED __builtin_amdgcn_sched_barrier(0)
; template <class Epi, class Sched, bool ALIGN_EPI = false, bool SP2 = false>
; __device__ __forceinline__ void gemm_phase(PG8_LAS unsigned char* lds, const Gemm g, const Sched& S, const Epi& E) {
;     ...
;             PG8_WAIT_V(8); PG8_WAIT_L(0); PG8_BAR; PG8_MMA(1, 0, At, B0); PG8_MMA(1, 1, At, B1); PG8_BAR; PG8_SCHED;
;             PG8_LDB(B0, 1, 0); PG8_LDB(B1, 1, 1); PG8_SCHED; PG8_LDA(At, 1, 0); PG8_STAGE(PG8_SA(0, 1), a2 + hstepA, voffA);
;             PG8_WAIT_V(8); PG8_WAIT_L(0); PG8_BAR; PG8_MMA(0, 0, At, B0); PG8_MMA(0, 1, At, B1); PG8_BAR; PG8_SCHED;
	s_waitcnt lgkmcnt(0)
	v_mfma_f32_16x16x32_bf16 v[60:63], v[150:153], v[182:185], v[60:63]
	v_mfma_f32_16x16x32_bf16 v[56:59], v[158:161], v[182:185], v[56:59]
	v_mfma_f32_16x16x32_bf16 v[52:55], v[150:153], v[196:199], v[52:55]
	v_mfma_f32_16x16x32_bf16 v[48:51], v[158:161], v[196:199], v[48:51]
	v_mfma_f32_16x16x32_bf16 v[36:39], v[150:153], v[204:207], v[36:39]
	v_mfma_f32_16x16x32_bf16 v[32:35], v[158:161], v[204:207], v[32:35]
	v_mfma_f32_16x16x32_bf16 v[20:23], v[150:153], v[212:215], v[20:23]
	v_mfma_f32_16x16x32_bf16 v[16:19], v[158:161], v[212:215], v[16:19]
	v_mfma_f32_16x16x32_bf16 v[60:63], v[154:157], v[186:189], v[60:63]
	v_mfma_f32_16x16x32_bf16 v[56:59], v[162:165], v[186:189], v[56:59]
	v_mfma_f32_16x16x32_bf16 v[52:55], v[154:157], v[200:203], v[52:55]
	v_mfma_f32_16x16x32_bf16 v[48:51], v[162:165], v[200:203], v[48:51]
	v_mfma_f32_16x16x32_bf16 v[36:39], v[154:157], v[208:211], v[36:39]
	v_mfma_f32_16x16x32_bf16 v[32:35], v[162:165], v[208:211], v[32:35]
	v_mfma_f32_16x16x32_bf16 v[20:23], v[154:157], v[216:219], v[20:23]
	v_mfma_f32_16x16x32_bf16 v[16:19], v[162:165], v[216:219], v[16:19]
	v_mfma_f32_16x16x32_bf16 v[44:47], v[166:169], v[182:185], v[44:47]
	v_mfma_f32_16x16x32_bf16 v[40:43], v[174:177], v[182:185], v[40:43]
	v_mfma_f32_16x16x32_bf16 v[28:31], v[166:169], v[196:199], v[28:31]
	v_mfma_f32_16x16x32_bf16 v[24:27], v[174:177], v[196:199], v[24:27]
	v_mfma_f32_16x16x32_bf16 v[12:15], v[166:169], v[204:207], v[12:15]
	v_mfma_f32_16x16x32_bf16 v[8:11], v[174:177], v[204:207], v[8:11]
	v_mfma_f32_16x16x32_bf16 v[4:7], v[166:169], v[212:215], v[4:7]
	v_mfma_f32_16x16x32_bf16 v[0:3], v[174:177], v[212:215], v[0:3]
	v_mfma_f32_16x16x32_bf16 v[44:47], v[170:173], v[186:189], v[44:47]
	v_mfma_f32_16x16x32_bf16 v[40:43], v[178:181], v[186:189], v[40:43]
	v_mfma_f32_16x16x32_bf16 v[28:31], v[170:173], v[200:203], v[28:31]
	v_mfma_f32_16x16x32_bf16 v[24:27], v[178:181], v[200:203], v[24:27]
	v_mfma_f32_16x16x32_bf16 v[12:15], v[170:173], v[208:211], v[12:15]
	v_mfma_f32_16x16x32_bf16 v[8:11], v[178:181], v[208:211], v[8:11]
	v_mfma_f32_16x16x32_bf16 v[4:7], v[170:173], v[216:219], v[4:7]
	v_mfma_f32_16x16x32_bf16 v[0:3], v[178:181], v[216:219], v[0:3]
	s_barrier
	s_add_i32 s44, 0, 0x18000
	s_add_i32 s45, 0, 0x1c000
	v_add_u32_e32 v162, s44, v146
	v_add_u32_e32 v178, s45, v146
	ds_read_b128 v[150:153], v162
	ds_read_b128 v[154:157], v162 offset:1024
	ds_read_b128 v[158:161], v162 offset:2048
	ds_read_b128 v[162:165], v162 offset:3072
	ds_read_b128 v[166:169], v178
	ds_read_b128 v[170:173], v178 offset:1024
	ds_read_b128 v[174:177], v178 offset:2048
	ds_read_b128 v[178:181], v178 offset:3072
	s_add_u32 s38, s38, 0x40000
	s_addc_u32 s39, s39, 0
	s_mov_b32 m0, s23
	v_lshl_add_u64 v[222:223], s[38:39], 0, v[128:129]
	ds_read_b128 v[182:185], v149 offset:32768
	ds_read_b128 v[186:189], v149 offset:33792
	ds_read_b128 v[196:199], v149 offset:34816
	ds_read_b128 v[200:203], v149 offset:35840
	ds_read_b128 v[204:207], v149 offset:36864
	ds_read_b128 v[208:211], v149 offset:37888
	ds_read_b128 v[212:215], v149 offset:38912
	ds_read_b128 v[216:219], v149 offset:39936
	global_load_lds_dwordx4 v[222:223], off
	v_lshl_add_u64 v[222:223], s[38:39], 0, v[132:133]
	s_mov_b32 m0, s33
	s_nop 0
	global_load_lds_dwordx4 v[222:223], off
	s_waitcnt vmcnt(8)
	s_waitcnt lgkmcnt(0)
	s_barrier
	s_waitcnt lgkmcnt(0)
	v_mfma_f32_16x16x32_bf16 v[124:127], v[150:153], v[182:185], v[124:127]
	v_mfma_f32_16x16x32_bf16 v[120:123], v[158:161], v[182:185], v[120:123]
	v_mfma_f32_16x16x32_bf16 v[116:119], v[150:153], v[196:199], v[116:119]
	v_mfma_f32_16x16x32_bf16 v[112:115], v[158:161], v[196:199], v[112:115]
	v_mfma_f32_16x16x32_bf16 v[100:103], v[150:153], v[204:207], v[100:103]
	v_mfma_f32_16x16x32_bf16 v[96:99], v[158:161], v[204:207], v[96:99]
	v_mfma_f32_16x16x32_bf16 v[84:87], v[150:153], v[212:215], v[84:87]
	v_mfma_f32_16x16x32_bf16 v[80:83], v[158:161], v[212:215], v[80:83]
	v_mfma_f32_16x16x32_bf16 v[124:127], v[154:157], v[186:189], v[124:127]
	v_mfma_f32_16x16x32_bf16 v[120:123], v[162:165], v[186:189], v[120:123]
	v_mfma_f32_16x16x32_bf16 v[116:119], v[154:157], v[200:203], v[116:119]
	v_mfma_f32_16x16x32_bf16 v[112:115], v[162:165], v[200:203], v[112:115]
	v_mfma_f32_16x16x32_bf16 v[100:103], v[154:157], v[208:211], v[100:103]
	v_mfma_f32_16x16x32_bf16 v[96:99], v[162:165], v[208:211], v[96:99]
	v_mfma_f32_16x16x32_bf16 v[84:87], v[154:157], v[216:219], v[84:87]
	v_mfma_f32_16x16x32_bf16 v[80:83], v[162:165], v[216:219], v[80:83]
	v_mfma_f32_16x16x32_bf16 v[108:111], v[166:169], v[182:185], v[108:111]
	v_mfma_f32_16x16x32_bf16 v[104:107], v[174:177], v[182:185], v[104:107]
	v_mfma_f32_16x16x32_bf16 v[92:95], v[166:169], v[196:199], v[92:95]
	v_mfma_f32_16x16x32_bf16 v[88:91], v[174:177], v[196:199], v[88:91]
	v_mfma_f32_16x16x32_bf16 v[76:79], v[166:169], v[204:207], v[76:79]
	v_mfma_f32_16x16x32_bf16 v[72:75], v[174:177], v[204:207], v[72:75]
	v_mfma_f32_16x16x32_bf16 v[68:71], v[166:169], v[212:215], v[68:71]
	v_mfma_f32_16x16x32_bf16 v[64:67], v[174:177], v[212:215], v[64:67]
	v_mfma_f32_16x16x32_bf16 v[108:111], v[170:173], v[186:189], v[108:111]
	v_mfma_f32_16x16x32_bf16 v[104:107], v[178:181], v[186:189], v[104:107]
	v_mfma_f32_16x16x32_bf16 v[92:95], v[170:173], v[200:203], v[92:95]
	v_mfma_f32_16x16x32_bf16 v[88:91], v[178:181], v[200:203], v[88:91]
	v_mfma_f32_16x16x32_bf16 v[76:79], v[170:173], v[208:211], v[76:79]
	v_mfma_f32_16x16x32_bf16 v[72:75], v[178:181], v[208:211], v[72:75]
	v_mfma_f32_16x16x32_bf16 v[68:71], v[170:173], v[216:219], v[68:71]
	v_mfma_f32_16x16x32_bf16 v[64:67], v[178:181], v[216:219], v[64:67]
	s_barrier
; #define PG8_STAGE(bufoff, gbase, voff) do { _Pragma("unroll") for (int _i = 0; _i < 2; ++_i) \
;         __builtin_amdgcn_global_load_lds((const unsigned*)((const char*)(gbase) + (voff)[_i]), (PG8_LAS unsigned*)(lds + (bufoff) + ldsw + _i * 8192), 16, 0, 0); } while (0)
; #define PG8_LDA(dst, b, h) do { _Pragma("unroll") for (int m = 0; m < 4; ++m) _Pragma("unroll") for (int k = 0; k < 2; ++k) dst[m][k] = *(const PG8_LAS bf16x8*)(lds + PG8_SA(b, h) + aoff + m * 2048 + k * 1024); } while (0)
; #define PG8_MMA(ai, bj, At, Bt) do { __builtin_amdgcn_s_setprio(1); _Pragma("unroll") for (int m = 0; m < 4; ++m) _Pragma("unroll") for (int n = 0; n < 2; ++n) _Pragma("unroll") for (int k = 0; k < 2; ++k) \
;         acc[ai][bj][m][n] = __builtin_amdgcn_mfma_f32_16x16x32_bf16(Bt[n][k], At[m][k], acc[ai][bj][m][n], 0, 0, 0); __builtin_amdgcn_s_setprio(0); } while (0)
; #define PG8_WAIT_V(n) asm volatile("s_waitcnt vmcnt(" #n ")" ::: "memory")
; #define PG8_WAIT_L(n) asm volatile("s_waitcnt lgkmcnt(" #n ")" ::: "memory")
; #define PG8_BAR __builtin_amdgcn_s_barrier()
; #define PG8_SCHED __builtin_amdgcn_sched_barrier(0)
; template <class Epi, class Sched, bool ALIGN_EPI = false, bool SP2 = false>
; __device__ __forceinline__ void gemm_phase(PG8_LAS unsigned char* lds, const Gemm g, const Sched& S, const Epi& E) {
;     ...
;             PG8_LDA(At, 1, 1); PG8_STAGE(PG8_SB(1, 0), b3, voffB); PG8_STAGE(PG8_SB(1, 1), b3 + hstepB, voffB); PG8_STAGE(PG8_SA(1, 0), a3, voffA);
;             PG8_WAIT_V(8); PG8_WAIT_L(0); PG8_BAR; PG8_MMA(1, 0, At, B0); PG8_MMA(1, 1, At, B1); PG8_BAR; PG8_SCHED;
	s_add_i32 s38, s44, s3
	v_lshl_add_u64 v[190:191], v[190:191], 0, s[16:17]
	s_mov_b32 m0, s38
	ds_read_b128 v[182:185], v149 offset:49152
	ds_read_b128 v[186:189], v149 offset:50176
	ds_read_b128 v[196:199], v149 offset:51200
	ds_read_b128 v[200:203], v149 offset:52224
	ds_read_b128 v[204:207], v149 offset:53248
	ds_read_b128 v[208:211], v149 offset:54272
	ds_read_b128 v[212:215], v149 offset:55296
	ds_read_b128 v[216:219], v149 offset:56320
	global_load_lds_dwordx4 v[190:191], off
	s_add_i32 m0, s38, 0x2000
	s_add_u32 s36, s36, 0x40080
	v_lshl_add_u64 v[190:191], v[192:193], 0, s[16:17]
	s_addc_u32 s37, s37, 0
	s_add_i32 s38, s45, s3
	global_load_lds_dwordx4 v[190:191], off
	v_lshl_add_u64 v[190:191], s[36:37], 0, v[130:131]
	s_mov_b32 m0, s38
	s_nop 0
	global_load_lds_dwordx4 v[190:191], off
	v_lshl_add_u64 v[190:191], s[36:37], 0, v[134:135]
	s_add_i32 m0, s38, 0x2000
	s_nop 0
	global_load_lds_dwordx4 v[190:191], off
	v_lshl_add_u64 v[190:191], v[194:195], 0, s[16:17]
	s_mov_b32 m0, s43
	s_nop 0
	global_load_lds_dwordx4 v[190:191], off
	v_lshl_add_u64 v[190:191], v[220:221], 0, s[16:17]
	s_mov_b32 m0, s50
	s_nop 0
	global_load_lds_dwordx4 v[190:191], off
	s_waitcnt vmcnt(8)
	s_waitcnt lgkmcnt(0)
	s_barrier
	s_waitcnt lgkmcnt(0)
	v_mfma_f32_16x16x32_bf16 v[60:63], v[150:153], v[182:185], v[60:63]
	v_mfma_f32_16x16x32_bf16 v[56:59], v[158:161], v[182:185], v[56:59]
	v_mfma_f32_16x16x32_bf16 v[52:55], v[150:153], v[196:199], v[52:55]
	v_mfma_f32_16x16x32_bf16 v[48:51], v[158:161], v[196:199], v[48:51]
	v_mfma_f32_16x16x32_bf16 v[36:39], v[150:153], v[204:207], v[36:39]
	v_mfma_f32_16x16x32_bf16 v[32:35], v[158:161], v[204:207], v[32:35]
	v_mfma_f32_16x16x32_bf16 v[20:23], v[150:153], v[212:215], v[20:23]
	v_mfma_f32_16x16x32_bf16 v[16:19], v[158:161], v[212:215], v[16:19]
	v_mfma_f32_16x16x32_bf16 v[60:63], v[154:157], v[186:189], v[60:63]
	v_mfma_f32_16x16x32_bf16 v[56:59], v[162:165], v[186:189], v[56:59]
	v_mfma_f32_16x16x32_bf16 v[52:55], v[154:157], v[200:203], v[52:55]
	v_mfma_f32_16x16x32_bf16 v[48:51], v[162:165], v[200:203], v[48:51]
	v_mfma_f32_16x16x32_bf16 v[36:39], v[154:157], v[208:211], v[36:39]
	v_mfma_f32_16x16x32_bf16 v[32:35], v[162:165], v[208:211], v[32:35]
	v_mfma_f32_16x16x32_bf16 v[20:23], v[154:157], v[216:219], v[20:23]
	v_mfma_f32_16x16x32_bf16 v[16:19], v[162:165], v[216:219], v[16:19]
	v_mfma_f32_16x16x32_bf16 v[44:47], v[166:169], v[182:185], v[44:47]
	v_mfma_f32_16x16x32_bf16 v[40:43], v[174:177], v[182:185], v[40:43]
	v_mfma_f32_16x16x32_bf16 v[28:31], v[166:169], v[196:199], v[28:31]
	v_mfma_f32_16x16x32_bf16 v[24:27], v[174:177], v[196:199], v[24:27]
	v_mfma_f32_16x16x32_bf16 v[12:15], v[166:169], v[204:207], v[12:15]
	v_mfma_f32_16x16x32_bf16 v[8:11], v[174:177], v[204:207], v[8:11]
	v_mfma_f32_16x16x32_bf16 v[4:7], v[166:169], v[212:215], v[4:7]
	v_mfma_f32_16x16x32_bf16 v[0:3], v[174:177], v[212:215], v[0:3]
	v_mfma_f32_16x16x32_bf16 v[44:47], v[170:173], v[186:189], v[44:47]
	v_mfma_f32_16x16x32_bf16 v[40:43], v[178:181], v[186:189], v[40:43]
	v_mfma_f32_16x16x32_bf16 v[28:31], v[170:173], v[200:203], v[28:31]
	v_mfma_f32_16x16x32_bf16 v[24:27], v[178:181], v[200:203], v[24:27]
	v_mfma_f32_16x16x32_bf16 v[12:15], v[170:173], v[208:211], v[12:15]
	v_mfma_f32_16x16x32_bf16 v[8:11], v[178:181], v[208:211], v[8:11]
	v_mfma_f32_16x16x32_bf16 v[4:7], v[170:173], v[216:219], v[4:7]
	v_mfma_f32_16x16x32_bf16 v[0:3], v[178:181], v[216:219], v[0:3]
	s_barrier
	s_add_i32 s64, s64, 2
	s_add_u32 s34, s34, 0x100
	s_addc_u32 s35, s35, 0
	s_add_u32 s62, s62, 0x100
	s_addc_u32 s63, s63, 0
	s_cmp_gt_u32 s64, 13
	s_cbranch_scc0 .LBB0_186
	s_and_b64 vcc, exec, s[18:19]
	s_cbranch_vccz .LBB0_189
	s_barrier

; #define PG8_STAGE(bufoff, gbase, voff) do { _Pragma("unroll") for (int _i = 0; _i < 2; ++_i) \
;         __builtin_amdgcn_global_load_lds((const unsigned*)((const char*)(gbase) + (voff)[_i]), (PG8_LAS unsigned*)(lds + (bufoff) + ldsw + _i * 8192), 16, 0, 0); } while (0)
; #define PG8_LDA(dst, b, h) do { _Pragma("unroll") for (int m = 0; m < 4; ++m) _Pragma("unroll") for (int k = 0; k < 2; ++k) dst[m][k] = *(const PG8_LAS bf16x8*)(lds + PG8_SA(b, h) + aoff + m * 2048 + k * 1024); } while (0)
; #define PG8_LDB(dst, b, h) do { _Pragma("unroll") for (int n = 0; n < 2; ++n) _Pragma("unroll") for (int k = 0; k < 2; ++k) dst[n][k] = *(const PG8_LAS bf16x8*)(lds + PG8_SB(b, h) + boff + n * 2048 + k * 1024); } while (0)
; #define PG8_MMA(ai, bj, At, Bt) do { __builtin_amdgcn_s_setprio(1); _Pragma("unroll") for (int m = 0; m < 4; ++m) _Pragma("unroll") for (int n = 0; n < 2; ++n) _Pragma("unroll") for (int k = 0; k < 2; ++k) \
;         acc[ai][bj][m][n] = __builtin_amdgcn_mfma_f32_16x16x32_bf16(Bt[n][k], At[m][k], acc[ai][bj][m][n], 0, 0, 0); __builtin_amdgcn_s_setprio(0); } while (0)
; #define PG8_WAIT_V(n) asm volatile("s_waitcnt vmcnt(" #n ")" ::: "memory")
; #define PG8_WAIT_L(n) asm volatile("s_waitcnt lgkmcnt(" #n ")" ::: "memory")
; #define PG8_BAR __builtin_amdgcn_s_barrier()
; #define PG8_SCHED __builtin_amdgcn_sched_barrier(0)
; template <class Epi, class Sched, bool ALIGN_EPI = false, bool SP2 = false>
; __device__ __forceinline__ void gemm_phase(PG8_LAS unsigned char* lds, const Gemm g, const Sched& S, const Epi& E) {
;     ...
;             const bool last = (t == nt - 2);
;             const char* a1 = cA + (size_t)(t + 1) * kstep;
;             const char* a2 = last ? nA : cA + (size_t)(t + 2) * kstep; const char* b2 = last ? nB : cB + (size_t)(t + 2) * kstep;
;             const char* a3 = a2 + kstep; const char* b3 = b2 + kstep;
;             if (last && has_next) S.a_ready(nxt);
;             if constexpr (SP2) {
;             PG8_LDB(B0, 0, 0); PG8_LDB(B1, 0, 1); PG8_SCHED; PG8_LDA(At, 0, 0); PG8_STAGE(PG8_SA(1, 1), a1 + hstepA, voffA);
;             PG8_WAIT_V(8); PG8_WAIT_L(0); PG8_BAR; PG8_MMA(0, 0, At, B0); PG8_MMA(0, 1, At, B1); PG8_BAR; PG8_SCHED;
;             PG8_LDA(At, 0, 1); PG8_STAGE(PG8_SB(0, 0), b2, voffB); PG8_STAGE(PG8_SB(0, 1), b2 + hstepB, voffB); PG8_STAGE(PG8_SA(0, 0), a2, voffA);
.LBB0_210:
	ds_read_b128 v[146:149], v143
	ds_read_b128 v[150:153], v143 offset:1024
	ds_read_b128 v[154:157], v143 offset:2048
	ds_read_b128 v[158:161], v143 offset:3072
	ds_read_b128 v[162:165], v144
	ds_read_b128 v[166:169], v144 offset:1024
	ds_read_b128 v[170:173], v144 offset:2048
	ds_read_b128 v[174:177], v144 offset:3072
	s_add_u32 s36, s34, 0xfffc0080
	s_addc_u32 s37, s35, -1
	s_cmp_eq_u32 s64, 12
	s_cselect_b32 s39, s25, s37
	s_cselect_b32 s38, s60, s36
	s_cselect_b32 s37, s23, s63
	s_cselect_b32 s36, s61, s62
	v_lshl_add_u64 v[190:191], s[34:35], 0, v[132:133]
	s_add_i32 m0, s31, 0xc000
	ds_read_b128 v[178:181], v145
	ds_read_b128 v[182:185], v145 offset:1024
	ds_read_b128 v[186:189], v145 offset:2048
	ds_read_b128 v[196:199], v145 offset:3072
	ds_read_b128 v[200:203], v145 offset:4096
	ds_read_b128 v[204:207], v145 offset:5120
	ds_read_b128 v[208:211], v145 offset:6144
	ds_read_b128 v[212:215], v145 offset:7168
	global_load_lds_dwordx4 v[190:191], off
	v_lshl_add_u64 v[190:191], s[34:35], 0, v[134:135]
	s_add_i32 m0, s31, 0xe000
	s_nop 0
	global_load_lds_dwordx4 v[190:191], off
	s_waitcnt vmcnt(8)
	s_waitcnt lgkmcnt(0)
	s_barrier
	s_waitcnt lgkmcnt(0)
	v_mfma_f32_16x16x32_bf16 v[124:127], v[146:149], v[178:181], v[124:127]
	v_mfma_f32_16x16x32_bf16 v[120:123], v[154:157], v[178:181], v[120:123]
	v_mfma_f32_16x16x32_bf16 v[108:111], v[146:149], v[186:189], v[108:111]
	v_mfma_f32_16x16x32_bf16 v[104:107], v[154:157], v[186:189], v[104:107]
	v_mfma_f32_16x16x32_bf16 v[92:95], v[146:149], v[200:203], v[92:95]
	v_mfma_f32_16x16x32_bf16 v[88:91], v[154:157], v[200:203], v[88:91]
	v_mfma_f32_16x16x32_bf16 v[76:79], v[146:149], v[208:211], v[76:79]
	v_mfma_f32_16x16x32_bf16 v[72:75], v[154:157], v[208:211], v[72:75]
	v_mfma_f32_16x16x32_bf16 v[124:127], v[150:153], v[182:185], v[124:127]
	v_mfma_f32_16x16x32_bf16 v[120:123], v[158:161], v[182:185], v[120:123]
	v_mfma_f32_16x16x32_bf16 v[108:111], v[150:153], v[196:199], v[108:111]
	v_mfma_f32_16x16x32_bf16 v[104:107], v[158:161], v[196:199], v[104:107]
	v_mfma_f32_16x16x32_bf16 v[92:95], v[150:153], v[204:207], v[92:95]
	v_mfma_f32_16x16x32_bf16 v[88:91], v[158:161], v[204:207], v[88:91]
	v_mfma_f32_16x16x32_bf16 v[76:79], v[150:153], v[212:215], v[76:79]
	v_mfma_f32_16x16x32_bf16 v[72:75], v[158:161], v[212:215], v[72:75]
	v_mfma_f32_16x16x32_bf16 v[116:119], v[162:165], v[178:181], v[116:119]
	v_mfma_f32_16x16x32_bf16 v[112:115], v[170:173], v[178:181], v[112:115]
	v_mfma_f32_16x16x32_bf16 v[100:103], v[162:165], v[186:189], v[100:103]
	v_mfma_f32_16x16x32_bf16 v[96:99], v[170:173], v[186:189], v[96:99]
	v_mfma_f32_16x16x32_bf16 v[84:87], v[162:165], v[200:203], v[84:87]
	v_mfma_f32_16x16x32_bf16 v[80:83], v[170:173], v[200:203], v[80:83]
	v_mfma_f32_16x16x32_bf16 v[68:71], v[162:165], v[208:211], v[68:71]
	v_mfma_f32_16x16x32_bf16 v[64:67], v[170:173], v[208:211], v[64:67]
	v_mfma_f32_16x16x32_bf16 v[116:119], v[166:169], v[182:185], v[116:119]
	v_mfma_f32_16x16x32_bf16 v[112:115], v[174:177], v[182:185], v[112:115]
	v_mfma_f32_16x16x32_bf16 v[100:103], v[166:169], v[196:199], v[100:103]
	v_mfma_f32_16x16x32_bf16 v[96:99], v[174:177], v[196:199], v[96:99]
	v_mfma_f32_16x16x32_bf16 v[84:87], v[166:169], v[204:207], v[84:87]
	v_mfma_f32_16x16x32_bf16 v[80:83], v[174:177], v[204:207], v[80:83]
	v_mfma_f32_16x16x32_bf16 v[68:71], v[166:169], v[212:215], v[68:71]
	v_mfma_f32_16x16x32_bf16 v[64:67], v[174:177], v[212:215], v[64:67]
	s_barrier
	s_add_i32 s44, s57, s9
	v_lshl_add_u64 v[190:191], s[36:37], 0, v[128:129]
	s_mov_b32 m0, s44
	ds_read_b128 v[178:181], v145 offset:16384
	ds_read_b128 v[182:185], v145 offset:17408
	ds_read_b128 v[186:189], v145 offset:18432
	ds_read_b128 v[196:199], v145 offset:19456
	ds_read_b128 v[200:203], v145 offset:20480
	ds_read_b128 v[204:207], v145 offset:21504
	ds_read_b128 v[208:211], v145 offset:22528
	ds_read_b128 v[212:215], v145 offset:23552
	global_load_lds_dwordx4 v[190:191], off
	s_add_i32 m0, s44, 0x2000
	s_add_u32 s44, s36, 0x40000
	v_lshl_add_u64 v[192:193], s[36:37], 0, v[130:131]
	s_addc_u32 s45, s37, 0
	s_add_i32 s48, s58, s9
	global_load_lds_dwordx4 v[192:193], off
	v_lshl_add_u64 v[194:195], s[44:45], 0, v[128:129]
	s_mov_b32 m0, s48
	v_lshl_add_u64 v[216:217], s[38:39], 0, v[130:131]
	global_load_lds_dwordx4 v[194:195], off
	v_lshl_add_u64 v[194:195], s[44:45], 0, v[130:131]
	s_add_i32 m0, s48, 0x2000
	s_nop 0
	global_load_lds_dwordx4 v[194:195], off
	v_lshl_add_u64 v[194:195], s[38:39], 0, v[128:129]
	s_mov_b32 m0, s31
	s_nop 0
	global_load_lds_dwordx4 v[194:195], off
	s_mov_b32 m0, s33
	s_nop 0
	global_load_lds_dwordx4 v[216:217], off
	s_waitcnt vmcnt(8)
	s_waitcnt lgkmcnt(0)
	s_barrier
; #define PG8_STAGE(bufoff, gbase, voff) do { _Pragma("unroll") for (int _i = 0; _i < 2; ++_i) \
;         __builtin_amdgcn_global_load_lds((const unsigned*)((const char*)(gbase) + (voff)[_i]), (PG8_LAS unsigned*)(lds + (bufoff) + ldsw + _i * 8192), 16, 0, 0); } while (0)
; #define PG8_LDA(dst, b, h) do { _Pragma("unroll") for (int m = 0; m < 4; ++m) _Pragma("unroll") for (int k = 0; k < 2; ++k) dst[m][k] = *(const PG8_LAS bf16x8*)(lds + PG8_SA(b, h) + aoff + m * 2048 + k * 1024); } while (0)
; #define PG8_LDB(dst, b, h) do { _Pragma("unroll") for (int n = 0; n < 2; ++n) _Pragma("unroll") for (int k = 0; k < 2; ++k) dst[n][k] = *(const PG8_LAS bf16x8*)(lds + PG8_SB(b, h) + boff + n * 2048 + k * 1024); } while (0)
; #define PG8_MMA(ai, bj, At, Bt) do { __builtin_amdgcn_s_setprio(1); _Pragma("unroll") for (int m = 0; m < 4; ++m) _Pragma("unroll") for (int n = 0; n < 2; ++n) _Pragma("unroll") for (int k = 0; k < 2; ++k) \
;         acc[ai][bj][m][n] = __builtin_amdgcn_mfma_f32_16x16x32_bf16(Bt[n][k], At[m][k], acc[ai][bj][m][n], 0, 0, 0); __builtin_amdgcn_s_setprio(0); } while (0)
; #define PG8_WAIT_V(n) asm volatile("s_waitcnt vmcnt(" #n ")" ::: "memory")
; #define PG8_WAIT_L(n) asm volatile("s_waitcnt lgkmcnt(" #n ")" ::: "memory")
; #define PG8_BAR __builtin_amdgcn_s_barrier()
; #define PG8_SCHED __builtin_amdgcn_sched_barrier(0)
; template <class Epi, class Sched, bool ALIGN_EPI = false, bool SP2 = false>
; __device__ __forceinline__ void gemm_phase(PG8_LAS unsigned char* lds, const Gemm g, const Sched& S, const Epi& E) {
;     ...
;             PG8_WAIT_V(8); PG8_WAIT_L(0); PG8_BAR; PG8_MMA(1, 0, At, B0); PG8_MMA(1, 1, At, B1); PG8_BAR; PG8_SCHED;
;             PG8_LDB(B0, 1, 0); PG8_LDB(B1, 1, 1); PG8_SCHED; PG8_LDA(At, 1, 0); PG8_STAGE(PG8_SA(0, 1), a2 + hstepA, voffA);
;             PG8_WAIT_V(8); PG8_WAIT_L(0); PG8_BAR; PG8_MMA(0, 0, At, B0); PG8_MMA(0, 1, At, B1); PG8_BAR; PG8_SCHED;
	s_waitcnt lgkmcnt(0)
	v_mfma_f32_16x16x32_bf16 v[60:63], v[146:149], v[178:181], v[60:63]
	v_mfma_f32_16x16x32_bf16 v[56:59], v[154:157], v[178:181], v[56:59]
	v_mfma_f32_16x16x32_bf16 v[44:47], v[146:149], v[186:189], v[44:47]
	v_mfma_f32_16x16x32_bf16 v[40:43], v[154:157], v[186:189], v[40:43]
	v_mfma_f32_16x16x32_bf16 v[28:31], v[146:149], v[200:203], v[28:31]
	v_mfma_f32_16x16x32_bf16 v[24:27], v[154:157], v[200:203], v[24:27]
	v_mfma_f32_16x16x32_bf16 v[12:15], v[146:149], v[208:211], v[12:15]
	v_mfma_f32_16x16x32_bf16 v[8:11], v[154:157], v[208:211], v[8:11]
	v_mfma_f32_16x16x32_bf16 v[60:63], v[150:153], v[182:185], v[60:63]
	v_mfma_f32_16x16x32_bf16 v[56:59], v[158:161], v[182:185], v[56:59]
	v_mfma_f32_16x16x32_bf16 v[44:47], v[150:153], v[196:199], v[44:47]
	v_mfma_f32_16x16x32_bf16 v[40:43], v[158:161], v[196:199], v[40:43]
	v_mfma_f32_16x16x32_bf16 v[28:31], v[150:153], v[204:207], v[28:31]
	v_mfma_f32_16x16x32_bf16 v[24:27], v[158:161], v[204:207], v[24:27]
	v_mfma_f32_16x16x32_bf16 v[12:15], v[150:153], v[212:215], v[12:15]
	v_mfma_f32_16x16x32_bf16 v[8:11], v[158:161], v[212:215], v[8:11]
	v_mfma_f32_16x16x32_bf16 v[52:55], v[162:165], v[178:181], v[52:55]
	v_mfma_f32_16x16x32_bf16 v[48:51], v[170:173], v[178:181], v[48:51]
	v_mfma_f32_16x16x32_bf16 v[36:39], v[162:165], v[186:189], v[36:39]
	v_mfma_f32_16x16x32_bf16 v[32:35], v[170:173], v[186:189], v[32:35]
	v_mfma_f32_16x16x32_bf16 v[20:23], v[162:165], v[200:203], v[20:23]
	v_mfma_f32_16x16x32_bf16 v[16:19], v[170:173], v[200:203], v[16:19]
	v_mfma_f32_16x16x32_bf16 v[4:7], v[162:165], v[208:211], v[4:7]
	v_mfma_f32_16x16x32_bf16 v[0:3], v[170:173], v[208:211], v[0:3]
	v_mfma_f32_16x16x32_bf16 v[52:55], v[166:169], v[182:185], v[52:55]
	v_mfma_f32_16x16x32_bf16 v[48:51], v[174:177], v[182:185], v[48:51]
	v_mfma_f32_16x16x32_bf16 v[36:39], v[166:169], v[196:199], v[36:39]
	v_mfma_f32_16x16x32_bf16 v[32:35], v[174:177], v[196:199], v[32:35]
	v_mfma_f32_16x16x32_bf16 v[20:23], v[166:169], v[204:207], v[20:23]
	v_mfma_f32_16x16x32_bf16 v[16:19], v[174:177], v[204:207], v[16:19]
	v_mfma_f32_16x16x32_bf16 v[4:7], v[166:169], v[212:215], v[4:7]
	v_mfma_f32_16x16x32_bf16 v[0:3], v[174:177], v[212:215], v[0:3]
	s_barrier
	s_add_i32 s44, 0, 0x18000
	s_add_i32 s45, 0, 0x1c000
	v_add_u32_e32 v158, s44, v142
	v_add_u32_e32 v174, s45, v142
	ds_read_b128 v[146:149], v158
	ds_read_b128 v[150:153], v158 offset:1024
	ds_read_b128 v[154:157], v158 offset:2048
	ds_read_b128 v[158:161], v158 offset:3072
	ds_read_b128 v[162:165], v174
	ds_read_b128 v[166:169], v174 offset:1024
	ds_read_b128 v[170:173], v174 offset:2048
	ds_read_b128 v[174:177], v174 offset:3072
	s_add_u32 s38, s38, 0x40000
	s_addc_u32 s39, s39, 0
	s_mov_b32 m0, s40
	v_lshl_add_u64 v[218:219], s[38:39], 0, v[128:129]
	ds_read_b128 v[178:181], v145 offset:32768
	ds_read_b128 v[182:185], v145 offset:33792
	ds_read_b128 v[186:189], v145 offset:34816
	ds_read_b128 v[196:199], v145 offset:35840
	ds_read_b128 v[200:203], v145 offset:36864
	ds_read_b128 v[204:207], v145 offset:37888
	ds_read_b128 v[208:211], v145 offset:38912
	ds_read_b128 v[212:215], v145 offset:39936
	global_load_lds_dwordx4 v[218:219], off
	v_lshl_add_u64 v[218:219], s[38:39], 0, v[130:131]
	s_mov_b32 m0, s41
	s_nop 0
	global_load_lds_dwordx4 v[218:219], off
	s_waitcnt vmcnt(8)
	s_waitcnt lgkmcnt(0)
	s_barrier
	s_waitcnt lgkmcnt(0)
	v_mfma_f32_16x16x32_bf16 v[124:127], v[146:149], v[178:181], v[124:127]
	v_mfma_f32_16x16x32_bf16 v[120:123], v[154:157], v[178:181], v[120:123]
	v_mfma_f32_16x16x32_bf16 v[108:111], v[146:149], v[186:189], v[108:111]
	v_mfma_f32_16x16x32_bf16 v[104:107], v[154:157], v[186:189], v[104:107]
	v_mfma_f32_16x16x32_bf16 v[92:95], v[146:149], v[200:203], v[92:95]
	v_mfma_f32_16x16x32_bf16 v[88:91], v[154:157], v[200:203], v[88:91]
	v_mfma_f32_16x16x32_bf16 v[76:79], v[146:149], v[208:211], v[76:79]
	v_mfma_f32_16x16x32_bf16 v[72:75], v[154:157], v[208:211], v[72:75]
	v_mfma_f32_16x16x32_bf16 v[124:127], v[150:153], v[182:185], v[124:127]
	v_mfma_f32_16x16x32_bf16 v[120:123], v[158:161], v[182:185], v[120:123]
	v_mfma_f32_16x16x32_bf16 v[108:111], v[150:153], v[196:199], v[108:111]
	v_mfma_f32_16x16x32_bf16 v[104:107], v[158:161], v[196:199], v[104:107]
	v_mfma_f32_16x16x32_bf16 v[92:95], v[150:153], v[204:207], v[92:95]
	v_mfma_f32_16x16x32_bf16 v[88:91], v[158:161], v[204:207], v[88:91]
	v_mfma_f32_16x16x32_bf16 v[76:79], v[150:153], v[212:215], v[76:79]
	v_mfma_f32_16x16x32_bf16 v[72:75], v[158:161], v[212:215], v[72:75]
	v_mfma_f32_16x16x32_bf16 v[116:119], v[162:165], v[178:181], v[116:119]
	v_mfma_f32_16x16x32_bf16 v[112:115], v[170:173], v[178:181], v[112:115]
	v_mfma_f32_16x16x32_bf16 v[100:103], v[162:165], v[186:189], v[100:103]
	v_mfma_f32_16x16x32_bf16 v[96:99], v[170:173], v[186:189], v[96:99]
	v_mfma_f32_16x16x32_bf16 v[84:87], v[162:165], v[200:203], v[84:87]
	v_mfma_f32_16x16x32_bf16 v[80:83], v[170:173], v[200:203], v[80:83]
	v_mfma_f32_16x16x32_bf16 v[68:71], v[162:165], v[208:211], v[68:71]
	v_mfma_f32_16x16x32_bf16 v[64:67], v[170:173], v[208:211], v[64:67]
	v_mfma_f32_16x16x32_bf16 v[116:119], v[166:169], v[182:185], v[116:119]
	v_mfma_f32_16x16x32_bf16 v[112:115], v[174:177], v[182:185], v[112:115]
	v_mfma_f32_16x16x32_bf16 v[100:103], v[166:169], v[196:199], v[100:103]
	v_mfma_f32_16x16x32_bf16 v[96:99], v[174:177], v[196:199], v[96:99]
	v_mfma_f32_16x16x32_bf16 v[84:87], v[166:169], v[204:207], v[84:87]
	v_mfma_f32_16x16x32_bf16 v[80:83], v[174:177], v[204:207], v[80:83]
	v_mfma_f32_16x16x32_bf16 v[68:71], v[166:169], v[212:215], v[68:71]
	v_mfma_f32_16x16x32_bf16 v[64:67], v[174:177], v[212:215], v[64:67]
	s_barrier
; #define PG8_STAGE(bufoff, gbase, voff) do { _Pragma("unroll") for (int _i = 0; _i < 2; ++_i) \
;         __builtin_amdgcn_global_load_lds((const unsigned*)((const char*)(gbase) + (voff)[_i]), (PG8_LAS unsigned*)(lds + (bufoff) + ldsw + _i * 8192), 16, 0, 0); } while (0)
; #define PG8_LDA(dst, b, h) do { _Pragma("unroll") for (int m = 0; m < 4; ++m) _Pragma("unroll") for (int k = 0; k < 2; ++k) dst[m][k] = *(const PG8_LAS bf16x8*)(lds + PG8_SA(b, h) + aoff + m * 2048 + k * 1024); } while (0)
; #define PG8_MMA(ai, bj, At, Bt) do { __builtin_amdgcn_s_setprio(1); _Pragma("unroll") for (int m = 0; m < 4; ++m) _Pragma("unroll") for (int n = 0; n < 2; ++n) _Pragma("unroll") for (int k = 0; k < 2; ++k) \
;         acc[ai][bj][m][n] = __builtin_amdgcn_mfma_f32_16x16x32_bf16(Bt[n][k], At[m][k], acc[ai][bj][m][n], 0, 0, 0); __builtin_amdgcn_s_setprio(0); } while (0)
; #define PG8_WAIT_V(n) asm volatile("s_waitcnt vmcnt(" #n ")" ::: "memory")
; #define PG8_WAIT_L(n) asm volatile("s_waitcnt lgkmcnt(" #n ")" ::: "memory")
; #define PG8_BAR __builtin_amdgcn_s_barrier()
; #define PG8_SCHED __builtin_amdgcn_sched_barrier(0)
; template <class Epi, class Sched, bool ALIGN_EPI = false, bool SP2 = false>
; __device__ __forceinline__ void gemm_phase(PG8_LAS unsigned char* lds, const Gemm g, const Sched& S, const Epi& E) {
;     ...
;             PG8_LDA(At, 1, 1); PG8_STAGE(PG8_SB(1, 0), b3, voffB); PG8_STAGE(PG8_SB(1, 1), b3 + hstepB, voffB); PG8_STAGE(PG8_SA(1, 0), a3, voffA);
;             PG8_WAIT_V(8); PG8_WAIT_L(0); PG8_BAR; PG8_MMA(1, 0, At, B0); PG8_MMA(1, 1, At, B1); PG8_BAR; PG8_SCHED;
	s_add_i32 s38, s44, s9
	v_lshl_add_u64 v[190:191], v[190:191], 0, s[16:17]
	s_mov_b32 m0, s38
	ds_read_b128 v[178:181], v145 offset:49152
	ds_read_b128 v[182:185], v145 offset:50176
	ds_read_b128 v[186:189], v145 offset:51200
	ds_read_b128 v[196:199], v145 offset:52224
	ds_read_b128 v[200:203], v145 offset:53248
	ds_read_b128 v[204:207], v145 offset:54272
	ds_read_b128 v[208:211], v145 offset:55296
	ds_read_b128 v[212:215], v145 offset:56320
	global_load_lds_dwordx4 v[190:191], off
	s_add_i32 m0, s38, 0x2000
	s_add_u32 s36, s36, 0x40080
	v_lshl_add_u64 v[190:191], v[192:193], 0, s[16:17]
	s_addc_u32 s37, s37, 0
	s_add_i32 s38, s45, s9
	global_load_lds_dwordx4 v[190:191], off
	v_lshl_add_u64 v[190:191], s[36:37], 0, v[128:129]
	s_mov_b32 m0, s38
	s_nop 0
	global_load_lds_dwordx4 v[190:191], off
	v_lshl_add_u64 v[190:191], s[36:37], 0, v[130:131]
	s_add_i32 m0, s38, 0x2000
	s_nop 0
	global_load_lds_dwordx4 v[190:191], off
	v_lshl_add_u64 v[190:191], v[194:195], 0, s[16:17]
	s_mov_b32 m0, s50
	s_nop 0
	global_load_lds_dwordx4 v[190:191], off
	v_lshl_add_u64 v[190:191], v[216:217], 0, s[16:17]
	s_mov_b32 m0, s51
	s_nop 0
	global_load_lds_dwordx4 v[190:191], off
	s_waitcnt vmcnt(8)
	s_waitcnt lgkmcnt(0)
	s_barrier
	s_waitcnt lgkmcnt(0)
	v_mfma_f32_16x16x32_bf16 v[60:63], v[146:149], v[178:181], v[60:63]
	v_mfma_f32_16x16x32_bf16 v[56:59], v[154:157], v[178:181], v[56:59]
	v_mfma_f32_16x16x32_bf16 v[44:47], v[146:149], v[186:189], v[44:47]
	v_mfma_f32_16x16x32_bf16 v[40:43], v[154:157], v[186:189], v[40:43]
	v_mfma_f32_16x16x32_bf16 v[28:31], v[146:149], v[200:203], v[28:31]
	v_mfma_f32_16x16x32_bf16 v[24:27], v[154:157], v[200:203], v[24:27]
	v_mfma_f32_16x16x32_bf16 v[12:15], v[146:149], v[208:211], v[12:15]
	v_mfma_f32_16x16x32_bf16 v[8:11], v[154:157], v[208:211], v[8:11]
	v_mfma_f32_16x16x32_bf16 v[60:63], v[150:153], v[182:185], v[60:63]
	v_mfma_f32_16x16x32_bf16 v[56:59], v[158:161], v[182:185], v[56:59]
	v_mfma_f32_16x16x32_bf16 v[44:47], v[150:153], v[196:199], v[44:47]
	v_mfma_f32_16x16x32_bf16 v[40:43], v[158:161], v[196:199], v[40:43]
	v_mfma_f32_16x16x32_bf16 v[28:31], v[150:153], v[204:207], v[28:31]
	v_mfma_f32_16x16x32_bf16 v[24:27], v[158:161], v[204:207], v[24:27]
	v_mfma_f32_16x16x32_bf16 v[12:15], v[150:153], v[212:215], v[12:15]
	v_mfma_f32_16x16x32_bf16 v[8:11], v[158:161], v[212:215], v[8:11]
	v_mfma_f32_16x16x32_bf16 v[52:55], v[162:165], v[178:181], v[52:55]
	v_mfma_f32_16x16x32_bf16 v[48:51], v[170:173], v[178:181], v[48:51]
	v_mfma_f32_16x16x32_bf16 v[36:39], v[162:165], v[186:189], v[36:39]
	v_mfma_f32_16x16x32_bf16 v[32:35], v[170:173], v[186:189], v[32:35]
	v_mfma_f32_16x16x32_bf16 v[20:23], v[162:165], v[200:203], v[20:23]
	v_mfma_f32_16x16x32_bf16 v[16:19], v[170:173], v[200:203], v[16:19]
	v_mfma_f32_16x16x32_bf16 v[4:7], v[162:165], v[208:211], v[4:7]
	v_mfma_f32_16x16x32_bf16 v[0:3], v[170:173], v[208:211], v[0:3]
	v_mfma_f32_16x16x32_bf16 v[52:55], v[166:169], v[182:185], v[52:55]
	v_mfma_f32_16x16x32_bf16 v[48:51], v[174:177], v[182:185], v[48:51]
	v_mfma_f32_16x16x32_bf16 v[36:39], v[166:169], v[196:199], v[36:39]
	v_mfma_f32_16x16x32_bf16 v[32:35], v[174:177], v[196:199], v[32:35]
	v_mfma_f32_16x16x32_bf16 v[20:23], v[166:169], v[204:207], v[20:23]
	v_mfma_f32_16x16x32_bf16 v[16:19], v[174:177], v[204:207], v[16:19]
	v_mfma_f32_16x16x32_bf16 v[4:7], v[166:169], v[212:215], v[4:7]
	v_mfma_f32_16x16x32_bf16 v[0:3], v[174:177], v[212:215], v[0:3]
	s_barrier
	s_add_i32 s64, s64, 2
	s_add_u32 s34, s34, 0x100
	s_addc_u32 s35, s35, 0
	s_add_u32 s62, s62, 0x100
	s_addc_u32 s63, s63, 0
	s_cmp_gt_u32 s64, 13
	s_cbranch_scc0 .LBB0_210
	s_and_b64 vcc, exec, s[18:19]
	s_cbranch_vccz .LBB0_213
	s_barrier

; #define PG8_STAGE(bufoff, gbase, voff) do { _Pragma("unroll") for (int _i = 0; _i < 2; ++_i) \
;         __builtin_amdgcn_global_load_lds((const unsigned*)((const char*)(gbase) + (voff)[_i]), (PG8_LAS unsigned*)(lds + (bufoff) + ldsw + _i * 8192), 16, 0, 0); } while (0)
; #define PG8_LDA(dst, b, h) do { _Pragma("unroll") for (int m = 0; m < 4; ++m) _Pragma("unroll") for (int k = 0; k < 2; ++k) dst[m][k] = *(const PG8_LAS bf16x8*)(lds + PG8_SA(b, h) + aoff + m * 2048 + k * 1024); } while (0)
; #define PG8_LDB(dst, b, h) do { _Pragma("unroll") for (int n = 0; n < 2; ++n) _Pragma("unroll") for (int k = 0; k < 2; ++k) dst[n][k] = *(const PG8_LAS bf16x8*)(lds + PG8_SB(b, h) + boff + n * 2048 + k * 1024); } while (0)
; #define PG8_MMA(ai, bj, At, Bt) do { __builtin_amdgcn_s_setprio(1); _Pragma("unroll") for (int m = 0; m < 4; ++m) _Pragma("unroll") for (int n = 0; n < 2; ++n) _Pragma("unroll") for (int k = 0; k < 2; ++k) \
;         acc[ai][bj][m][n] = __builtin_amdgcn_mfma_f32_16x16x32_bf16(Bt[n][k], At[m][k], acc[ai][bj][m][n], 0, 0, 0); __builtin_amdgcn_s_setprio(0); } while (0)
; #define PG8_WAIT_V(n) asm volatile("s_waitcnt vmcnt(" #n ")" ::: "memory")
; template <class Epi, class Sched, bool ALIGN_EPI = false, bool SP2 = false>
; __device__ __forceinline__ void gemm_phase(PG8_LAS unsigned char* lds, const Gemm g, const Sched& S, const Epi& E) {
;     ...
;         const char* nA = has_next ? (const char*)g.A + (size_t)nxt.pm * tstepA : cA; const char* nB = has_next ? (const char*)g.Bt + (size_t)nxt.pn * tstepB : cB;
;         for (int t = 0; t < nt; t += 2) {
;             const bool last = (t == nt - 2);
;             const char* a1 = cA + (size_t)(t + 1) * kstep;
;             const char* a2 = last ? nA : cA + (size_t)(t + 2) * kstep; const char* b2 = last ? nB : cB + (size_t)(t + 2) * kstep;
;             const char* a3 = a2 + kstep; const char* b3 = b2 + kstep;
;             if (last && has_next) S.a_ready(nxt);
;             if constexpr (SP2) {
;             PG8_LDB(B0, 0, 0); PG8_LDB(B1, 0, 1); PG8_SCHED; PG8_LDA(At, 0, 0); PG8_STAGE(PG8_SA(1, 1), a1 + hstepA, voffA);
;             PG8_WAIT_V(8); PG8_WAIT_L(0); PG8_BAR; PG8_MMA(0, 0, At, B0); PG8_MMA(0, 1, At, B1); PG8_BAR; PG8_SCHED;
;             PG8_LDA(At, 0, 1); PG8_STAGE(PG8_SB(0, 0), b2, voffB); PG8_STAGE(PG8_SB(0, 1), b2 + hstepB, voffB); PG8_STAGE(PG8_SA(0, 0), a2, voffA);
.LBB0_234:
	ds_read_b128 v[0:3], v143
	ds_read_b128 v[4:7], v143 offset:1024
	ds_read_b128 v[8:11], v143 offset:2048
	ds_read_b128 v[12:15], v143 offset:3072
	ds_read_b128 v[16:19], v144
	ds_read_b128 v[20:23], v144 offset:1024
	ds_read_b128 v[24:27], v144 offset:2048
	ds_read_b128 v[28:31], v144 offset:3072
	s_ashr_i32 s31, s30, 31
	s_lshl_b64 s[34:35], s[30:31], 17
	s_add_u32 s34, s54, s34
	s_addc_u32 s35, s55, s35
	s_and_b64 s[36:37], s[4:5], exec
	s_cselect_b32 s53, s35, s39
	s_cselect_b32 s52, s34, s38
	s_ashr_i32 s29, s28, 31
	s_lshl_b64 s[36:37], s[28:29], 17
	s_add_u32 s36, s2, s36
	s_addc_u32 s37, s3, s37
	s_and_b64 s[44:45], s[4:5], exec
	s_cselect_b32 s51, s37, s41
	s_cselect_b32 s50, s36, s40
	s_add_u32 s44, s38, 0x10080
	s_addc_u32 s45, s39, 0
	s_add_i32 s62, s9, 0xc000
	v_lshl_add_u64 v[64:65], s[44:45], 0, v[128:129]
	s_mov_b32 m0, s62
	s_add_i32 s29, s9, 0xe000
	ds_read_b128 v[32:35], v145
	ds_read_b128 v[36:39], v145 offset:1024
	ds_read_b128 v[40:43], v145 offset:2048
	ds_read_b128 v[44:47], v145 offset:3072
	ds_read_b128 v[48:51], v145 offset:4096
	ds_read_b128 v[52:55], v145 offset:5120
	ds_read_b128 v[56:59], v145 offset:6144
	ds_read_b128 v[60:63], v145 offset:7168
	global_load_lds_dwordx4 v[64:65], off
	v_lshl_add_u64 v[64:65], s[44:45], 0, v[132:133]
	s_mov_b32 m0, s29
	s_nop 0
	global_load_lds_dwordx4 v[64:65], off
	s_waitcnt vmcnt(8)
	s_waitcnt lgkmcnt(0)
	s_barrier
	s_waitcnt lgkmcnt(0)
	v_mfma_f32_16x16x32_bf16 v[64:67], v[0:3], v[32:35], 0
	v_mfma_f32_16x16x32_bf16 v[68:71], v[8:11], v[32:35], 0
	v_mfma_f32_16x16x32_bf16 v[72:75], v[0:3], v[40:43], 0
	v_mfma_f32_16x16x32_bf16 v[76:79], v[8:11], v[40:43], 0
	v_mfma_f32_16x16x32_bf16 v[80:83], v[0:3], v[48:51], 0
	v_mfma_f32_16x16x32_bf16 v[84:87], v[8:11], v[48:51], 0
	v_mfma_f32_16x16x32_bf16 v[88:91], v[0:3], v[56:59], 0
	v_mfma_f32_16x16x32_bf16 v[92:95], v[8:11], v[56:59], 0
	v_mfma_f32_16x16x32_bf16 v[64:67], v[4:7], v[36:39], v[64:67]
	v_mfma_f32_16x16x32_bf16 v[68:71], v[12:15], v[36:39], v[68:71]
	v_mfma_f32_16x16x32_bf16 v[72:75], v[4:7], v[44:47], v[72:75]
	v_mfma_f32_16x16x32_bf16 v[76:79], v[12:15], v[44:47], v[76:79]
	v_mfma_f32_16x16x32_bf16 v[80:83], v[4:7], v[52:55], v[80:83]
	v_mfma_f32_16x16x32_bf16 v[84:87], v[12:15], v[52:55], v[84:87]
	v_mfma_f32_16x16x32_bf16 v[88:91], v[4:7], v[60:63], v[88:91]
	v_mfma_f32_16x16x32_bf16 v[92:95], v[12:15], v[60:63], v[92:95]
	v_mfma_f32_16x16x32_bf16 v[96:99], v[16:19], v[32:35], 0
	v_mfma_f32_16x16x32_bf16 v[32:35], v[24:27], v[32:35], 0
	v_mfma_f32_16x16x32_bf16 v[96:99], v[20:23], v[36:39], v[96:99]
	v_mfma_f32_16x16x32_bf16 v[32:35], v[28:31], v[36:39], v[32:35]
	v_mfma_f32_16x16x32_bf16 v[36:39], v[16:19], v[40:43], 0
	v_mfma_f32_16x16x32_bf16 v[40:43], v[24:27], v[40:43], 0
	v_mfma_f32_16x16x32_bf16 v[36:39], v[20:23], v[44:47], v[36:39]
	v_mfma_f32_16x16x32_bf16 v[40:43], v[28:31], v[44:47], v[40:43]
	v_mfma_f32_16x16x32_bf16 v[44:47], v[16:19], v[48:51], 0
	v_mfma_f32_16x16x32_bf16 v[48:51], v[24:27], v[48:51], 0
	v_mfma_f32_16x16x32_bf16 v[44:47], v[20:23], v[52:55], v[44:47]
	v_mfma_f32_16x16x32_bf16 v[48:51], v[28:31], v[52:55], v[48:51]
	v_mfma_f32_16x16x32_bf16 v[52:55], v[16:19], v[56:59], 0
	v_mfma_f32_16x16x32_bf16 v[56:59], v[24:27], v[56:59], 0
	v_mfma_f32_16x16x32_bf16 v[52:55], v[20:23], v[60:63], v[52:55]
	v_mfma_f32_16x16x32_bf16 v[56:59], v[28:31], v[60:63], v[56:59]
	s_barrier
	s_add_i32 s48, s59, s8
	v_lshl_add_u64 v[190:191], s[40:41], 0, v[130:131]
	s_add_i32 s31, s48, 0x2000
	v_lshl_add_u64 v[146:147], v[190:191], 0, s[22:23]
	s_mov_b32 m0, s48
	v_lshl_add_u64 v[192:193], s[40:41], 0, v[134:135]
	s_add_u32 s64, s40, 0x10100
	ds_read_b128 v[60:63], v145 offset:16384
	ds_read_b128 v[100:103], v145 offset:17408
	ds_read_b128 v[104:107], v145 offset:18432
	ds_read_b128 v[108:111], v145 offset:19456
	ds_read_b128 v[112:115], v145 offset:20480
	ds_read_b128 v[116:119], v145 offset:21504
	ds_read_b128 v[120:123], v145 offset:22528
	ds_read_b128 v[124:127], v145 offset:23552
	global_load_lds_dwordx4 v[146:147], off
	v_lshl_add_u64 v[146:147], v[192:193], 0, s[22:23]
	s_mov_b32 m0, s31
	s_addc_u32 s65, s41, 0
	s_add_i32 s44, s60, s8
	global_load_lds_dwordx4 v[146:147], off
	v_lshl_add_u64 v[146:147], s[64:65], 0, v[130:131]
	s_mov_b32 m0, s44
	s_add_i32 s45, s44, 0x2000
	global_load_lds_dwordx4 v[146:147], off
	v_lshl_add_u64 v[146:147], s[64:65], 0, v[134:135]
	s_mov_b32 m0, s45
	v_lshl_add_u64 v[194:195], s[38:39], 0, v[128:129]
	global_load_lds_dwordx4 v[146:147], off
	v_lshl_add_u64 v[146:147], v[194:195], 0, s[22:23]
	s_mov_b32 m0, s9
	v_lshl_add_u64 v[216:217], s[38:39], 0, v[132:133]
	global_load_lds_dwordx4 v[146:147], off
	v_lshl_add_u64 v[146:147], v[216:217], 0, s[22:23]
	s_mov_b32 m0, s10
	s_nop 0
	global_load_lds_dwordx4 v[146:147], off
	s_waitcnt vmcnt(8)
	s_waitcnt lgkmcnt(0)
	s_barrier
; #define PG8_STAGE(bufoff, gbase, voff) do { _Pragma("unroll") for (int _i = 0; _i < 2; ++_i) \
;         __builtin_amdgcn_global_load_lds((const unsigned*)((const char*)(gbase) + (voff)[_i]), (PG8_LAS unsigned*)(lds + (bufoff) + ldsw + _i * 8192), 16, 0, 0); } while (0)
; #define PG8_LDA(dst, b, h) do { _Pragma("unroll") for (int m = 0; m < 4; ++m) _Pragma("unroll") for (int k = 0; k < 2; ++k) dst[m][k] = *(const PG8_LAS bf16x8*)(lds + PG8_SA(b, h) + aoff + m * 2048 + k * 1024); } while (0)
; #define PG8_LDB(dst, b, h) do { _Pragma("unroll") for (int n = 0; n < 2; ++n) _Pragma("unroll") for (int k = 0; k < 2; ++k) dst[n][k] = *(const PG8_LAS bf16x8*)(lds + PG8_SB(b, h) + boff + n * 2048 + k * 1024); } while (0)
; #define PG8_MMA(ai, bj, At, Bt) do { __builtin_amdgcn_s_setprio(1); _Pragma("unroll") for (int m = 0; m < 4; ++m) _Pragma("unroll") for (int n = 0; n < 2; ++n) _Pragma("unroll") for (int k = 0; k < 2; ++k) \
;         acc[ai][bj][m][n] = __builtin_amdgcn_mfma_f32_16x16x32_bf16(Bt[n][k], At[m][k], acc[ai][bj][m][n], 0, 0, 0); __builtin_amdgcn_s_setprio(0); } while (0)
; #define PG8_WAIT_V(n) asm volatile("s_waitcnt vmcnt(" #n ")" ::: "memory")
; #define PG8_WAIT_L(n) asm volatile("s_waitcnt lgkmcnt(" #n ")" ::: "memory")
; #define PG8_BAR __builtin_amdgcn_s_barrier()
; #define PG8_SCHED __builtin_amdgcn_sched_barrier(0)
; template <class Epi, class Sched, bool ALIGN_EPI = false, bool SP2 = false>
; __device__ __forceinline__ void gemm_phase(PG8_LAS unsigned char* lds, const Gemm g, const Sched& S, const Epi& E) {
;     ...
;             PG8_WAIT_V(8); PG8_WAIT_L(0); PG8_BAR; PG8_MMA(1, 0, At, B0); PG8_MMA(1, 1, At, B1); PG8_BAR; PG8_SCHED;
;             PG8_LDB(B0, 1, 0); PG8_LDB(B1, 1, 1); PG8_SCHED; PG8_LDA(At, 1, 0); PG8_STAGE(PG8_SA(0, 1), a2 + hstepA, voffA);
;             PG8_WAIT_V(8); PG8_WAIT_L(0); PG8_BAR; PG8_MMA(0, 0, At, B0); PG8_MMA(0, 1, At, B1); PG8_BAR; PG8_SCHED;
	s_waitcnt lgkmcnt(0)
	v_mfma_f32_16x16x32_bf16 v[146:149], v[0:3], v[60:63], 0
	v_mfma_f32_16x16x32_bf16 v[154:157], v[0:3], v[104:107], 0
	v_mfma_f32_16x16x32_bf16 v[162:165], v[0:3], v[112:115], 0
	v_mfma_f32_16x16x32_bf16 v[0:3], v[0:3], v[120:123], 0
	v_mfma_f32_16x16x32_bf16 v[146:149], v[4:7], v[100:103], v[146:149]
	v_mfma_f32_16x16x32_bf16 v[154:157], v[4:7], v[108:111], v[154:157]
	v_mfma_f32_16x16x32_bf16 v[162:165], v[4:7], v[116:119], v[162:165]
	v_mfma_f32_16x16x32_bf16 v[0:3], v[4:7], v[124:127], v[0:3]
	v_mfma_f32_16x16x32_bf16 v[4:7], v[8:11], v[120:123], 0
	v_mfma_f32_16x16x32_bf16 v[150:153], v[8:11], v[60:63], 0
	v_mfma_f32_16x16x32_bf16 v[158:161], v[8:11], v[104:107], 0
	v_mfma_f32_16x16x32_bf16 v[166:169], v[8:11], v[112:115], 0
	v_mfma_f32_16x16x32_bf16 v[4:7], v[12:15], v[124:127], v[4:7]
	v_mfma_f32_16x16x32_bf16 v[150:153], v[12:15], v[100:103], v[150:153]
	v_mfma_f32_16x16x32_bf16 v[158:161], v[12:15], v[108:111], v[158:161]
	v_mfma_f32_16x16x32_bf16 v[166:169], v[12:15], v[116:119], v[166:169]
	v_mfma_f32_16x16x32_bf16 v[8:11], v[16:19], v[60:63], 0
	v_mfma_f32_16x16x32_bf16 v[12:15], v[24:27], v[60:63], 0
	v_mfma_f32_16x16x32_bf16 v[8:11], v[20:23], v[100:103], v[8:11]
	v_mfma_f32_16x16x32_bf16 v[12:15], v[28:31], v[100:103], v[12:15]
	v_mfma_f32_16x16x32_bf16 v[60:63], v[16:19], v[104:107], 0
	v_mfma_f32_16x16x32_bf16 v[100:103], v[24:27], v[104:107], 0
	v_mfma_f32_16x16x32_bf16 v[104:107], v[16:19], v[112:115], 0
	v_mfma_f32_16x16x32_bf16 v[16:19], v[16:19], v[120:123], 0
	v_mfma_f32_16x16x32_bf16 v[60:63], v[20:23], v[108:111], v[60:63]
	v_mfma_f32_16x16x32_bf16 v[100:103], v[28:31], v[108:111], v[100:103]
	v_mfma_f32_16x16x32_bf16 v[104:107], v[20:23], v[116:119], v[104:107]
	v_mfma_f32_16x16x32_bf16 v[108:111], v[24:27], v[112:115], 0
	v_mfma_f32_16x16x32_bf16 v[16:19], v[20:23], v[124:127], v[16:19]
	v_mfma_f32_16x16x32_bf16 v[20:23], v[24:27], v[120:123], 0
	v_mfma_f32_16x16x32_bf16 v[108:111], v[28:31], v[116:119], v[108:111]
	v_mfma_f32_16x16x32_bf16 v[20:23], v[28:31], v[124:127], v[20:23]
	s_barrier
	s_add_i32 s63, 0, 0x18000
	s_add_i32 s66, 0, 0x1c000
	v_add_u32_e32 v220, s63, v142
	v_add_u32_e32 v228, s66, v142
	ds_read_b128 v[24:27], v220
	ds_read_b128 v[28:31], v220 offset:1024
	ds_read_b128 v[112:115], v220 offset:2048
	ds_read_b128 v[116:119], v220 offset:3072
	ds_read_b128 v[120:123], v228
	ds_read_b128 v[124:127], v228 offset:1024
	ds_read_b128 v[170:173], v228 offset:2048
	ds_read_b128 v[174:177], v228 offset:3072
	s_add_u32 s64, s38, 0x10100
	s_addc_u32 s65, s39, 0
	s_mov_b32 m0, s11
	v_lshl_add_u64 v[218:219], s[64:65], 0, v[128:129]
	ds_read_b128 v[178:181], v145 offset:32768
	ds_read_b128 v[182:185], v145 offset:33792
	ds_read_b128 v[186:189], v145 offset:34816
	ds_read_b128 v[196:199], v145 offset:35840
	ds_read_b128 v[200:203], v145 offset:36864
	ds_read_b128 v[204:207], v145 offset:37888
	ds_read_b128 v[208:211], v145 offset:38912
	ds_read_b128 v[212:215], v145 offset:39936
	global_load_lds_dwordx4 v[218:219], off
	v_lshl_add_u64 v[218:219], s[64:65], 0, v[132:133]
	s_mov_b32 m0, s27
	s_nop 0
	global_load_lds_dwordx4 v[218:219], off
	s_waitcnt vmcnt(8)
	s_waitcnt lgkmcnt(0)
	s_barrier
	s_waitcnt lgkmcnt(0)
	v_mfma_f32_16x16x32_bf16 v[64:67], v[24:27], v[178:181], v[64:67]
	v_mfma_f32_16x16x32_bf16 v[68:71], v[112:115], v[178:181], v[68:71]
	v_mfma_f32_16x16x32_bf16 v[72:75], v[24:27], v[186:189], v[72:75]
	v_mfma_f32_16x16x32_bf16 v[76:79], v[112:115], v[186:189], v[76:79]
	v_mfma_f32_16x16x32_bf16 v[80:83], v[24:27], v[200:203], v[80:83]
	v_mfma_f32_16x16x32_bf16 v[84:87], v[112:115], v[200:203], v[84:87]
	v_mfma_f32_16x16x32_bf16 v[88:91], v[24:27], v[208:211], v[88:91]
	v_mfma_f32_16x16x32_bf16 v[92:95], v[112:115], v[208:211], v[92:95]
	v_mfma_f32_16x16x32_bf16 v[64:67], v[28:31], v[182:185], v[64:67]
	v_mfma_f32_16x16x32_bf16 v[68:71], v[116:119], v[182:185], v[68:71]
	v_mfma_f32_16x16x32_bf16 v[72:75], v[28:31], v[196:199], v[72:75]
	v_mfma_f32_16x16x32_bf16 v[76:79], v[116:119], v[196:199], v[76:79]
	v_mfma_f32_16x16x32_bf16 v[80:83], v[28:31], v[204:207], v[80:83]
	v_mfma_f32_16x16x32_bf16 v[84:87], v[116:119], v[204:207], v[84:87]
	v_mfma_f32_16x16x32_bf16 v[88:91], v[28:31], v[212:215], v[88:91]
	v_mfma_f32_16x16x32_bf16 v[92:95], v[116:119], v[212:215], v[92:95]
	v_mfma_f32_16x16x32_bf16 v[96:99], v[120:123], v[178:181], v[96:99]
	v_mfma_f32_16x16x32_bf16 v[32:35], v[170:173], v[178:181], v[32:35]
	v_mfma_f32_16x16x32_bf16 v[36:39], v[120:123], v[186:189], v[36:39]
	v_mfma_f32_16x16x32_bf16 v[40:43], v[170:173], v[186:189], v[40:43]
	v_mfma_f32_16x16x32_bf16 v[44:47], v[120:123], v[200:203], v[44:47]
	v_mfma_f32_16x16x32_bf16 v[48:51], v[170:173], v[200:203], v[48:51]
	v_mfma_f32_16x16x32_bf16 v[52:55], v[120:123], v[208:211], v[52:55]
	v_mfma_f32_16x16x32_bf16 v[56:59], v[170:173], v[208:211], v[56:59]
	v_mfma_f32_16x16x32_bf16 v[96:99], v[124:127], v[182:185], v[96:99]
	v_mfma_f32_16x16x32_bf16 v[32:35], v[174:177], v[182:185], v[32:35]
	v_mfma_f32_16x16x32_bf16 v[36:39], v[124:127], v[196:199], v[36:39]
	v_mfma_f32_16x16x32_bf16 v[40:43], v[174:177], v[196:199], v[40:43]
	v_mfma_f32_16x16x32_bf16 v[44:47], v[124:127], v[204:207], v[44:47]
	v_mfma_f32_16x16x32_bf16 v[48:51], v[174:177], v[204:207], v[48:51]
	v_mfma_f32_16x16x32_bf16 v[52:55], v[124:127], v[212:215], v[52:55]
	v_mfma_f32_16x16x32_bf16 v[56:59], v[174:177], v[212:215], v[56:59]
	s_barrier
; #define PG8_STAGE(bufoff, gbase, voff) do { _Pragma("unroll") for (int _i = 0; _i < 2; ++_i) \
;         __builtin_amdgcn_global_load_lds((const unsigned*)((const char*)(gbase) + (voff)[_i]), (PG8_LAS unsigned*)(lds + (bufoff) + ldsw + _i * 8192), 16, 0, 0); } while (0)
; #define PG8_LDA(dst, b, h) do { _Pragma("unroll") for (int m = 0; m < 4; ++m) _Pragma("unroll") for (int k = 0; k < 2; ++k) dst[m][k] = *(const PG8_LAS bf16x8*)(lds + PG8_SA(b, h) + aoff + m * 2048 + k * 1024); } while (0)
; #define PG8_LDB(dst, b, h) do { _Pragma("unroll") for (int n = 0; n < 2; ++n) _Pragma("unroll") for (int k = 0; k < 2; ++k) dst[n][k] = *(const PG8_LAS bf16x8*)(lds + PG8_SB(b, h) + boff + n * 2048 + k * 1024); } while (0)
; #define PG8_MMA(ai, bj, At, Bt) do { __builtin_amdgcn_s_setprio(1); _Pragma("unroll") for (int m = 0; m < 4; ++m) _Pragma("unroll") for (int n = 0; n < 2; ++n) _Pragma("unroll") for (int k = 0; k < 2; ++k) \
;         acc[ai][bj][m][n] = __builtin_amdgcn_mfma_f32_16x16x32_bf16(Bt[n][k], At[m][k], acc[ai][bj][m][n], 0, 0, 0); __builtin_amdgcn_s_setprio(0); } while (0)
; #define PG8_WAIT_V(n) asm volatile("s_waitcnt vmcnt(" #n ")" ::: "memory")
; template <class Epi, class Sched, bool ALIGN_EPI = false, bool SP2 = false>
; __device__ __forceinline__ void gemm_phase(PG8_LAS unsigned char* lds, const Gemm g, const Sched& S, const Epi& E) {
;     ...
;             PG8_LDB(B0, 0, 0); PG8_LDB(B1, 0, 1); PG8_SCHED; PG8_LDA(At, 0, 0); PG8_STAGE(PG8_SA(1, 1), a1 + hstepA, voffA);
;             PG8_WAIT_V(8); PG8_WAIT_L(0); PG8_BAR; PG8_MMA(0, 0, At, B0); PG8_MMA(0, 1, At, B1); PG8_BAR; PG8_SCHED;
;             PG8_LDA(At, 0, 1); PG8_STAGE(PG8_SB(0, 0), b2, voffB); PG8_STAGE(PG8_SB(0, 1), b2 + hstepB, voffB); PG8_STAGE(PG8_SA(0, 0), a2, voffA);
;             PG8_WAIT_V(8); PG8_WAIT_L(0); PG8_BAR; PG8_MMA(1, 0, At, B0); PG8_MMA(1, 1, At, B1); PG8_BAR; PG8_SCHED;
;             PG8_LDB(B0, 1, 0); PG8_LDB(B1, 1, 1); PG8_SCHED; PG8_LDA(At, 1, 0); PG8_STAGE(PG8_SA(0, 1), a2 + hstepA, voffA);
;             PG8_WAIT_V(8); PG8_WAIT_L(0); PG8_BAR; PG8_MMA(0, 0, At, B0); PG8_MMA(0, 1, At, B1); PG8_BAR; PG8_SCHED;
;             PG8_LDA(At, 1, 1); PG8_STAGE(PG8_SB(1, 0), b3, voffB); PG8_STAGE(PG8_SB(1, 1), b3 + hstepB, voffB); PG8_STAGE(PG8_SA(1, 0), a3, voffA);
;             PG8_WAIT_V(8); PG8_WAIT_L(0); PG8_BAR; PG8_MMA(1, 0, At, B0); PG8_MMA(1, 1, At, B1); PG8_BAR; PG8_SCHED;
	s_add_i32 s63, s63, s8
	s_add_i32 s49, s63, 0x2000
	v_lshl_add_u64 v[190:191], v[190:191], 0, s[24:25]
	s_mov_b32 m0, s63
	s_add_u32 s64, s40, 0x10180
	ds_read_b128 v[178:181], v145 offset:49152
	ds_read_b128 v[182:185], v145 offset:50176
	ds_read_b128 v[186:189], v145 offset:51200
	ds_read_b128 v[196:199], v145 offset:52224
	ds_read_b128 v[200:203], v145 offset:53248
	ds_read_b128 v[204:207], v145 offset:54272
	ds_read_b128 v[208:211], v145 offset:55296
	ds_read_b128 v[212:215], v145 offset:56320
	global_load_lds_dwordx4 v[190:191], off
	v_lshl_add_u64 v[190:191], v[192:193], 0, s[24:25]
	s_mov_b32 m0, s49
	s_addc_u32 s65, s41, 0
	s_add_i32 s40, s66, s8
	global_load_lds_dwordx4 v[190:191], off
	v_lshl_add_u64 v[190:191], s[64:65], 0, v[130:131]
	s_mov_b32 m0, s40
	s_add_i32 s41, s40, 0x2000
	global_load_lds_dwordx4 v[190:191], off
	v_lshl_add_u64 v[190:191], s[64:65], 0, v[134:135]
	s_mov_b32 m0, s41
	s_nop 0
	global_load_lds_dwordx4 v[190:191], off
	v_lshl_add_u64 v[190:191], v[194:195], 0, s[24:25]
	s_mov_b32 m0, s43
	s_nop 0
	global_load_lds_dwordx4 v[190:191], off
	v_lshl_add_u64 v[190:191], v[216:217], 0, s[24:25]
	s_mov_b32 m0, s56
	s_nop 0
	global_load_lds_dwordx4 v[190:191], off
	s_waitcnt vmcnt(8)
	s_waitcnt lgkmcnt(0)
	s_barrier
	s_waitcnt lgkmcnt(0)
	v_mfma_f32_16x16x32_bf16 v[0:3], v[24:27], v[208:211], v[0:3]
	v_mfma_f32_16x16x32_bf16 v[4:7], v[112:115], v[208:211], v[4:7]
	v_mfma_f32_16x16x32_bf16 v[146:149], v[24:27], v[178:181], v[146:149]
	v_mfma_f32_16x16x32_bf16 v[150:153], v[112:115], v[178:181], v[150:153]
	v_mfma_f32_16x16x32_bf16 v[154:157], v[24:27], v[186:189], v[154:157]
	v_mfma_f32_16x16x32_bf16 v[158:161], v[112:115], v[186:189], v[158:161]
	v_mfma_f32_16x16x32_bf16 v[162:165], v[24:27], v[200:203], v[162:165]
	v_mfma_f32_16x16x32_bf16 v[166:169], v[112:115], v[200:203], v[166:169]
	v_mfma_f32_16x16x32_bf16 v[0:3], v[28:31], v[212:215], v[0:3]
	v_mfma_f32_16x16x32_bf16 v[4:7], v[116:119], v[212:215], v[4:7]
	v_mfma_f32_16x16x32_bf16 v[146:149], v[28:31], v[182:185], v[146:149]
	v_mfma_f32_16x16x32_bf16 v[150:153], v[116:119], v[182:185], v[150:153]
	v_mfma_f32_16x16x32_bf16 v[154:157], v[28:31], v[196:199], v[154:157]
	v_mfma_f32_16x16x32_bf16 v[158:161], v[116:119], v[196:199], v[158:161]
	v_mfma_f32_16x16x32_bf16 v[162:165], v[28:31], v[204:207], v[162:165]
	v_mfma_f32_16x16x32_bf16 v[166:169], v[116:119], v[204:207], v[166:169]
	v_mfma_f32_16x16x32_bf16 v[8:11], v[120:123], v[178:181], v[8:11]
	v_mfma_f32_16x16x32_bf16 v[12:15], v[170:173], v[178:181], v[12:15]
	v_mfma_f32_16x16x32_bf16 v[24:27], v[120:123], v[186:189], v[60:63]
	v_mfma_f32_16x16x32_bf16 v[28:31], v[170:173], v[186:189], v[100:103]
	v_mfma_f32_16x16x32_bf16 v[60:63], v[120:123], v[200:203], v[104:107]
	v_mfma_f32_16x16x32_bf16 v[100:103], v[170:173], v[200:203], v[108:111]
	v_mfma_f32_16x16x32_bf16 v[16:19], v[120:123], v[208:211], v[16:19]
	v_mfma_f32_16x16x32_bf16 v[20:23], v[170:173], v[208:211], v[20:23]
	v_mfma_f32_16x16x32_bf16 v[8:11], v[124:127], v[182:185], v[8:11]
	v_mfma_f32_16x16x32_bf16 v[12:15], v[174:177], v[182:185], v[12:15]
	v_mfma_f32_16x16x32_bf16 v[24:27], v[124:127], v[196:199], v[24:27]
	v_mfma_f32_16x16x32_bf16 v[28:31], v[174:177], v[196:199], v[28:31]
	v_mfma_f32_16x16x32_bf16 v[60:63], v[124:127], v[204:207], v[60:63]
	v_mfma_f32_16x16x32_bf16 v[100:103], v[174:177], v[204:207], v[100:103]
	v_mfma_f32_16x16x32_bf16 v[16:19], v[124:127], v[212:215], v[16:19]
	v_mfma_f32_16x16x32_bf16 v[20:23], v[174:177], v[212:215], v[20:23]
	s_barrier
	ds_read_b128 v[104:107], v143
	ds_read_b128 v[108:111], v143 offset:1024
	ds_read_b128 v[112:115], v143 offset:2048
	ds_read_b128 v[116:119], v143 offset:3072
	ds_read_b128 v[120:123], v144
	ds_read_b128 v[124:127], v144 offset:1024
	ds_read_b128 v[170:173], v144 offset:2048
	ds_read_b128 v[174:177], v144 offset:3072
	s_add_u32 s38, s38, 0x10180
	s_addc_u32 s39, s39, 0
	s_mov_b32 m0, s62
	v_lshl_add_u64 v[190:191], s[38:39], 0, v[128:129]
	ds_read_b128 v[178:181], v145
	ds_read_b128 v[182:185], v145 offset:1024
	ds_read_b128 v[186:189], v145 offset:2048
	ds_read_b128 v[196:199], v145 offset:3072
	ds_read_b128 v[200:203], v145 offset:4096
	ds_read_b128 v[204:207], v145 offset:5120
	ds_read_b128 v[208:211], v145 offset:6144
	ds_read_b128 v[212:215], v145 offset:7168
	global_load_lds_dwordx4 v[190:191], off
	v_lshl_add_u64 v[190:191], s[38:39], 0, v[132:133]
	s_mov_b32 m0, s29
	s_nop 0
	global_load_lds_dwordx4 v[190:191], off
	s_waitcnt vmcnt(8)
	s_waitcnt lgkmcnt(0)
	s_barrier
; #define PG8_STAGE(bufoff, gbase, voff) do { _Pragma("unroll") for (int _i = 0; _i < 2; ++_i) \
;         __builtin_amdgcn_global_load_lds((const unsigned*)((const char*)(gbase) + (voff)[_i]), (PG8_LAS unsigned*)(lds + (bufoff) + ldsw + _i * 8192), 16, 0, 0); } while (0)
; #define PG8_LDA(dst, b, h) do { _Pragma("unroll") for (int m = 0; m < 4; ++m) _Pragma("unroll") for (int k = 0; k < 2; ++k) dst[m][k] = *(const PG8_LAS bf16x8*)(lds + PG8_SA(b, h) + aoff + m * 2048 + k * 1024); } while (0)
; #define PG8_MMA(ai, bj, At, Bt) do { __builtin_amdgcn_s_setprio(1); _Pragma("unroll") for (int m = 0; m < 4; ++m) _Pragma("unroll") for (int n = 0; n < 2; ++n) _Pragma("unroll") for (int k = 0; k < 2; ++k) \
;         acc[ai][bj][m][n] = __builtin_amdgcn_mfma_f32_16x16x32_bf16(Bt[n][k], At[m][k], acc[ai][bj][m][n], 0, 0, 0); __builtin_amdgcn_s_setprio(0); } while (0)
; #define PG8_WAIT_V(n) asm volatile("s_waitcnt vmcnt(" #n ")" ::: "memory")
; #define PG8_WAIT_L(n) asm volatile("s_waitcnt lgkmcnt(" #n ")" ::: "memory")
; #define PG8_BAR __builtin_amdgcn_s_barrier()
; #define PG8_SCHED __builtin_amdgcn_sched_barrier(0)
; template <class Epi, class Sched, bool ALIGN_EPI = false, bool SP2 = false>
; __device__ __forceinline__ void gemm_phase(PG8_LAS unsigned char* lds, const Gemm g, const Sched& S, const Epi& E) {
;     ...
;             PG8_WAIT_V(8); PG8_WAIT_L(0); PG8_BAR; PG8_MMA(0, 0, At, B0); PG8_MMA(0, 1, At, B1); PG8_BAR; PG8_SCHED;
;             PG8_LDA(At, 0, 1); PG8_STAGE(PG8_SB(0, 0), b2, voffB); PG8_STAGE(PG8_SB(0, 1), b2 + hstepB, voffB); PG8_STAGE(PG8_SA(0, 0), a2, voffA);
;             PG8_WAIT_V(8); PG8_WAIT_L(0); PG8_BAR; PG8_MMA(1, 0, At, B0); PG8_MMA(1, 1, At, B1); PG8_BAR; PG8_SCHED;
	s_waitcnt lgkmcnt(0)
	v_mfma_f32_16x16x32_bf16 v[64:67], v[104:107], v[178:181], v[64:67]
	v_mfma_f32_16x16x32_bf16 v[68:71], v[112:115], v[178:181], v[68:71]
	v_mfma_f32_16x16x32_bf16 v[72:75], v[104:107], v[186:189], v[72:75]
	v_mfma_f32_16x16x32_bf16 v[76:79], v[112:115], v[186:189], v[76:79]
	v_mfma_f32_16x16x32_bf16 v[80:83], v[104:107], v[200:203], v[80:83]
	v_mfma_f32_16x16x32_bf16 v[84:87], v[112:115], v[200:203], v[84:87]
	v_mfma_f32_16x16x32_bf16 v[88:91], v[104:107], v[208:211], v[88:91]
	v_mfma_f32_16x16x32_bf16 v[92:95], v[112:115], v[208:211], v[92:95]
	v_mfma_f32_16x16x32_bf16 v[64:67], v[108:111], v[182:185], v[64:67]
	v_mfma_f32_16x16x32_bf16 v[68:71], v[116:119], v[182:185], v[68:71]
	v_mfma_f32_16x16x32_bf16 v[72:75], v[108:111], v[196:199], v[72:75]
	v_mfma_f32_16x16x32_bf16 v[76:79], v[116:119], v[196:199], v[76:79]
	v_mfma_f32_16x16x32_bf16 v[80:83], v[108:111], v[204:207], v[80:83]
	v_mfma_f32_16x16x32_bf16 v[84:87], v[116:119], v[204:207], v[84:87]
	v_mfma_f32_16x16x32_bf16 v[88:91], v[108:111], v[212:215], v[88:91]
	v_mfma_f32_16x16x32_bf16 v[92:95], v[116:119], v[212:215], v[92:95]
	v_mfma_f32_16x16x32_bf16 v[32:35], v[170:173], v[178:181], v[32:35]
	v_mfma_f32_16x16x32_bf16 v[96:99], v[120:123], v[178:181], v[96:99]
	v_mfma_f32_16x16x32_bf16 v[178:181], v[174:177], v[182:185], v[32:35]
	v_mfma_f32_16x16x32_bf16 v[32:35], v[120:123], v[186:189], v[36:39]
	v_mfma_f32_16x16x32_bf16 v[216:219], v[124:127], v[182:185], v[96:99]
	v_mfma_f32_16x16x32_bf16 v[182:185], v[124:127], v[196:199], v[32:35]
	v_mfma_f32_16x16x32_bf16 v[32:35], v[170:173], v[186:189], v[40:43]
	v_mfma_f32_16x16x32_bf16 v[40:43], v[174:177], v[196:199], v[32:35]
	v_mfma_f32_16x16x32_bf16 v[32:35], v[120:123], v[200:203], v[44:47]
	v_mfma_f32_16x16x32_bf16 v[44:47], v[124:127], v[204:207], v[32:35]
	v_mfma_f32_16x16x32_bf16 v[32:35], v[170:173], v[200:203], v[48:51]
	v_mfma_f32_16x16x32_bf16 v[48:51], v[174:177], v[204:207], v[32:35]
	v_mfma_f32_16x16x32_bf16 v[32:35], v[120:123], v[208:211], v[52:55]
	v_mfma_f32_16x16x32_bf16 v[52:55], v[124:127], v[212:215], v[32:35]
	v_mfma_f32_16x16x32_bf16 v[32:35], v[170:173], v[208:211], v[56:59]
	v_mfma_f32_16x16x32_bf16 v[56:59], v[174:177], v[212:215], v[32:35]
	s_barrier
	s_mov_b32 m0, s48
	v_lshl_add_u64 v[190:191], s[50:51], 0, v[130:131]
	s_add_u32 s38, s50, 0x10000
	s_nop 1
	ds_read_b128 v[32:35], v145 offset:16384
	ds_read_b128 v[36:39], v145 offset:17408
	ds_read_b128 v[96:99], v145 offset:18432
	ds_read_b128 v[186:189], v145 offset:19456
	ds_read_b128 v[196:199], v145 offset:20480
	ds_read_b128 v[200:203], v145 offset:21504
	ds_read_b128 v[204:207], v145 offset:22528
	ds_read_b128 v[208:211], v145 offset:23552
	global_load_lds_dwordx4 v[190:191], off
	v_lshl_add_u64 v[192:193], s[50:51], 0, v[134:135]
	s_mov_b32 m0, s31
	s_addc_u32 s39, s51, 0
	global_load_lds_dwordx4 v[192:193], off
	v_lshl_add_u64 v[194:195], s[38:39], 0, v[130:131]
	s_mov_b32 m0, s44
	v_lshl_add_u64 v[252:253], s[52:53], 0, v[132:133]
	global_load_lds_dwordx4 v[194:195], off
	v_lshl_add_u64 v[194:195], s[38:39], 0, v[134:135]
	s_mov_b32 m0, s45
	s_nop 0
	global_load_lds_dwordx4 v[194:195], off
	v_lshl_add_u64 v[194:195], s[52:53], 0, v[128:129]
	s_mov_b32 m0, s9
	s_nop 0
	global_load_lds_dwordx4 v[194:195], off
	s_mov_b32 m0, s10
	s_nop 0
	global_load_lds_dwordx4 v[252:253], off
	s_waitcnt vmcnt(8)
	s_waitcnt lgkmcnt(0)
	s_barrier
	s_waitcnt lgkmcnt(0)
	v_mfma_f32_16x16x32_bf16 v[0:3], v[104:107], v[204:207], v[0:3]
	v_mfma_f32_16x16x32_bf16 v[4:7], v[112:115], v[204:207], v[4:7]
	v_mfma_f32_16x16x32_bf16 v[146:149], v[104:107], v[32:35], v[146:149]
	v_mfma_f32_16x16x32_bf16 v[150:153], v[112:115], v[32:35], v[150:153]
	v_mfma_f32_16x16x32_bf16 v[154:157], v[104:107], v[96:99], v[154:157]
	v_mfma_f32_16x16x32_bf16 v[158:161], v[112:115], v[96:99], v[158:161]
	v_mfma_f32_16x16x32_bf16 v[162:165], v[104:107], v[196:199], v[162:165]
	v_mfma_f32_16x16x32_bf16 v[166:169], v[112:115], v[196:199], v[166:169]
	v_mfma_f32_16x16x32_bf16 v[0:3], v[108:111], v[208:211], v[0:3]
	v_mfma_f32_16x16x32_bf16 v[4:7], v[116:119], v[208:211], v[4:7]
	v_mfma_f32_16x16x32_bf16 v[146:149], v[108:111], v[36:39], v[146:149]
	v_mfma_f32_16x16x32_bf16 v[150:153], v[116:119], v[36:39], v[150:153]
	v_mfma_f32_16x16x32_bf16 v[154:157], v[108:111], v[186:189], v[154:157]
	v_mfma_f32_16x16x32_bf16 v[158:161], v[116:119], v[186:189], v[158:161]
	v_mfma_f32_16x16x32_bf16 v[162:165], v[108:111], v[200:203], v[162:165]
	v_mfma_f32_16x16x32_bf16 v[166:169], v[116:119], v[200:203], v[166:169]
	v_mfma_f32_16x16x32_bf16 v[8:11], v[120:123], v[32:35], v[8:11]
	v_mfma_f32_16x16x32_bf16 v[12:15], v[170:173], v[32:35], v[12:15]
	v_mfma_f32_16x16x32_bf16 v[24:27], v[120:123], v[96:99], v[24:27]
	v_mfma_f32_16x16x32_bf16 v[28:31], v[170:173], v[96:99], v[28:31]
	v_mfma_f32_16x16x32_bf16 v[32:35], v[120:123], v[196:199], v[60:63]
	v_mfma_f32_16x16x32_bf16 v[24:27], v[124:127], v[186:189], v[24:27]
	v_mfma_f32_16x16x32_bf16 v[28:31], v[174:177], v[186:189], v[28:31]
	v_mfma_f32_16x16x32_bf16 v[186:189], v[124:127], v[200:203], v[32:35]
	v_mfma_f32_16x16x32_bf16 v[32:35], v[170:173], v[196:199], v[100:103]
	v_mfma_f32_16x16x32_bf16 v[16:19], v[120:123], v[204:207], v[16:19]
	v_mfma_f32_16x16x32_bf16 v[8:11], v[124:127], v[36:39], v[8:11]
	v_mfma_f32_16x16x32_bf16 v[12:15], v[174:177], v[36:39], v[12:15]
	v_mfma_f32_16x16x32_bf16 v[196:199], v[174:177], v[200:203], v[32:35]
	v_mfma_f32_16x16x32_bf16 v[200:203], v[124:127], v[208:211], v[16:19]
	v_mfma_f32_16x16x32_bf16 v[16:19], v[170:173], v[204:207], v[20:23]
	v_mfma_f32_16x16x32_bf16 v[170:173], v[174:177], v[208:211], v[16:19]
	s_barrier
; #define PG8_STAGE(bufoff, gbase, voff) do { _Pragma("unroll") for (int _i = 0; _i < 2; ++_i) \
;         __builtin_amdgcn_global_load_lds((const unsigned*)((const char*)(gbase) + (voff)[_i]), (PG8_LAS unsigned*)(lds + (bufoff) + ldsw + _i * 8192), 16, 0, 0); } while (0)
; #define PG8_LDA(dst, b, h) do { _Pragma("unroll") for (int m = 0; m < 4; ++m) _Pragma("unroll") for (int k = 0; k < 2; ++k) dst[m][k] = *(const PG8_LAS bf16x8*)(lds + PG8_SA(b, h) + aoff + m * 2048 + k * 1024); } while (0)
; #define PG8_LDB(dst, b, h) do { _Pragma("unroll") for (int n = 0; n < 2; ++n) _Pragma("unroll") for (int k = 0; k < 2; ++k) dst[n][k] = *(const PG8_LAS bf16x8*)(lds + PG8_SB(b, h) + boff + n * 2048 + k * 1024); } while (0)
; #define PG8_MMA(ai, bj, At, Bt) do { __builtin_amdgcn_s_setprio(1); _Pragma("unroll") for (int m = 0; m < 4; ++m) _Pragma("unroll") for (int n = 0; n < 2; ++n) _Pragma("unroll") for (int k = 0; k < 2; ++k) \
;         acc[ai][bj][m][n] = __builtin_amdgcn_mfma_f32_16x16x32_bf16(Bt[n][k], At[m][k], acc[ai][bj][m][n], 0, 0, 0); __builtin_amdgcn_s_setprio(0); } while (0)
; #define PG8_WAIT_V(n) asm volatile("s_waitcnt vmcnt(" #n ")" ::: "memory")
; #define PG8_WAIT_L(n) asm volatile("s_waitcnt lgkmcnt(" #n ")" ::: "memory")
; #define PG8_BAR __builtin_amdgcn_s_barrier()
; #define PG8_SCHED __builtin_amdgcn_sched_barrier(0)
; template <class Epi, class Sched, bool ALIGN_EPI = false, bool SP2 = false>
; __device__ __forceinline__ void gemm_phase(PG8_LAS unsigned char* lds, const Gemm g, const Sched& S, const Epi& E) {
;     ...
;             PG8_LDB(B0, 1, 0); PG8_LDB(B1, 1, 1); PG8_SCHED; PG8_LDA(At, 1, 0); PG8_STAGE(PG8_SA(0, 1), a2 + hstepA, voffA);
;             PG8_WAIT_V(8); PG8_WAIT_L(0); PG8_BAR; PG8_MMA(0, 0, At, B0); PG8_MMA(0, 1, At, B1); PG8_BAR; PG8_SCHED;
;             PG8_LDA(At, 1, 1); PG8_STAGE(PG8_SB(1, 0), b3, voffB); PG8_STAGE(PG8_SB(1, 1), b3 + hstepB, voffB); PG8_STAGE(PG8_SA(1, 0), a3, voffA);
;             PG8_WAIT_V(8); PG8_WAIT_L(0); PG8_BAR; PG8_MMA(1, 0, At, B0); PG8_MMA(1, 1, At, B1); PG8_BAR; PG8_SCHED;
	ds_read_b128 v[60:63], v220
	ds_read_b128 v[174:177], v220 offset:1024
	ds_read_b128 v[204:207], v220 offset:2048
	ds_read_b128 v[208:211], v220 offset:3072
	ds_read_b128 v[212:215], v228
	ds_read_b128 v[220:223], v228 offset:1024
	ds_read_b128 v[224:227], v228 offset:2048
	ds_read_b128 v[228:231], v228 offset:3072
	s_add_u32 s38, s52, 0x10000
	s_addc_u32 s39, s53, 0
	s_mov_b32 m0, s11
	v_lshl_add_u64 v[32:33], s[38:39], 0, v[128:129]
	ds_read_b128 v[16:19], v145 offset:32768
	ds_read_b128 v[20:23], v145 offset:33792
	ds_read_b128 v[108:111], v145 offset:34816
	ds_read_b128 v[232:235], v145 offset:35840
	ds_read_b128 v[236:239], v145 offset:36864
	ds_read_b128 v[240:243], v145 offset:37888
	ds_read_b128 v[244:247], v145 offset:38912
	ds_read_b128 v[248:251], v145 offset:39936
	global_load_lds_dwordx4 v[32:33], off
	v_lshl_add_u64 v[32:33], s[38:39], 0, v[132:133]
	s_mov_b32 m0, s27
	s_nop 0
	global_load_lds_dwordx4 v[32:33], off
	s_waitcnt vmcnt(8)
	s_waitcnt lgkmcnt(0)
	s_barrier
	s_waitcnt lgkmcnt(0)
	v_mfma_f32_16x16x32_bf16 v[32:35], v[60:63], v[16:19], v[64:67]
	v_mfma_f32_16x16x32_bf16 v[112:115], v[174:177], v[20:23], v[32:35]
	v_mfma_f32_16x16x32_bf16 v[32:35], v[204:207], v[16:19], v[68:71]
	v_mfma_f32_16x16x32_bf16 v[116:119], v[208:211], v[20:23], v[32:35]
	v_mfma_f32_16x16x32_bf16 v[32:35], v[60:63], v[108:111], v[72:75]
	v_mfma_f32_16x16x32_bf16 v[96:99], v[174:177], v[232:235], v[32:35]
	v_mfma_f32_16x16x32_bf16 v[32:35], v[204:207], v[108:111], v[76:79]
	v_mfma_f32_16x16x32_bf16 v[100:103], v[208:211], v[232:235], v[32:35]
	v_mfma_f32_16x16x32_bf16 v[32:35], v[60:63], v[236:239], v[80:83]
	v_mfma_f32_16x16x32_bf16 v[64:67], v[174:177], v[240:243], v[32:35]
	v_mfma_f32_16x16x32_bf16 v[32:35], v[204:207], v[236:239], v[84:87]
	v_mfma_f32_16x16x32_bf16 v[68:71], v[208:211], v[240:243], v[32:35]
	v_mfma_f32_16x16x32_bf16 v[32:35], v[60:63], v[244:247], v[88:91]
	v_mfma_f32_16x16x32_bf16 v[36:39], v[204:207], v[244:247], v[92:95]
	v_mfma_f32_16x16x32_bf16 v[32:35], v[174:177], v[248:251], v[32:35]
	v_mfma_f32_16x16x32_bf16 v[36:39], v[208:211], v[248:251], v[36:39]
	v_mfma_f32_16x16x32_bf16 v[72:75], v[212:215], v[16:19], v[216:219]
	v_mfma_f32_16x16x32_bf16 v[16:19], v[224:227], v[16:19], v[178:181]
	v_mfma_f32_16x16x32_bf16 v[124:127], v[228:231], v[20:23], v[16:19]
	v_mfma_f32_16x16x32_bf16 v[16:19], v[212:215], v[108:111], v[182:185]
	v_mfma_f32_16x16x32_bf16 v[104:107], v[220:223], v[232:235], v[16:19]
	v_mfma_f32_16x16x32_bf16 v[16:19], v[224:227], v[108:111], v[40:43]
	v_mfma_f32_16x16x32_bf16 v[108:111], v[228:231], v[232:235], v[16:19]
	v_mfma_f32_16x16x32_bf16 v[16:19], v[212:215], v[236:239], v[44:47]
	v_mfma_f32_16x16x32_bf16 v[120:123], v[220:223], v[20:23], v[72:75]
	v_mfma_f32_16x16x32_bf16 v[72:75], v[220:223], v[240:243], v[16:19]
	v_mfma_f32_16x16x32_bf16 v[16:19], v[224:227], v[236:239], v[48:51]
	v_mfma_f32_16x16x32_bf16 v[76:79], v[228:231], v[240:243], v[16:19]
	v_mfma_f32_16x16x32_bf16 v[16:19], v[212:215], v[244:247], v[52:55]
	v_mfma_f32_16x16x32_bf16 v[40:43], v[220:223], v[248:251], v[16:19]
	v_mfma_f32_16x16x32_bf16 v[16:19], v[224:227], v[244:247], v[56:59]
	v_mfma_f32_16x16x32_bf16 v[44:47], v[228:231], v[248:251], v[16:19]
	s_barrier
	s_mov_b32 m0, s63
	s_nop 3
	v_lshl_add_u64 v[16:17], v[190:191], 0, s[16:17]
	s_add_u32 s38, s50, 0x10080
	ds_read_b128 v[56:59], v145 offset:49152
	ds_read_b128 v[92:95], v145 offset:50176
	ds_read_b128 v[178:181], v145 offset:51200
	ds_read_b128 v[182:185], v145 offset:52224
	ds_read_b128 v[216:219], v145 offset:53248
	ds_read_b128 v[232:235], v145 offset:54272
	ds_read_b128 v[236:239], v145 offset:55296
	ds_read_b128 v[240:243], v145 offset:56320
	global_load_lds_dwordx4 v[16:17], off
	v_lshl_add_u64 v[16:17], v[192:193], 0, s[16:17]
	s_mov_b32 m0, s49
	s_addc_u32 s39, s51, 0
	global_load_lds_dwordx4 v[16:17], off
	v_lshl_add_u64 v[16:17], s[38:39], 0, v[130:131]
	s_mov_b32 m0, s40
	s_nop 0
	global_load_lds_dwordx4 v[16:17], off
	v_lshl_add_u64 v[16:17], s[38:39], 0, v[134:135]
	s_mov_b32 m0, s41
	s_nop 0
	global_load_lds_dwordx4 v[16:17], off
	v_lshl_add_u64 v[16:17], v[194:195], 0, s[16:17]
	s_mov_b32 m0, s43
	s_nop 0
	global_load_lds_dwordx4 v[16:17], off
	v_lshl_add_u64 v[16:17], v[252:253], 0, s[16:17]
	s_mov_b32 m0, s56
	s_nop 0
	global_load_lds_dwordx4 v[16:17], off
	s_waitcnt vmcnt(8)
	s_waitcnt lgkmcnt(0)
	s_barrier
	s_waitcnt lgkmcnt(0)
	v_mfma_f32_16x16x32_bf16 v[16:19], v[60:63], v[56:59], v[146:149]
	v_mfma_f32_16x16x32_bf16 v[80:83], v[174:177], v[92:95], v[16:19]
	v_mfma_f32_16x16x32_bf16 v[16:19], v[204:207], v[56:59], v[150:153]
	v_mfma_f32_16x16x32_bf16 v[84:87], v[208:211], v[92:95], v[16:19]
	v_mfma_f32_16x16x32_bf16 v[16:19], v[60:63], v[178:181], v[154:157]
	v_mfma_f32_16x16x32_bf16 v[48:51], v[174:177], v[182:185], v[16:19]
	v_mfma_f32_16x16x32_bf16 v[16:19], v[204:207], v[178:181], v[158:161]
	v_mfma_f32_16x16x32_bf16 v[52:55], v[208:211], v[182:185], v[16:19]
	v_mfma_f32_16x16x32_bf16 v[16:19], v[60:63], v[216:219], v[162:165]
	v_mfma_f32_16x16x32_bf16 v[20:23], v[204:207], v[216:219], v[166:169]
	v_mfma_f32_16x16x32_bf16 v[0:3], v[60:63], v[236:239], v[0:3]
	v_mfma_f32_16x16x32_bf16 v[4:7], v[204:207], v[236:239], v[4:7]
	v_mfma_f32_16x16x32_bf16 v[16:19], v[174:177], v[232:235], v[16:19]
	v_mfma_f32_16x16x32_bf16 v[20:23], v[208:211], v[232:235], v[20:23]
	v_mfma_f32_16x16x32_bf16 v[0:3], v[174:177], v[240:243], v[0:3]
	v_mfma_f32_16x16x32_bf16 v[4:7], v[208:211], v[240:243], v[4:7]
	v_mfma_f32_16x16x32_bf16 v[8:11], v[212:215], v[56:59], v[8:11]
	v_mfma_f32_16x16x32_bf16 v[88:91], v[220:223], v[92:95], v[8:11]
	v_mfma_f32_16x16x32_bf16 v[8:11], v[224:227], v[56:59], v[12:15]
	v_mfma_f32_16x16x32_bf16 v[92:95], v[228:231], v[92:95], v[8:11]
	v_mfma_f32_16x16x32_bf16 v[8:11], v[212:215], v[178:181], v[24:27]
	v_mfma_f32_16x16x32_bf16 v[56:59], v[220:223], v[182:185], v[8:11]
	v_mfma_f32_16x16x32_bf16 v[8:11], v[224:227], v[178:181], v[28:31]
	v_mfma_f32_16x16x32_bf16 v[60:63], v[228:231], v[182:185], v[8:11]
	v_mfma_f32_16x16x32_bf16 v[8:11], v[212:215], v[216:219], v[186:189]
	v_mfma_f32_16x16x32_bf16 v[24:27], v[220:223], v[232:235], v[8:11]
	v_mfma_f32_16x16x32_bf16 v[8:11], v[224:227], v[216:219], v[196:199]
	v_mfma_f32_16x16x32_bf16 v[28:31], v[228:231], v[232:235], v[8:11]
	v_mfma_f32_16x16x32_bf16 v[8:11], v[212:215], v[236:239], v[200:203]
	v_mfma_f32_16x16x32_bf16 v[12:15], v[224:227], v[236:239], v[170:173]
	v_mfma_f32_16x16x32_bf16 v[8:11], v[220:223], v[240:243], v[8:11]
	v_mfma_f32_16x16x32_bf16 v[12:15], v[228:231], v[240:243], v[12:15]
	s_barrier
	s_andn2_b64 vcc, exec, s[18:19]
	s_cbranch_vccnz .LBB0_236
	s_barrier

; #define PG8_STAGE(bufoff, gbase, voff) do { _Pragma("unroll") for (int _i = 0; _i < 2; ++_i) \
;         __builtin_amdgcn_global_load_lds((const unsigned*)((const char*)(gbase) + (voff)[_i]), (PG8_LAS unsigned*)(lds + (bufoff) + ldsw + _i * 8192), 16, 0, 0); } while (0)
; #define PG8_LDA(dst, b, h) do { _Pragma("unroll") for (int m = 0; m < 4; ++m) _Pragma("unroll") for (int k = 0; k < 2; ++k) dst[m][k] = *(const PG8_LAS bf16x8*)(lds + PG8_SA(b, h) + aoff + m * 2048 + k * 1024); } while (0)
; #define PG8_LDB(dst, b, h) do { _Pragma("unroll") for (int n = 0; n < 2; ++n) _Pragma("unroll") for (int k = 0; k < 2; ++k) dst[n][k] = *(const PG8_LAS bf16x8*)(lds + PG8_SB(b, h) + boff + n * 2048 + k * 1024); } while (0)
; #define PG8_MMA(ai, bj, At, Bt) do { __builtin_amdgcn_s_setprio(1); _Pragma("unroll") for (int m = 0; m < 4; ++m) _Pragma("unroll") for (int n = 0; n < 2; ++n) _Pragma("unroll") for (int k = 0; k < 2; ++k) \
;         acc[ai][bj][m][n] = __builtin_amdgcn_mfma_f32_16x16x32_bf16(Bt[n][k], At[m][k], acc[ai][bj][m][n], 0, 0, 0); __builtin_amdgcn_s_setprio(0); } while (0)
; #define PG8_WAIT_V(n) asm volatile("s_waitcnt vmcnt(" #n ")" ::: "memory")
; #define PG8_WAIT_L(n) asm volatile("s_waitcnt lgkmcnt(" #n ")" ::: "memory")
; #define PG8_BAR __builtin_amdgcn_s_barrier()
; #define PG8_SCHED __builtin_amdgcn_sched_barrier(0)
; template <class Epi, class Sched, bool ALIGN_EPI = false, bool SP2 = false>
; __device__ __forceinline__ void gemm_phase(PG8_LAS unsigned char* lds, const Gemm g, const Sched& S, const Epi& E) {
;     ...
;             const bool last = (t == nt - 2);
;             const char* a1 = cA + (size_t)(t + 1) * kstep;
;             const char* a2 = last ? nA : cA + (size_t)(t + 2) * kstep; const char* b2 = last ? nB : cB + (size_t)(t + 2) * kstep;
;             const char* a3 = a2 + kstep; const char* b3 = b2 + kstep;
;             if (last && has_next) S.a_ready(nxt);
;             if constexpr (SP2) {
;             PG8_LDB(B0, 0, 0); PG8_LDB(B1, 0, 1); PG8_SCHED; PG8_LDA(At, 0, 0); PG8_STAGE(PG8_SA(1, 1), a1 + hstepA, voffA);
;             PG8_WAIT_V(8); PG8_WAIT_L(0); PG8_BAR; PG8_MMA(0, 0, At, B0); PG8_MMA(0, 1, At, B1); PG8_BAR; PG8_SCHED;
;             PG8_LDA(At, 0, 1); PG8_STAGE(PG8_SB(0, 0), b2, voffB); PG8_STAGE(PG8_SB(0, 1), b2 + hstepB, voffB); PG8_STAGE(PG8_SA(0, 0), a2, voffA);
.LBB0_303:
	ds_read_b128 v[150:153], v147
	ds_read_b128 v[154:157], v147 offset:1024
	ds_read_b128 v[158:161], v147 offset:2048
	ds_read_b128 v[162:165], v147 offset:3072
	ds_read_b128 v[166:169], v148
	ds_read_b128 v[170:173], v148 offset:1024
	ds_read_b128 v[174:177], v148 offset:2048
	ds_read_b128 v[178:181], v148 offset:3072
	s_add_u32 s28, s0, 0xfff80080
	s_addc_u32 s29, s1, -1
	s_cmp_eq_u32 s53, 2
	s_cselect_b32 s31, s23, s29
	s_cselect_b32 s30, s50, s28
	s_cselect_b32 s29, s25, s52
	s_cselect_b32 s28, s24, s51
	v_lshl_add_u64 v[190:191], s[0:1], 0, v[136:137]
	s_add_i32 m0, s8, 0xc000
	ds_read_b128 v[182:185], v149
	ds_read_b128 v[186:189], v149 offset:1024
	ds_read_b128 v[196:199], v149 offset:2048
	ds_read_b128 v[200:203], v149 offset:3072
	ds_read_b128 v[204:207], v149 offset:4096
	ds_read_b128 v[208:211], v149 offset:5120
	ds_read_b128 v[212:215], v149 offset:6144
	ds_read_b128 v[216:219], v149 offset:7168
	global_load_lds_dwordx4 v[190:191], off
	v_lshl_add_u64 v[190:191], s[0:1], 0, v[138:139]
	s_add_i32 m0, s8, 0xe000
	s_nop 0
	global_load_lds_dwordx4 v[190:191], off
	s_waitcnt vmcnt(8)
	s_waitcnt lgkmcnt(0)
	s_barrier
	s_waitcnt lgkmcnt(0)
	v_mfma_f32_16x16x32_bf16 v[124:127], v[150:153], v[182:185], v[124:127]
	v_mfma_f32_16x16x32_bf16 v[120:123], v[158:161], v[182:185], v[120:123]
	v_mfma_f32_16x16x32_bf16 v[116:119], v[150:153], v[196:199], v[116:119]
	v_mfma_f32_16x16x32_bf16 v[112:115], v[158:161], v[196:199], v[112:115]
	v_mfma_f32_16x16x32_bf16 v[100:103], v[150:153], v[204:207], v[100:103]
	v_mfma_f32_16x16x32_bf16 v[96:99], v[158:161], v[204:207], v[96:99]
	v_mfma_f32_16x16x32_bf16 v[84:87], v[150:153], v[212:215], v[84:87]
	v_mfma_f32_16x16x32_bf16 v[80:83], v[158:161], v[212:215], v[80:83]
	v_mfma_f32_16x16x32_bf16 v[124:127], v[154:157], v[186:189], v[124:127]
	v_mfma_f32_16x16x32_bf16 v[120:123], v[162:165], v[186:189], v[120:123]
	v_mfma_f32_16x16x32_bf16 v[116:119], v[154:157], v[200:203], v[116:119]
	v_mfma_f32_16x16x32_bf16 v[112:115], v[162:165], v[200:203], v[112:115]
	v_mfma_f32_16x16x32_bf16 v[100:103], v[154:157], v[208:211], v[100:103]
	v_mfma_f32_16x16x32_bf16 v[96:99], v[162:165], v[208:211], v[96:99]
	v_mfma_f32_16x16x32_bf16 v[84:87], v[154:157], v[216:219], v[84:87]
	v_mfma_f32_16x16x32_bf16 v[80:83], v[162:165], v[216:219], v[80:83]
	v_mfma_f32_16x16x32_bf16 v[108:111], v[166:169], v[182:185], v[108:111]
	v_mfma_f32_16x16x32_bf16 v[104:107], v[174:177], v[182:185], v[104:107]
	v_mfma_f32_16x16x32_bf16 v[92:95], v[166:169], v[196:199], v[92:95]
	v_mfma_f32_16x16x32_bf16 v[88:91], v[174:177], v[196:199], v[88:91]
	v_mfma_f32_16x16x32_bf16 v[76:79], v[166:169], v[204:207], v[76:79]
	v_mfma_f32_16x16x32_bf16 v[72:75], v[174:177], v[204:207], v[72:75]
	v_mfma_f32_16x16x32_bf16 v[68:71], v[166:169], v[212:215], v[68:71]
	v_mfma_f32_16x16x32_bf16 v[64:67], v[174:177], v[212:215], v[64:67]
	v_mfma_f32_16x16x32_bf16 v[108:111], v[170:173], v[186:189], v[108:111]
	v_mfma_f32_16x16x32_bf16 v[104:107], v[178:181], v[186:189], v[104:107]
	v_mfma_f32_16x16x32_bf16 v[92:95], v[170:173], v[200:203], v[92:95]
	v_mfma_f32_16x16x32_bf16 v[88:91], v[178:181], v[200:203], v[88:91]
	v_mfma_f32_16x16x32_bf16 v[76:79], v[170:173], v[208:211], v[76:79]
	v_mfma_f32_16x16x32_bf16 v[72:75], v[178:181], v[208:211], v[72:75]
	v_mfma_f32_16x16x32_bf16 v[68:71], v[170:173], v[216:219], v[68:71]
	v_mfma_f32_16x16x32_bf16 v[64:67], v[178:181], v[216:219], v[64:67]
	s_barrier
	s_add_i32 s44, s39, s2
	v_lshl_add_u64 v[190:191], s[28:29], 0, v[132:133]
	s_mov_b32 m0, s44
	ds_read_b128 v[182:185], v149 offset:16384
	ds_read_b128 v[186:189], v149 offset:17408
	ds_read_b128 v[196:199], v149 offset:18432
	ds_read_b128 v[200:203], v149 offset:19456
	ds_read_b128 v[204:207], v149 offset:20480
	ds_read_b128 v[208:211], v149 offset:21504
	ds_read_b128 v[212:215], v149 offset:22528
	ds_read_b128 v[216:219], v149 offset:23552
	global_load_lds_dwordx4 v[190:191], off
	s_add_i32 m0, s44, 0x2000
	s_add_u32 s44, s28, 0x18000
	v_lshl_add_u64 v[192:193], s[28:29], 0, v[128:129]
	s_addc_u32 s45, s29, 0
	s_add_i32 s48, s40, s2
	global_load_lds_dwordx4 v[192:193], off
	v_lshl_add_u64 v[194:195], s[44:45], 0, v[132:133]
	s_mov_b32 m0, s48
	v_lshl_add_u64 v[220:221], s[30:31], 0, v[130:131]
	global_load_lds_dwordx4 v[194:195], off
	v_lshl_add_u64 v[194:195], s[44:45], 0, v[128:129]
	s_add_i32 m0, s48, 0x2000
	s_nop 0
	global_load_lds_dwordx4 v[194:195], off
	v_lshl_add_u64 v[194:195], s[30:31], 0, v[134:135]
	s_mov_b32 m0, s8
	s_nop 0
	global_load_lds_dwordx4 v[194:195], off
	s_mov_b32 m0, s9
	s_nop 0
	global_load_lds_dwordx4 v[220:221], off
	s_waitcnt vmcnt(8)
	s_waitcnt lgkmcnt(0)
	s_barrier
; #define PG8_STAGE(bufoff, gbase, voff) do { _Pragma("unroll") for (int _i = 0; _i < 2; ++_i) \
;         __builtin_amdgcn_global_load_lds((const unsigned*)((const char*)(gbase) + (voff)[_i]), (PG8_LAS unsigned*)(lds + (bufoff) + ldsw + _i * 8192), 16, 0, 0); } while (0)
; #define PG8_LDA(dst, b, h) do { _Pragma("unroll") for (int m = 0; m < 4; ++m) _Pragma("unroll") for (int k = 0; k < 2; ++k) dst[m][k] = *(const PG8_LAS bf16x8*)(lds + PG8_SA(b, h) + aoff + m * 2048 + k * 1024); } while (0)
; #define PG8_LDB(dst, b, h) do { _Pragma("unroll") for (int n = 0; n < 2; ++n) _Pragma("unroll") for (int k = 0; k < 2; ++k) dst[n][k] = *(const PG8_LAS bf16x8*)(lds + PG8_SB(b, h) + boff + n * 2048 + k * 1024); } while (0)
; #define PG8_MMA(ai, bj, At, Bt) do { __builtin_amdgcn_s_setprio(1); _Pragma("unroll") for (int m = 0; m < 4; ++m) _Pragma("unroll") for (int n = 0; n < 2; ++n) _Pragma("unroll") for (int k = 0; k < 2; ++k) \
;         acc[ai][bj][m][n] = __builtin_amdgcn_mfma_f32_16x16x32_bf16(Bt[n][k], At[m][k], acc[ai][bj][m][n], 0, 0, 0); __builtin_amdgcn_s_setprio(0); } while (0)
; #define PG8_WAIT_V(n) asm volatile("s_waitcnt vmcnt(" #n ")" ::: "memory")
; #define PG8_WAIT_L(n) asm volatile("s_waitcnt lgkmcnt(" #n ")" ::: "memory")
; #define PG8_BAR __builtin_amdgcn_s_barrier()
; #define PG8_SCHED __builtin_amdgcn_sched_barrier(0)
; template <class Epi, class Sched, bool ALIGN_EPI = false, bool SP2 = false>
; __device__ __forceinline__ void gemm_phase(PG8_LAS unsigned char* lds, const Gemm g, const Sched& S, const Epi& E) {
;     ...
;             PG8_WAIT_V(8); PG8_WAIT_L(0); PG8_BAR; PG8_MMA(1, 0, At, B0); PG8_MMA(1, 1, At, B1); PG8_BAR; PG8_SCHED;
;             PG8_LDB(B0, 1, 0); PG8_LDB(B1, 1, 1); PG8_SCHED; PG8_LDA(At, 1, 0); PG8_STAGE(PG8_SA(0, 1), a2 + hstepA, voffA);
;             PG8_WAIT_V(8); PG8_WAIT_L(0); PG8_BAR; PG8_MMA(0, 0, At, B0); PG8_MMA(0, 1, At, B1); PG8_BAR; PG8_SCHED;
	s_waitcnt lgkmcnt(0)
	v_mfma_f32_16x16x32_bf16 v[60:63], v[150:153], v[182:185], v[60:63]
	v_mfma_f32_16x16x32_bf16 v[56:59], v[158:161], v[182:185], v[56:59]
	v_mfma_f32_16x16x32_bf16 v[52:55], v[150:153], v[196:199], v[52:55]
	v_mfma_f32_16x16x32_bf16 v[48:51], v[158:161], v[196:199], v[48:51]
	v_mfma_f32_16x16x32_bf16 v[36:39], v[150:153], v[204:207], v[36:39]
	v_mfma_f32_16x16x32_bf16 v[32:35], v[158:161], v[204:207], v[32:35]
	v_mfma_f32_16x16x32_bf16 v[20:23], v[150:153], v[212:215], v[20:23]
	v_mfma_f32_16x16x32_bf16 v[16:19], v[158:161], v[212:215], v[16:19]
	v_mfma_f32_16x16x32_bf16 v[60:63], v[154:157], v[186:189], v[60:63]
	v_mfma_f32_16x16x32_bf16 v[56:59], v[162:165], v[186:189], v[56:59]
	v_mfma_f32_16x16x32_bf16 v[52:55], v[154:157], v[200:203], v[52:55]
	v_mfma_f32_16x16x32_bf16 v[48:51], v[162:165], v[200:203], v[48:51]
	v_mfma_f32_16x16x32_bf16 v[36:39], v[154:157], v[208:211], v[36:39]
	v_mfma_f32_16x16x32_bf16 v[32:35], v[162:165], v[208:211], v[32:35]
	v_mfma_f32_16x16x32_bf16 v[20:23], v[154:157], v[216:219], v[20:23]
	v_mfma_f32_16x16x32_bf16 v[16:19], v[162:165], v[216:219], v[16:19]
	v_mfma_f32_16x16x32_bf16 v[44:47], v[166:169], v[182:185], v[44:47]
	v_mfma_f32_16x16x32_bf16 v[40:43], v[174:177], v[182:185], v[40:43]
	v_mfma_f32_16x16x32_bf16 v[28:31], v[166:169], v[196:199], v[28:31]
	v_mfma_f32_16x16x32_bf16 v[24:27], v[174:177], v[196:199], v[24:27]
	v_mfma_f32_16x16x32_bf16 v[12:15], v[166:169], v[204:207], v[12:15]
	v_mfma_f32_16x16x32_bf16 v[8:11], v[174:177], v[204:207], v[8:11]
	v_mfma_f32_16x16x32_bf16 v[4:7], v[166:169], v[212:215], v[4:7]
	v_mfma_f32_16x16x32_bf16 v[0:3], v[174:177], v[212:215], v[0:3]
	v_mfma_f32_16x16x32_bf16 v[44:47], v[170:173], v[186:189], v[44:47]
	v_mfma_f32_16x16x32_bf16 v[40:43], v[178:181], v[186:189], v[40:43]
	v_mfma_f32_16x16x32_bf16 v[28:31], v[170:173], v[200:203], v[28:31]
	v_mfma_f32_16x16x32_bf16 v[24:27], v[178:181], v[200:203], v[24:27]
	v_mfma_f32_16x16x32_bf16 v[12:15], v[170:173], v[208:211], v[12:15]
	v_mfma_f32_16x16x32_bf16 v[8:11], v[178:181], v[208:211], v[8:11]
	v_mfma_f32_16x16x32_bf16 v[4:7], v[170:173], v[216:219], v[4:7]
	v_mfma_f32_16x16x32_bf16 v[0:3], v[178:181], v[216:219], v[0:3]
	s_barrier
	s_add_i32 s44, 0, 0x18000
	s_add_i32 s45, 0, 0x1c000
	v_add_u32_e32 v162, s44, v146
	v_add_u32_e32 v178, s45, v146
	ds_read_b128 v[150:153], v162
	ds_read_b128 v[154:157], v162 offset:1024
	ds_read_b128 v[158:161], v162 offset:2048
	ds_read_b128 v[162:165], v162 offset:3072
	ds_read_b128 v[166:169], v178
	ds_read_b128 v[170:173], v178 offset:1024
	ds_read_b128 v[174:177], v178 offset:2048
	ds_read_b128 v[178:181], v178 offset:3072
	s_add_u32 s30, s30, 0x80000
	s_addc_u32 s31, s31, 0
	s_mov_b32 m0, s10
	v_lshl_add_u64 v[222:223], s[30:31], 0, v[134:135]
	ds_read_b128 v[182:185], v149 offset:32768
	ds_read_b128 v[186:189], v149 offset:33792
	ds_read_b128 v[196:199], v149 offset:34816
	ds_read_b128 v[200:203], v149 offset:35840
	ds_read_b128 v[204:207], v149 offset:36864
	ds_read_b128 v[208:211], v149 offset:37888
	ds_read_b128 v[212:215], v149 offset:38912
	ds_read_b128 v[216:219], v149 offset:39936
	global_load_lds_dwordx4 v[222:223], off
	v_lshl_add_u64 v[222:223], s[30:31], 0, v[130:131]
	s_mov_b32 m0, s11
	s_nop 0
	global_load_lds_dwordx4 v[222:223], off
	s_waitcnt vmcnt(8)
	s_waitcnt lgkmcnt(0)
	s_barrier
	s_waitcnt lgkmcnt(0)
	v_mfma_f32_16x16x32_bf16 v[124:127], v[150:153], v[182:185], v[124:127]
	v_mfma_f32_16x16x32_bf16 v[120:123], v[158:161], v[182:185], v[120:123]
	v_mfma_f32_16x16x32_bf16 v[116:119], v[150:153], v[196:199], v[116:119]
	v_mfma_f32_16x16x32_bf16 v[112:115], v[158:161], v[196:199], v[112:115]
	v_mfma_f32_16x16x32_bf16 v[100:103], v[150:153], v[204:207], v[100:103]
	v_mfma_f32_16x16x32_bf16 v[96:99], v[158:161], v[204:207], v[96:99]
	v_mfma_f32_16x16x32_bf16 v[84:87], v[150:153], v[212:215], v[84:87]
	v_mfma_f32_16x16x32_bf16 v[80:83], v[158:161], v[212:215], v[80:83]
	v_mfma_f32_16x16x32_bf16 v[124:127], v[154:157], v[186:189], v[124:127]
	v_mfma_f32_16x16x32_bf16 v[120:123], v[162:165], v[186:189], v[120:123]
	v_mfma_f32_16x16x32_bf16 v[116:119], v[154:157], v[200:203], v[116:119]
	v_mfma_f32_16x16x32_bf16 v[112:115], v[162:165], v[200:203], v[112:115]
	v_mfma_f32_16x16x32_bf16 v[100:103], v[154:157], v[208:211], v[100:103]
	v_mfma_f32_16x16x32_bf16 v[96:99], v[162:165], v[208:211], v[96:99]
	v_mfma_f32_16x16x32_bf16 v[84:87], v[154:157], v[216:219], v[84:87]
	v_mfma_f32_16x16x32_bf16 v[80:83], v[162:165], v[216:219], v[80:83]
	v_mfma_f32_16x16x32_bf16 v[108:111], v[166:169], v[182:185], v[108:111]
	v_mfma_f32_16x16x32_bf16 v[104:107], v[174:177], v[182:185], v[104:107]
	v_mfma_f32_16x16x32_bf16 v[92:95], v[166:169], v[196:199], v[92:95]
	v_mfma_f32_16x16x32_bf16 v[88:91], v[174:177], v[196:199], v[88:91]
	v_mfma_f32_16x16x32_bf16 v[76:79], v[166:169], v[204:207], v[76:79]
	v_mfma_f32_16x16x32_bf16 v[72:75], v[174:177], v[204:207], v[72:75]
	v_mfma_f32_16x16x32_bf16 v[68:71], v[166:169], v[212:215], v[68:71]
	v_mfma_f32_16x16x32_bf16 v[64:67], v[174:177], v[212:215], v[64:67]
	v_mfma_f32_16x16x32_bf16 v[108:111], v[170:173], v[186:189], v[108:111]
	v_mfma_f32_16x16x32_bf16 v[104:107], v[178:181], v[186:189], v[104:107]
	v_mfma_f32_16x16x32_bf16 v[92:95], v[170:173], v[200:203], v[92:95]
	v_mfma_f32_16x16x32_bf16 v[88:91], v[178:181], v[200:203], v[88:91]
	v_mfma_f32_16x16x32_bf16 v[76:79], v[170:173], v[208:211], v[76:79]
	v_mfma_f32_16x16x32_bf16 v[72:75], v[178:181], v[208:211], v[72:75]
	v_mfma_f32_16x16x32_bf16 v[68:71], v[170:173], v[216:219], v[68:71]
	v_mfma_f32_16x16x32_bf16 v[64:67], v[178:181], v[216:219], v[64:67]
	s_barrier
; #define PG8_STAGE(bufoff, gbase, voff) do { _Pragma("unroll") for (int _i = 0; _i < 2; ++_i) \
;         __builtin_amdgcn_global_load_lds((const unsigned*)((const char*)(gbase) + (voff)[_i]), (PG8_LAS unsigned*)(lds + (bufoff) + ldsw + _i * 8192), 16, 0, 0); } while (0)
; #define PG8_LDA(dst, b, h) do { _Pragma("unroll") for (int m = 0; m < 4; ++m) _Pragma("unroll") for (int k = 0; k < 2; ++k) dst[m][k] = *(const PG8_LAS bf16x8*)(lds + PG8_SA(b, h) + aoff + m * 2048 + k * 1024); } while (0)
; #define PG8_MMA(ai, bj, At, Bt) do { __builtin_amdgcn_s_setprio(1); _Pragma("unroll") for (int m = 0; m < 4; ++m) _Pragma("unroll") for (int n = 0; n < 2; ++n) _Pragma("unroll") for (int k = 0; k < 2; ++k) \
;         acc[ai][bj][m][n] = __builtin_amdgcn_mfma_f32_16x16x32_bf16(Bt[n][k], At[m][k], acc[ai][bj][m][n], 0, 0, 0); __builtin_amdgcn_s_setprio(0); } while (0)
; #define PG8_WAIT_V(n) asm volatile("s_waitcnt vmcnt(" #n ")" ::: "memory")
; #define PG8_WAIT_L(n) asm volatile("s_waitcnt lgkmcnt(" #n ")" ::: "memory")
; #define PG8_BAR __builtin_amdgcn_s_barrier()
; #define PG8_SCHED __builtin_amdgcn_sched_barrier(0)
; template <class Epi, class Sched, bool ALIGN_EPI = false, bool SP2 = false>
; __device__ __forceinline__ void gemm_phase(PG8_LAS unsigned char* lds, const Gemm g, const Sched& S, const Epi& E) {
;     ...
;             PG8_LDA(At, 1, 1); PG8_STAGE(PG8_SB(1, 0), b3, voffB); PG8_STAGE(PG8_SB(1, 1), b3 + hstepB, voffB); PG8_STAGE(PG8_SA(1, 0), a3, voffA);
;             PG8_WAIT_V(8); PG8_WAIT_L(0); PG8_BAR; PG8_MMA(1, 0, At, B0); PG8_MMA(1, 1, At, B1); PG8_BAR; PG8_SCHED;
	s_add_i32 s30, s44, s2
	v_lshl_add_u64 v[190:191], v[190:191], 0, s[16:17]
	s_mov_b32 m0, s30
	ds_read_b128 v[182:185], v149 offset:49152
	ds_read_b128 v[186:189], v149 offset:50176
	ds_read_b128 v[196:199], v149 offset:51200
	ds_read_b128 v[200:203], v149 offset:52224
	ds_read_b128 v[204:207], v149 offset:53248
	ds_read_b128 v[208:211], v149 offset:54272
	ds_read_b128 v[212:215], v149 offset:55296
	ds_read_b128 v[216:219], v149 offset:56320
	global_load_lds_dwordx4 v[190:191], off
	s_add_i32 m0, s30, 0x2000
	s_add_u32 s28, s28, 0x18080
	v_lshl_add_u64 v[190:191], v[192:193], 0, s[16:17]
	s_addc_u32 s29, s29, 0
	s_add_i32 s30, s45, s2
	global_load_lds_dwordx4 v[190:191], off
	v_lshl_add_u64 v[190:191], s[28:29], 0, v[132:133]
	s_mov_b32 m0, s30
	s_nop 0
	global_load_lds_dwordx4 v[190:191], off
	v_lshl_add_u64 v[190:191], s[28:29], 0, v[128:129]
	s_add_i32 m0, s30, 0x2000
	s_nop 0
	global_load_lds_dwordx4 v[190:191], off
	v_lshl_add_u64 v[190:191], v[194:195], 0, s[16:17]
	s_mov_b32 m0, s35
	s_nop 0
	global_load_lds_dwordx4 v[190:191], off
	v_lshl_add_u64 v[190:191], v[220:221], 0, s[16:17]
	s_mov_b32 m0, s36
	s_nop 0
	global_load_lds_dwordx4 v[190:191], off
	s_waitcnt vmcnt(8)
	s_waitcnt lgkmcnt(0)
	s_barrier
	s_waitcnt lgkmcnt(0)
	v_mfma_f32_16x16x32_bf16 v[60:63], v[150:153], v[182:185], v[60:63]
	v_mfma_f32_16x16x32_bf16 v[56:59], v[158:161], v[182:185], v[56:59]
	v_mfma_f32_16x16x32_bf16 v[52:55], v[150:153], v[196:199], v[52:55]
	v_mfma_f32_16x16x32_bf16 v[48:51], v[158:161], v[196:199], v[48:51]
	v_mfma_f32_16x16x32_bf16 v[36:39], v[150:153], v[204:207], v[36:39]
	v_mfma_f32_16x16x32_bf16 v[32:35], v[158:161], v[204:207], v[32:35]
	v_mfma_f32_16x16x32_bf16 v[20:23], v[150:153], v[212:215], v[20:23]
	v_mfma_f32_16x16x32_bf16 v[16:19], v[158:161], v[212:215], v[16:19]
	v_mfma_f32_16x16x32_bf16 v[60:63], v[154:157], v[186:189], v[60:63]
	v_mfma_f32_16x16x32_bf16 v[56:59], v[162:165], v[186:189], v[56:59]
	v_mfma_f32_16x16x32_bf16 v[52:55], v[154:157], v[200:203], v[52:55]
	v_mfma_f32_16x16x32_bf16 v[48:51], v[162:165], v[200:203], v[48:51]
	v_mfma_f32_16x16x32_bf16 v[36:39], v[154:157], v[208:211], v[36:39]
	v_mfma_f32_16x16x32_bf16 v[32:35], v[162:165], v[208:211], v[32:35]
	v_mfma_f32_16x16x32_bf16 v[20:23], v[154:157], v[216:219], v[20:23]
	v_mfma_f32_16x16x32_bf16 v[16:19], v[162:165], v[216:219], v[16:19]
	v_mfma_f32_16x16x32_bf16 v[44:47], v[166:169], v[182:185], v[44:47]
	v_mfma_f32_16x16x32_bf16 v[40:43], v[174:177], v[182:185], v[40:43]
	v_mfma_f32_16x16x32_bf16 v[28:31], v[166:169], v[196:199], v[28:31]
	v_mfma_f32_16x16x32_bf16 v[24:27], v[174:177], v[196:199], v[24:27]
	v_mfma_f32_16x16x32_bf16 v[12:15], v[166:169], v[204:207], v[12:15]
	v_mfma_f32_16x16x32_bf16 v[8:11], v[174:177], v[204:207], v[8:11]
	v_mfma_f32_16x16x32_bf16 v[4:7], v[166:169], v[212:215], v[4:7]
	v_mfma_f32_16x16x32_bf16 v[0:3], v[174:177], v[212:215], v[0:3]
	v_mfma_f32_16x16x32_bf16 v[44:47], v[170:173], v[186:189], v[44:47]
	v_mfma_f32_16x16x32_bf16 v[40:43], v[178:181], v[186:189], v[40:43]
	v_mfma_f32_16x16x32_bf16 v[28:31], v[170:173], v[200:203], v[28:31]
	v_mfma_f32_16x16x32_bf16 v[24:27], v[178:181], v[200:203], v[24:27]
	v_mfma_f32_16x16x32_bf16 v[12:15], v[170:173], v[208:211], v[12:15]
	v_mfma_f32_16x16x32_bf16 v[8:11], v[178:181], v[208:211], v[8:11]
	v_mfma_f32_16x16x32_bf16 v[4:7], v[170:173], v[216:219], v[4:7]
	v_mfma_f32_16x16x32_bf16 v[0:3], v[178:181], v[216:219], v[0:3]
	s_barrier
	s_add_i32 s53, s53, 2
	s_add_u32 s0, s0, 0x100
	s_addc_u32 s1, s1, 0
	s_add_u32 s51, s51, 0x100
	s_addc_u32 s52, s52, 0
	s_cmp_gt_u32 s53, 3
	s_cbranch_scc0 .LBB0_303
	s_and_b64 vcc, exec, s[18:19]
	s_cbranch_vccz .LBB0_306
	s_barrier

; #define PG8_STAGE(bufoff, gbase, voff) do { _Pragma("unroll") for (int _i = 0; _i < 2; ++_i) \
;         __builtin_amdgcn_global_load_lds((const unsigned*)((const char*)(gbase) + (voff)[_i]), (PG8_LAS unsigned*)(lds + (bufoff) + ldsw + _i * 8192), 16, 0, 0); } while (0)
; #define PG8_LDA(dst, b, h) do { _Pragma("unroll") for (int m = 0; m < 4; ++m) _Pragma("unroll") for (int k = 0; k < 2; ++k) dst[m][k] = *(const PG8_LAS bf16x8*)(lds + PG8_SA(b, h) + aoff + m * 2048 + k * 1024); } while (0)
; #define PG8_LDB(dst, b, h) do { _Pragma("unroll") for (int n = 0; n < 2; ++n) _Pragma("unroll") for (int k = 0; k < 2; ++k) dst[n][k] = *(const PG8_LAS bf16x8*)(lds + PG8_SB(b, h) + boff + n * 2048 + k * 1024); } while (0)
; #define PG8_MMA(ai, bj, At, Bt) do { __builtin_amdgcn_s_setprio(1); _Pragma("unroll") for (int m = 0; m < 4; ++m) _Pragma("unroll") for (int n = 0; n < 2; ++n) _Pragma("unroll") for (int k = 0; k < 2; ++k) \
;         acc[ai][bj][m][n] = __builtin_amdgcn_mfma_f32_16x16x32_bf16(Bt[n][k], At[m][k], acc[ai][bj][m][n], 0, 0, 0); __builtin_amdgcn_s_setprio(0); } while (0)
; #define PG8_WAIT_V(n) asm volatile("s_waitcnt vmcnt(" #n ")" ::: "memory")
; #define PG8_WAIT_L(n) asm volatile("s_waitcnt lgkmcnt(" #n ")" ::: "memory")
; #define PG8_BAR __builtin_amdgcn_s_barrier()
; #define PG8_SCHED __builtin_amdgcn_sched_barrier(0)
; template <class Epi, class Sched, bool ALIGN_EPI = false, bool SP2 = false>
; __device__ __forceinline__ void gemm_phase(PG8_LAS unsigned char* lds, const Gemm g, const Sched& S, const Epi& E) {
;     ...
;             const bool last = (t == nt - 2);
;             const char* a1 = cA + (size_t)(t + 1) * kstep;
;             const char* a2 = last ? nA : cA + (size_t)(t + 2) * kstep; const char* b2 = last ? nB : cB + (size_t)(t + 2) * kstep;
;             const char* a3 = a2 + kstep; const char* b3 = b2 + kstep;
;             if (last && has_next) S.a_ready(nxt);
;             if constexpr (SP2) {
;             PG8_LDB(B0, 0, 0); PG8_LDB(B1, 0, 1); PG8_SCHED; PG8_LDA(At, 0, 0); PG8_STAGE(PG8_SA(1, 1), a1 + hstepA, voffA);
;             PG8_WAIT_V(8); PG8_WAIT_L(0); PG8_BAR; PG8_MMA(0, 0, At, B0); PG8_MMA(0, 1, At, B1); PG8_BAR; PG8_SCHED;
;             PG8_LDA(At, 0, 1); PG8_STAGE(PG8_SB(0, 0), b2, voffB); PG8_STAGE(PG8_SB(0, 1), b2 + hstepB, voffB); PG8_STAGE(PG8_SA(0, 0), a2, voffA);
.LBB0_632:
	ds_read_b128 v[144:147], v151
	ds_read_b128 v[156:159], v151 offset:1024
	ds_read_b128 v[160:163], v151 offset:2048
	ds_read_b128 v[164:167], v151 offset:3072
	ds_read_b128 v[168:171], v152
	ds_read_b128 v[172:175], v152 offset:1024
	ds_read_b128 v[176:179], v152 offset:2048
	ds_read_b128 v[180:183], v152 offset:3072
	s_add_u32 s28, s26, 0xfffc0080
	s_addc_u32 s29, s27, -1
	s_cmp_eq_u32 s50, 12
	s_cselect_b32 s31, s17, s29
	s_cselect_b32 s30, s23, s28
	s_cselect_b32 s29, s15, s49
	s_cselect_b32 s28, s43, s48
	v_lshl_add_u64 v[192:193], s[26:27], 0, v[136:137]
	s_add_i32 m0, s9, 0xc000
	ds_read_b128 v[184:187], v153
	ds_read_b128 v[188:191], v153 offset:1024
	ds_read_b128 v[194:197], v153 offset:2048
	ds_read_b128 v[198:201], v153 offset:3072
	ds_read_b128 v[202:205], v153 offset:4096
	ds_read_b128 v[206:209], v153 offset:5120
	ds_read_b128 v[210:213], v153 offset:6144
	ds_read_b128 v[214:217], v153 offset:7168
	global_load_lds_dwordx4 v[192:193], off
	v_lshl_add_u64 v[192:193], s[26:27], 0, v[138:139]
	s_add_i32 m0, s9, 0xe000
	s_nop 0
	global_load_lds_dwordx4 v[192:193], off
	s_waitcnt vmcnt(8)
	s_waitcnt lgkmcnt(0)
	s_barrier
	s_waitcnt lgkmcnt(0)
	v_mfma_f32_16x16x32_bf16 v[124:127], v[144:147], v[184:187], v[124:127]
	v_mfma_f32_16x16x32_bf16 v[120:123], v[160:163], v[184:187], v[120:123]
	v_mfma_f32_16x16x32_bf16 v[108:111], v[144:147], v[194:197], v[108:111]
	v_mfma_f32_16x16x32_bf16 v[104:107], v[160:163], v[194:197], v[104:107]
	v_mfma_f32_16x16x32_bf16 v[92:95], v[144:147], v[202:205], v[92:95]
	v_mfma_f32_16x16x32_bf16 v[88:91], v[160:163], v[202:205], v[88:91]
	v_mfma_f32_16x16x32_bf16 v[76:79], v[144:147], v[210:213], v[76:79]
	v_mfma_f32_16x16x32_bf16 v[72:75], v[160:163], v[210:213], v[72:75]
	v_mfma_f32_16x16x32_bf16 v[124:127], v[156:159], v[188:191], v[124:127]
	v_mfma_f32_16x16x32_bf16 v[120:123], v[164:167], v[188:191], v[120:123]
	v_mfma_f32_16x16x32_bf16 v[108:111], v[156:159], v[198:201], v[108:111]
	v_mfma_f32_16x16x32_bf16 v[104:107], v[164:167], v[198:201], v[104:107]
	v_mfma_f32_16x16x32_bf16 v[92:95], v[156:159], v[206:209], v[92:95]
	v_mfma_f32_16x16x32_bf16 v[88:91], v[164:167], v[206:209], v[88:91]
	v_mfma_f32_16x16x32_bf16 v[76:79], v[156:159], v[214:217], v[76:79]
	v_mfma_f32_16x16x32_bf16 v[72:75], v[164:167], v[214:217], v[72:75]
	v_mfma_f32_16x16x32_bf16 v[116:119], v[168:171], v[184:187], v[116:119]
	v_mfma_f32_16x16x32_bf16 v[112:115], v[176:179], v[184:187], v[112:115]
	v_mfma_f32_16x16x32_bf16 v[100:103], v[168:171], v[194:197], v[100:103]
	v_mfma_f32_16x16x32_bf16 v[96:99], v[176:179], v[194:197], v[96:99]
	v_mfma_f32_16x16x32_bf16 v[84:87], v[168:171], v[202:205], v[84:87]
	v_mfma_f32_16x16x32_bf16 v[80:83], v[176:179], v[202:205], v[80:83]
	v_mfma_f32_16x16x32_bf16 v[68:71], v[168:171], v[210:213], v[68:71]
	v_mfma_f32_16x16x32_bf16 v[64:67], v[176:179], v[210:213], v[64:67]
	v_mfma_f32_16x16x32_bf16 v[116:119], v[172:175], v[188:191], v[116:119]
	v_mfma_f32_16x16x32_bf16 v[112:115], v[180:183], v[188:191], v[112:115]
	v_mfma_f32_16x16x32_bf16 v[100:103], v[172:175], v[198:201], v[100:103]
	v_mfma_f32_16x16x32_bf16 v[96:99], v[180:183], v[198:201], v[96:99]
	v_mfma_f32_16x16x32_bf16 v[84:87], v[172:175], v[206:209], v[84:87]
	v_mfma_f32_16x16x32_bf16 v[80:83], v[180:183], v[206:209], v[80:83]
	v_mfma_f32_16x16x32_bf16 v[68:71], v[172:175], v[214:217], v[68:71]
	v_mfma_f32_16x16x32_bf16 v[64:67], v[180:183], v[214:217], v[64:67]
	s_barrier
	s_add_i32 s44, s41, s8
	v_lshl_add_u64 v[192:193], s[28:29], 0, v[130:131]
	s_mov_b32 m0, s44
	ds_read_b128 v[184:187], v153 offset:16384
	ds_read_b128 v[188:191], v153 offset:17408
	ds_read_b128 v[194:197], v153 offset:18432
	ds_read_b128 v[198:201], v153 offset:19456
	ds_read_b128 v[202:205], v153 offset:20480
	ds_read_b128 v[206:209], v153 offset:21504
	ds_read_b128 v[210:213], v153 offset:22528
	ds_read_b128 v[214:217], v153 offset:23552
	global_load_lds_dwordx4 v[192:193], off
	s_add_i32 m0, s44, 0x2000
	s_add_u32 s44, s28, 0x40000
	v_lshl_add_u64 v[218:219], s[28:29], 0, v[134:135]
	s_addc_u32 s45, s29, 0
	s_add_i32 s51, s42, s8
	global_load_lds_dwordx4 v[218:219], off
	v_lshl_add_u64 v[220:221], s[44:45], 0, v[130:131]
	s_mov_b32 m0, s51
	v_lshl_add_u64 v[222:223], s[30:31], 0, v[132:133]
	global_load_lds_dwordx4 v[220:221], off
	v_lshl_add_u64 v[220:221], s[44:45], 0, v[134:135]
	s_add_i32 m0, s51, 0x2000
	s_nop 0
	global_load_lds_dwordx4 v[220:221], off
	v_lshl_add_u64 v[220:221], s[30:31], 0, v[128:129]
	s_mov_b32 m0, s9
	s_nop 0
	global_load_lds_dwordx4 v[220:221], off
	s_mov_b32 m0, s10
	s_nop 0
	global_load_lds_dwordx4 v[222:223], off
	s_waitcnt vmcnt(8)
	s_waitcnt lgkmcnt(0)
	s_barrier
; #define PG8_STAGE(bufoff, gbase, voff) do { _Pragma("unroll") for (int _i = 0; _i < 2; ++_i) \
;         __builtin_amdgcn_global_load_lds((const unsigned*)((const char*)(gbase) + (voff)[_i]), (PG8_LAS unsigned*)(lds + (bufoff) + ldsw + _i * 8192), 16, 0, 0); } while (0)
; #define PG8_LDA(dst, b, h) do { _Pragma("unroll") for (int m = 0; m < 4; ++m) _Pragma("unroll") for (int k = 0; k < 2; ++k) dst[m][k] = *(const PG8_LAS bf16x8*)(lds + PG8_SA(b, h) + aoff + m * 2048 + k * 1024); } while (0)
; #define PG8_LDB(dst, b, h) do { _Pragma("unroll") for (int n = 0; n < 2; ++n) _Pragma("unroll") for (int k = 0; k < 2; ++k) dst[n][k] = *(const PG8_LAS bf16x8*)(lds + PG8_SB(b, h) + boff + n * 2048 + k * 1024); } while (0)
; #define PG8_MMA(ai, bj, At, Bt) do { __builtin_amdgcn_s_setprio(1); _Pragma("unroll") for (int m = 0; m < 4; ++m) _Pragma("unroll") for (int n = 0; n < 2; ++n) _Pragma("unroll") for (int k = 0; k < 2; ++k) \
;         acc[ai][bj][m][n] = __builtin_amdgcn_mfma_f32_16x16x32_bf16(Bt[n][k], At[m][k], acc[ai][bj][m][n], 0, 0, 0); __builtin_amdgcn_s_setprio(0); } while (0)
; #define PG8_WAIT_V(n) asm volatile("s_waitcnt vmcnt(" #n ")" ::: "memory")
; #define PG8_WAIT_L(n) asm volatile("s_waitcnt lgkmcnt(" #n ")" ::: "memory")
; #define PG8_BAR __builtin_amdgcn_s_barrier()
; #define PG8_SCHED __builtin_amdgcn_sched_barrier(0)
; template <class Epi, class Sched, bool ALIGN_EPI = false, bool SP2 = false>
; __device__ __forceinline__ void gemm_phase(PG8_LAS unsigned char* lds, const Gemm g, const Sched& S, const Epi& E) {
;     ...
;             PG8_WAIT_V(8); PG8_WAIT_L(0); PG8_BAR; PG8_MMA(1, 0, At, B0); PG8_MMA(1, 1, At, B1); PG8_BAR; PG8_SCHED;
;             PG8_LDB(B0, 1, 0); PG8_LDB(B1, 1, 1); PG8_SCHED; PG8_LDA(At, 1, 0); PG8_STAGE(PG8_SA(0, 1), a2 + hstepA, voffA);
;             PG8_WAIT_V(8); PG8_WAIT_L(0); PG8_BAR; PG8_MMA(0, 0, At, B0); PG8_MMA(0, 1, At, B1); PG8_BAR; PG8_SCHED;
	s_waitcnt lgkmcnt(0)
	v_mfma_f32_16x16x32_bf16 v[60:63], v[144:147], v[184:187], v[60:63]
	v_mfma_f32_16x16x32_bf16 v[56:59], v[160:163], v[184:187], v[56:59]
	v_mfma_f32_16x16x32_bf16 v[44:47], v[144:147], v[194:197], v[44:47]
	v_mfma_f32_16x16x32_bf16 v[40:43], v[160:163], v[194:197], v[40:43]
	v_mfma_f32_16x16x32_bf16 v[28:31], v[144:147], v[202:205], v[28:31]
	v_mfma_f32_16x16x32_bf16 v[24:27], v[160:163], v[202:205], v[24:27]
	v_mfma_f32_16x16x32_bf16 v[12:15], v[144:147], v[210:213], v[12:15]
	v_mfma_f32_16x16x32_bf16 v[8:11], v[160:163], v[210:213], v[8:11]
	v_mfma_f32_16x16x32_bf16 v[60:63], v[156:159], v[188:191], v[60:63]
	v_mfma_f32_16x16x32_bf16 v[56:59], v[164:167], v[188:191], v[56:59]
	v_mfma_f32_16x16x32_bf16 v[44:47], v[156:159], v[198:201], v[44:47]
	v_mfma_f32_16x16x32_bf16 v[40:43], v[164:167], v[198:201], v[40:43]
	v_mfma_f32_16x16x32_bf16 v[28:31], v[156:159], v[206:209], v[28:31]
	v_mfma_f32_16x16x32_bf16 v[24:27], v[164:167], v[206:209], v[24:27]
	v_mfma_f32_16x16x32_bf16 v[12:15], v[156:159], v[214:217], v[12:15]
	v_mfma_f32_16x16x32_bf16 v[8:11], v[164:167], v[214:217], v[8:11]
	v_mfma_f32_16x16x32_bf16 v[52:55], v[168:171], v[184:187], v[52:55]
	v_mfma_f32_16x16x32_bf16 v[48:51], v[176:179], v[184:187], v[48:51]
	v_mfma_f32_16x16x32_bf16 v[36:39], v[168:171], v[194:197], v[36:39]
	v_mfma_f32_16x16x32_bf16 v[32:35], v[176:179], v[194:197], v[32:35]
	v_mfma_f32_16x16x32_bf16 v[20:23], v[168:171], v[202:205], v[20:23]
	v_mfma_f32_16x16x32_bf16 v[16:19], v[176:179], v[202:205], v[16:19]
	v_mfma_f32_16x16x32_bf16 v[4:7], v[168:171], v[210:213], v[4:7]
	v_mfma_f32_16x16x32_bf16 v[0:3], v[176:179], v[210:213], v[0:3]
	v_mfma_f32_16x16x32_bf16 v[52:55], v[172:175], v[188:191], v[52:55]
	v_mfma_f32_16x16x32_bf16 v[48:51], v[180:183], v[188:191], v[48:51]
	v_mfma_f32_16x16x32_bf16 v[36:39], v[172:175], v[198:201], v[36:39]
	v_mfma_f32_16x16x32_bf16 v[32:35], v[180:183], v[198:201], v[32:35]
	v_mfma_f32_16x16x32_bf16 v[20:23], v[172:175], v[206:209], v[20:23]
	v_mfma_f32_16x16x32_bf16 v[16:19], v[180:183], v[206:209], v[16:19]
	v_mfma_f32_16x16x32_bf16 v[4:7], v[172:175], v[214:217], v[4:7]
	v_mfma_f32_16x16x32_bf16 v[0:3], v[180:183], v[214:217], v[0:3]
	s_barrier
	s_add_i32 s44, 0, 0x18000
	v_add_u32_e32 v155, s44, v150
	s_add_i32 s45, 0, 0x1c000
	ds_read_b128 v[144:147], v155
	ds_read_b128 v[156:159], v155 offset:1024
	ds_read_b128 v[160:163], v155 offset:2048
	ds_read_b128 v[164:167], v155 offset:3072
	v_add_u32_e32 v155, s45, v150
	ds_read_b128 v[168:171], v155
	ds_read_b128 v[172:175], v155 offset:1024
	ds_read_b128 v[176:179], v155 offset:2048
	ds_read_b128 v[180:183], v155 offset:3072
	s_add_u32 s30, s30, 0x40000
	s_addc_u32 s31, s31, 0
	s_mov_b32 m0, s11
	v_lshl_add_u64 v[224:225], s[30:31], 0, v[128:129]
	ds_read_b128 v[184:187], v153 offset:32768
	ds_read_b128 v[188:191], v153 offset:33792
	ds_read_b128 v[194:197], v153 offset:34816
	ds_read_b128 v[198:201], v153 offset:35840
	ds_read_b128 v[202:205], v153 offset:36864
	ds_read_b128 v[206:209], v153 offset:37888
	ds_read_b128 v[210:213], v153 offset:38912
	ds_read_b128 v[214:217], v153 offset:39936
	global_load_lds_dwordx4 v[224:225], off
	v_lshl_add_u64 v[224:225], s[30:31], 0, v[132:133]
	s_mov_b32 m0, s25
	s_nop 0
	global_load_lds_dwordx4 v[224:225], off
	s_waitcnt vmcnt(8)
	s_waitcnt lgkmcnt(0)
	s_barrier
	s_waitcnt lgkmcnt(0)
	v_mfma_f32_16x16x32_bf16 v[124:127], v[144:147], v[184:187], v[124:127]
	v_mfma_f32_16x16x32_bf16 v[120:123], v[160:163], v[184:187], v[120:123]
	v_mfma_f32_16x16x32_bf16 v[108:111], v[144:147], v[194:197], v[108:111]
	v_mfma_f32_16x16x32_bf16 v[104:107], v[160:163], v[194:197], v[104:107]
	v_mfma_f32_16x16x32_bf16 v[92:95], v[144:147], v[202:205], v[92:95]
	v_mfma_f32_16x16x32_bf16 v[88:91], v[160:163], v[202:205], v[88:91]
	v_mfma_f32_16x16x32_bf16 v[76:79], v[144:147], v[210:213], v[76:79]
	v_mfma_f32_16x16x32_bf16 v[72:75], v[160:163], v[210:213], v[72:75]
	v_mfma_f32_16x16x32_bf16 v[124:127], v[156:159], v[188:191], v[124:127]
	v_mfma_f32_16x16x32_bf16 v[120:123], v[164:167], v[188:191], v[120:123]
	v_mfma_f32_16x16x32_bf16 v[108:111], v[156:159], v[198:201], v[108:111]
	v_mfma_f32_16x16x32_bf16 v[104:107], v[164:167], v[198:201], v[104:107]
	v_mfma_f32_16x16x32_bf16 v[92:95], v[156:159], v[206:209], v[92:95]
	v_mfma_f32_16x16x32_bf16 v[88:91], v[164:167], v[206:209], v[88:91]
	v_mfma_f32_16x16x32_bf16 v[76:79], v[156:159], v[214:217], v[76:79]
	v_mfma_f32_16x16x32_bf16 v[72:75], v[164:167], v[214:217], v[72:75]
	v_mfma_f32_16x16x32_bf16 v[116:119], v[168:171], v[184:187], v[116:119]
	v_mfma_f32_16x16x32_bf16 v[112:115], v[176:179], v[184:187], v[112:115]
	v_mfma_f32_16x16x32_bf16 v[100:103], v[168:171], v[194:197], v[100:103]
	v_mfma_f32_16x16x32_bf16 v[96:99], v[176:179], v[194:197], v[96:99]
	v_mfma_f32_16x16x32_bf16 v[84:87], v[168:171], v[202:205], v[84:87]
	v_mfma_f32_16x16x32_bf16 v[80:83], v[176:179], v[202:205], v[80:83]
	v_mfma_f32_16x16x32_bf16 v[68:71], v[168:171], v[210:213], v[68:71]
	v_mfma_f32_16x16x32_bf16 v[64:67], v[176:179], v[210:213], v[64:67]
	v_mfma_f32_16x16x32_bf16 v[116:119], v[172:175], v[188:191], v[116:119]
	v_mfma_f32_16x16x32_bf16 v[112:115], v[180:183], v[188:191], v[112:115]
	v_mfma_f32_16x16x32_bf16 v[100:103], v[172:175], v[198:201], v[100:103]
	v_mfma_f32_16x16x32_bf16 v[96:99], v[180:183], v[198:201], v[96:99]
	v_mfma_f32_16x16x32_bf16 v[84:87], v[172:175], v[206:209], v[84:87]
	v_mfma_f32_16x16x32_bf16 v[80:83], v[180:183], v[206:209], v[80:83]
	v_mfma_f32_16x16x32_bf16 v[68:71], v[172:175], v[214:217], v[68:71]
	v_mfma_f32_16x16x32_bf16 v[64:67], v[180:183], v[214:217], v[64:67]
	s_barrier
; #define PG8_STAGE(bufoff, gbase, voff) do { _Pragma("unroll") for (int _i = 0; _i < 2; ++_i) \
;         __builtin_amdgcn_global_load_lds((const unsigned*)((const char*)(gbase) + (voff)[_i]), (PG8_LAS unsigned*)(lds + (bufoff) + ldsw + _i * 8192), 16, 0, 0); } while (0)
; #define PG8_LDA(dst, b, h) do { _Pragma("unroll") for (int m = 0; m < 4; ++m) _Pragma("unroll") for (int k = 0; k < 2; ++k) dst[m][k] = *(const PG8_LAS bf16x8*)(lds + PG8_SA(b, h) + aoff + m * 2048 + k * 1024); } while (0)
; #define PG8_MMA(ai, bj, At, Bt) do { __builtin_amdgcn_s_setprio(1); _Pragma("unroll") for (int m = 0; m < 4; ++m) _Pragma("unroll") for (int n = 0; n < 2; ++n) _Pragma("unroll") for (int k = 0; k < 2; ++k) \
;         acc[ai][bj][m][n] = __builtin_amdgcn_mfma_f32_16x16x32_bf16(Bt[n][k], At[m][k], acc[ai][bj][m][n], 0, 0, 0); __builtin_amdgcn_s_setprio(0); } while (0)
; #define PG8_WAIT_V(n) asm volatile("s_waitcnt vmcnt(" #n ")" ::: "memory")
; #define PG8_WAIT_L(n) asm volatile("s_waitcnt lgkmcnt(" #n ")" ::: "memory")
; #define PG8_BAR __builtin_amdgcn_s_barrier()
; #define PG8_SCHED __builtin_amdgcn_sched_barrier(0)
; template <class Epi, class Sched, bool ALIGN_EPI = false, bool SP2 = false>
; __device__ __forceinline__ void gemm_phase(PG8_LAS unsigned char* lds, const Gemm g, const Sched& S, const Epi& E) {
;     ...
;             PG8_LDA(At, 1, 1); PG8_STAGE(PG8_SB(1, 0), b3, voffB); PG8_STAGE(PG8_SB(1, 1), b3 + hstepB, voffB); PG8_STAGE(PG8_SA(1, 0), a3, voffA);
;             PG8_WAIT_V(8); PG8_WAIT_L(0); PG8_BAR; PG8_MMA(1, 0, At, B0); PG8_MMA(1, 1, At, B1); PG8_BAR; PG8_SCHED;
	s_add_i32 s30, s44, s8
	v_lshl_add_u64 v[192:193], v[192:193], 0, s[6:7]
	s_mov_b32 m0, s30
	ds_read_b128 v[184:187], v153 offset:49152
	ds_read_b128 v[188:191], v153 offset:50176
	ds_read_b128 v[194:197], v153 offset:51200
	ds_read_b128 v[198:201], v153 offset:52224
	ds_read_b128 v[202:205], v153 offset:53248
	ds_read_b128 v[206:209], v153 offset:54272
	ds_read_b128 v[210:213], v153 offset:55296
	ds_read_b128 v[214:217], v153 offset:56320
	global_load_lds_dwordx4 v[192:193], off
	s_add_i32 m0, s30, 0x2000
	s_add_u32 s28, s28, 0x40080
	v_lshl_add_u64 v[192:193], v[218:219], 0, s[6:7]
	s_addc_u32 s29, s29, 0
	s_add_i32 s30, s45, s8
	global_load_lds_dwordx4 v[192:193], off
	v_lshl_add_u64 v[192:193], s[28:29], 0, v[130:131]
	s_mov_b32 m0, s30
	s_nop 0
	global_load_lds_dwordx4 v[192:193], off
	v_lshl_add_u64 v[192:193], s[28:29], 0, v[134:135]
	s_add_i32 m0, s30, 0x2000
	s_nop 0
	global_load_lds_dwordx4 v[192:193], off
	v_lshl_add_u64 v[192:193], v[220:221], 0, s[6:7]
	s_mov_b32 m0, s36
	s_nop 0
	global_load_lds_dwordx4 v[192:193], off
	v_lshl_add_u64 v[192:193], v[222:223], 0, s[6:7]
	s_mov_b32 m0, s37
	s_nop 0
	global_load_lds_dwordx4 v[192:193], off
	s_waitcnt vmcnt(8)
	s_waitcnt lgkmcnt(0)
	s_barrier
	s_waitcnt lgkmcnt(0)
	v_mfma_f32_16x16x32_bf16 v[60:63], v[144:147], v[184:187], v[60:63]
	v_mfma_f32_16x16x32_bf16 v[56:59], v[160:163], v[184:187], v[56:59]
	v_mfma_f32_16x16x32_bf16 v[44:47], v[144:147], v[194:197], v[44:47]
	v_mfma_f32_16x16x32_bf16 v[40:43], v[160:163], v[194:197], v[40:43]
	v_mfma_f32_16x16x32_bf16 v[28:31], v[144:147], v[202:205], v[28:31]
	v_mfma_f32_16x16x32_bf16 v[24:27], v[160:163], v[202:205], v[24:27]
	v_mfma_f32_16x16x32_bf16 v[12:15], v[144:147], v[210:213], v[12:15]
	v_mfma_f32_16x16x32_bf16 v[8:11], v[160:163], v[210:213], v[8:11]
	v_mfma_f32_16x16x32_bf16 v[60:63], v[156:159], v[188:191], v[60:63]
	v_mfma_f32_16x16x32_bf16 v[56:59], v[164:167], v[188:191], v[56:59]
	v_mfma_f32_16x16x32_bf16 v[44:47], v[156:159], v[198:201], v[44:47]
	v_mfma_f32_16x16x32_bf16 v[40:43], v[164:167], v[198:201], v[40:43]
	v_mfma_f32_16x16x32_bf16 v[28:31], v[156:159], v[206:209], v[28:31]
	v_mfma_f32_16x16x32_bf16 v[24:27], v[164:167], v[206:209], v[24:27]
	v_mfma_f32_16x16x32_bf16 v[12:15], v[156:159], v[214:217], v[12:15]
	v_mfma_f32_16x16x32_bf16 v[8:11], v[164:167], v[214:217], v[8:11]
	v_mfma_f32_16x16x32_bf16 v[52:55], v[168:171], v[184:187], v[52:55]
	v_mfma_f32_16x16x32_bf16 v[48:51], v[176:179], v[184:187], v[48:51]
	v_mfma_f32_16x16x32_bf16 v[36:39], v[168:171], v[194:197], v[36:39]
	v_mfma_f32_16x16x32_bf16 v[32:35], v[176:179], v[194:197], v[32:35]
	v_mfma_f32_16x16x32_bf16 v[20:23], v[168:171], v[202:205], v[20:23]
	v_mfma_f32_16x16x32_bf16 v[16:19], v[176:179], v[202:205], v[16:19]
	v_mfma_f32_16x16x32_bf16 v[4:7], v[168:171], v[210:213], v[4:7]
	v_mfma_f32_16x16x32_bf16 v[0:3], v[176:179], v[210:213], v[0:3]
	v_mfma_f32_16x16x32_bf16 v[52:55], v[172:175], v[188:191], v[52:55]
	v_mfma_f32_16x16x32_bf16 v[48:51], v[180:183], v[188:191], v[48:51]
	v_mfma_f32_16x16x32_bf16 v[36:39], v[172:175], v[198:201], v[36:39]
	v_mfma_f32_16x16x32_bf16 v[32:35], v[180:183], v[198:201], v[32:35]
	v_mfma_f32_16x16x32_bf16 v[20:23], v[172:175], v[206:209], v[20:23]
	v_mfma_f32_16x16x32_bf16 v[16:19], v[180:183], v[206:209], v[16:19]
	v_mfma_f32_16x16x32_bf16 v[4:7], v[172:175], v[214:217], v[4:7]
	v_mfma_f32_16x16x32_bf16 v[0:3], v[180:183], v[214:217], v[0:3]
	s_barrier
	s_add_i32 s50, s50, 2
	s_add_u32 s26, s26, 0x100
	s_addc_u32 s27, s27, 0
	s_add_u32 s48, s48, 0x100
	s_addc_u32 s49, s49, 0
	s_cmp_gt_u32 s50, 13
	s_cbranch_scc0 .LBB0_632
	s_and_b64 vcc, exec, s[12:13]
	s_cbranch_vccz .LBB0_635
	s_barrier

; #define PG8_STAGE(bufoff, gbase, voff) do { _Pragma("unroll") for (int _i = 0; _i < 2; ++_i) \
;         __builtin_amdgcn_global_load_lds((const unsigned*)((const char*)(gbase) + (voff)[_i]), (PG8_LAS unsigned*)(lds + (bufoff) + ldsw + _i * 8192), 16, 0, 0); } while (0)
; #define PG8_LDA(dst, b, h) do { _Pragma("unroll") for (int m = 0; m < 4; ++m) _Pragma("unroll") for (int k = 0; k < 2; ++k) dst[m][k] = *(const PG8_LAS bf16x8*)(lds + PG8_SA(b, h) + aoff + m * 2048 + k * 1024); } while (0)
; #define PG8_LDB(dst, b, h) do { _Pragma("unroll") for (int n = 0; n < 2; ++n) _Pragma("unroll") for (int k = 0; k < 2; ++k) dst[n][k] = *(const PG8_LAS bf16x8*)(lds + PG8_SB(b, h) + boff + n * 2048 + k * 1024); } while (0)
; #define PG8_MMA(ai, bj, At, Bt) do { __builtin_amdgcn_s_setprio(1); _Pragma("unroll") for (int m = 0; m < 4; ++m) _Pragma("unroll") for (int n = 0; n < 2; ++n) _Pragma("unroll") for (int k = 0; k < 2; ++k) \
;         acc[ai][bj][m][n] = __builtin_amdgcn_mfma_f32_16x16x32_bf16(Bt[n][k], At[m][k], acc[ai][bj][m][n], 0, 0, 0); __builtin_amdgcn_s_setprio(0); } while (0)
; #define PG8_WAIT_V(n) asm volatile("s_waitcnt vmcnt(" #n ")" ::: "memory")
; #define PG8_WAIT_L(n) asm volatile("s_waitcnt lgkmcnt(" #n ")" ::: "memory")
; #define PG8_BAR __builtin_amdgcn_s_barrier()
; #define PG8_SCHED __builtin_amdgcn_sched_barrier(0)
; template <class Epi, class Sched, bool ALIGN_EPI = false, bool SP2 = false>
; __device__ __forceinline__ void gemm_phase(PG8_LAS unsigned char* lds, const Gemm g, const Sched& S, const Epi& E) {
;     ...
;             const bool last = (t == nt - 2);
;             const char* a1 = cA + (size_t)(t + 1) * kstep;
;             const char* a2 = last ? nA : cA + (size_t)(t + 2) * kstep; const char* b2 = last ? nB : cB + (size_t)(t + 2) * kstep;
;             const char* a3 = a2 + kstep; const char* b3 = b2 + kstep;
;             if (last && has_next) S.a_ready(nxt);
;             if constexpr (SP2) {
;             PG8_LDB(B0, 0, 0); PG8_LDB(B1, 0, 1); PG8_SCHED; PG8_LDA(At, 0, 0); PG8_STAGE(PG8_SA(1, 1), a1 + hstepA, voffA);
;             PG8_WAIT_V(8); PG8_WAIT_L(0); PG8_BAR; PG8_MMA(0, 0, At, B0); PG8_MMA(0, 1, At, B1); PG8_BAR; PG8_SCHED;
;             PG8_LDA(At, 0, 1); PG8_STAGE(PG8_SB(0, 0), b2, voffB); PG8_STAGE(PG8_SB(0, 1), b2 + hstepB, voffB); PG8_STAGE(PG8_SA(0, 0), a2, voffA);
.LBB0_724:
	ds_read_b128 v[144:147], v151
	ds_read_b128 v[156:159], v151 offset:1024
	ds_read_b128 v[160:163], v151 offset:2048
	ds_read_b128 v[164:167], v151 offset:3072
	ds_read_b128 v[168:171], v152
	ds_read_b128 v[172:175], v152 offset:1024
	ds_read_b128 v[176:179], v152 offset:2048
	ds_read_b128 v[180:183], v152 offset:3072
	s_add_u32 s44, s40, 0xfffc0080
	s_addc_u32 s45, s41, -1
	s_cmp_eq_u32 s63, 12
	s_cselect_b32 s49, s8, s45
	s_cselect_b32 s48, s9, s44
	s_cselect_b32 s45, s29, s62
	s_cselect_b32 s44, s31, s42
	v_lshl_add_u64 v[192:193], s[40:41], 0, v[136:137]
	s_add_i32 m0, s39, 0xc000
	ds_read_b128 v[184:187], v153
	ds_read_b128 v[188:191], v153 offset:1024
	ds_read_b128 v[194:197], v153 offset:2048
	ds_read_b128 v[198:201], v153 offset:3072
	ds_read_b128 v[202:205], v153 offset:4096
	ds_read_b128 v[206:209], v153 offset:5120
	ds_read_b128 v[210:213], v153 offset:6144
	ds_read_b128 v[214:217], v153 offset:7168
	global_load_lds_dwordx4 v[192:193], off
	v_lshl_add_u64 v[192:193], s[40:41], 0, v[138:139]
	s_add_i32 m0, s39, 0xe000
	s_nop 0
	global_load_lds_dwordx4 v[192:193], off
	s_waitcnt vmcnt(8)
	s_waitcnt lgkmcnt(0)
	s_barrier
	s_waitcnt lgkmcnt(0)
	v_mfma_f32_16x16x32_bf16 v[124:127], v[144:147], v[184:187], v[124:127]
	v_mfma_f32_16x16x32_bf16 v[120:123], v[160:163], v[184:187], v[120:123]
	v_mfma_f32_16x16x32_bf16 v[108:111], v[144:147], v[194:197], v[108:111]
	v_mfma_f32_16x16x32_bf16 v[104:107], v[160:163], v[194:197], v[104:107]
	v_mfma_f32_16x16x32_bf16 v[92:95], v[144:147], v[202:205], v[92:95]
	v_mfma_f32_16x16x32_bf16 v[88:91], v[160:163], v[202:205], v[88:91]
	v_mfma_f32_16x16x32_bf16 v[76:79], v[144:147], v[210:213], v[76:79]
	v_mfma_f32_16x16x32_bf16 v[72:75], v[160:163], v[210:213], v[72:75]
	v_mfma_f32_16x16x32_bf16 v[124:127], v[156:159], v[188:191], v[124:127]
	v_mfma_f32_16x16x32_bf16 v[120:123], v[164:167], v[188:191], v[120:123]
	v_mfma_f32_16x16x32_bf16 v[108:111], v[156:159], v[198:201], v[108:111]
	v_mfma_f32_16x16x32_bf16 v[104:107], v[164:167], v[198:201], v[104:107]
	v_mfma_f32_16x16x32_bf16 v[92:95], v[156:159], v[206:209], v[92:95]
	v_mfma_f32_16x16x32_bf16 v[88:91], v[164:167], v[206:209], v[88:91]
	v_mfma_f32_16x16x32_bf16 v[76:79], v[156:159], v[214:217], v[76:79]
	v_mfma_f32_16x16x32_bf16 v[72:75], v[164:167], v[214:217], v[72:75]
	v_mfma_f32_16x16x32_bf16 v[116:119], v[168:171], v[184:187], v[116:119]
	v_mfma_f32_16x16x32_bf16 v[112:115], v[176:179], v[184:187], v[112:115]
	v_mfma_f32_16x16x32_bf16 v[100:103], v[168:171], v[194:197], v[100:103]
	v_mfma_f32_16x16x32_bf16 v[96:99], v[176:179], v[194:197], v[96:99]
	v_mfma_f32_16x16x32_bf16 v[84:87], v[168:171], v[202:205], v[84:87]
	v_mfma_f32_16x16x32_bf16 v[80:83], v[176:179], v[202:205], v[80:83]
	v_mfma_f32_16x16x32_bf16 v[68:71], v[168:171], v[210:213], v[68:71]
	v_mfma_f32_16x16x32_bf16 v[64:67], v[176:179], v[210:213], v[64:67]
	v_mfma_f32_16x16x32_bf16 v[116:119], v[172:175], v[188:191], v[116:119]
	v_mfma_f32_16x16x32_bf16 v[112:115], v[180:183], v[188:191], v[112:115]
	v_mfma_f32_16x16x32_bf16 v[100:103], v[172:175], v[198:201], v[100:103]
	v_mfma_f32_16x16x32_bf16 v[96:99], v[180:183], v[198:201], v[96:99]
	v_mfma_f32_16x16x32_bf16 v[84:87], v[172:175], v[206:209], v[84:87]
	v_mfma_f32_16x16x32_bf16 v[80:83], v[180:183], v[206:209], v[80:83]
	v_mfma_f32_16x16x32_bf16 v[68:71], v[172:175], v[214:217], v[68:71]
	v_mfma_f32_16x16x32_bf16 v[64:67], v[180:183], v[214:217], v[64:67]
	s_barrier
	s_add_i32 s64, s60, s50
	v_lshl_add_u64 v[192:193], s[44:45], 0, v[130:131]
	s_mov_b32 m0, s64
	ds_read_b128 v[184:187], v153 offset:16384
	ds_read_b128 v[188:191], v153 offset:17408
	ds_read_b128 v[194:197], v153 offset:18432
	ds_read_b128 v[198:201], v153 offset:19456
	ds_read_b128 v[202:205], v153 offset:20480
	ds_read_b128 v[206:209], v153 offset:21504
	ds_read_b128 v[210:213], v153 offset:22528
	ds_read_b128 v[214:217], v153 offset:23552
	global_load_lds_dwordx4 v[192:193], off
	s_add_i32 m0, s64, 0x2000
	s_add_u32 s64, s44, 0x40000
	v_lshl_add_u64 v[218:219], s[44:45], 0, v[134:135]
	s_addc_u32 s65, s45, 0
	s_add_i32 s66, s61, s50
	global_load_lds_dwordx4 v[218:219], off
	v_lshl_add_u64 v[220:221], s[64:65], 0, v[130:131]
	s_mov_b32 m0, s66
	v_lshl_add_u64 v[222:223], s[48:49], 0, v[132:133]
	global_load_lds_dwordx4 v[220:221], off
	v_lshl_add_u64 v[220:221], s[64:65], 0, v[134:135]
	s_add_i32 m0, s66, 0x2000
	s_nop 0
	global_load_lds_dwordx4 v[220:221], off
	v_lshl_add_u64 v[220:221], s[48:49], 0, v[128:129]
	s_mov_b32 m0, s39
	s_nop 0
	global_load_lds_dwordx4 v[220:221], off
	s_mov_b32 m0, s51
	s_nop 0
	global_load_lds_dwordx4 v[222:223], off
	s_waitcnt vmcnt(8)
	s_waitcnt lgkmcnt(0)
	s_barrier
; #define PG8_STAGE(bufoff, gbase, voff) do { _Pragma("unroll") for (int _i = 0; _i < 2; ++_i) \
;         __builtin_amdgcn_global_load_lds((const unsigned*)((const char*)(gbase) + (voff)[_i]), (PG8_LAS unsigned*)(lds + (bufoff) + ldsw + _i * 8192), 16, 0, 0); } while (0)
; #define PG8_LDA(dst, b, h) do { _Pragma("unroll") for (int m = 0; m < 4; ++m) _Pragma("unroll") for (int k = 0; k < 2; ++k) dst[m][k] = *(const PG8_LAS bf16x8*)(lds + PG8_SA(b, h) + aoff + m * 2048 + k * 1024); } while (0)
; #define PG8_LDB(dst, b, h) do { _Pragma("unroll") for (int n = 0; n < 2; ++n) _Pragma("unroll") for (int k = 0; k < 2; ++k) dst[n][k] = *(const PG8_LAS bf16x8*)(lds + PG8_SB(b, h) + boff + n * 2048 + k * 1024); } while (0)
; #define PG8_MMA(ai, bj, At, Bt) do { __builtin_amdgcn_s_setprio(1); _Pragma("unroll") for (int m = 0; m < 4; ++m) _Pragma("unroll") for (int n = 0; n < 2; ++n) _Pragma("unroll") for (int k = 0; k < 2; ++k) \
;         acc[ai][bj][m][n] = __builtin_amdgcn_mfma_f32_16x16x32_bf16(Bt[n][k], At[m][k], acc[ai][bj][m][n], 0, 0, 0); __builtin_amdgcn_s_setprio(0); } while (0)
; #define PG8_WAIT_V(n) asm volatile("s_waitcnt vmcnt(" #n ")" ::: "memory")
; #define PG8_WAIT_L(n) asm volatile("s_waitcnt lgkmcnt(" #n ")" ::: "memory")
; #define PG8_BAR __builtin_amdgcn_s_barrier()
; #define PG8_SCHED __builtin_amdgcn_sched_barrier(0)
; template <class Epi, class Sched, bool ALIGN_EPI = false, bool SP2 = false>
; __device__ __forceinline__ void gemm_phase(PG8_LAS unsigned char* lds, const Gemm g, const Sched& S, const Epi& E) {
;     ...
;             PG8_WAIT_V(8); PG8_WAIT_L(0); PG8_BAR; PG8_MMA(1, 0, At, B0); PG8_MMA(1, 1, At, B1); PG8_BAR; PG8_SCHED;
;             PG8_LDB(B0, 1, 0); PG8_LDB(B1, 1, 1); PG8_SCHED; PG8_LDA(At, 1, 0); PG8_STAGE(PG8_SA(0, 1), a2 + hstepA, voffA);
;             PG8_WAIT_V(8); PG8_WAIT_L(0); PG8_BAR; PG8_MMA(0, 0, At, B0); PG8_MMA(0, 1, At, B1); PG8_BAR; PG8_SCHED;
	s_waitcnt lgkmcnt(0)
	v_mfma_f32_16x16x32_bf16 v[60:63], v[144:147], v[184:187], v[60:63]
	v_mfma_f32_16x16x32_bf16 v[56:59], v[160:163], v[184:187], v[56:59]
	v_mfma_f32_16x16x32_bf16 v[44:47], v[144:147], v[194:197], v[44:47]
	v_mfma_f32_16x16x32_bf16 v[40:43], v[160:163], v[194:197], v[40:43]
	v_mfma_f32_16x16x32_bf16 v[28:31], v[144:147], v[202:205], v[28:31]
	v_mfma_f32_16x16x32_bf16 v[24:27], v[160:163], v[202:205], v[24:27]
	v_mfma_f32_16x16x32_bf16 v[12:15], v[144:147], v[210:213], v[12:15]
	v_mfma_f32_16x16x32_bf16 v[8:11], v[160:163], v[210:213], v[8:11]
	v_mfma_f32_16x16x32_bf16 v[60:63], v[156:159], v[188:191], v[60:63]
	v_mfma_f32_16x16x32_bf16 v[56:59], v[164:167], v[188:191], v[56:59]
	v_mfma_f32_16x16x32_bf16 v[44:47], v[156:159], v[198:201], v[44:47]
	v_mfma_f32_16x16x32_bf16 v[40:43], v[164:167], v[198:201], v[40:43]
	v_mfma_f32_16x16x32_bf16 v[28:31], v[156:159], v[206:209], v[28:31]
	v_mfma_f32_16x16x32_bf16 v[24:27], v[164:167], v[206:209], v[24:27]
	v_mfma_f32_16x16x32_bf16 v[12:15], v[156:159], v[214:217], v[12:15]
	v_mfma_f32_16x16x32_bf16 v[8:11], v[164:167], v[214:217], v[8:11]
	v_mfma_f32_16x16x32_bf16 v[52:55], v[168:171], v[184:187], v[52:55]
	v_mfma_f32_16x16x32_bf16 v[48:51], v[176:179], v[184:187], v[48:51]
	v_mfma_f32_16x16x32_bf16 v[36:39], v[168:171], v[194:197], v[36:39]
	v_mfma_f32_16x16x32_bf16 v[32:35], v[176:179], v[194:197], v[32:35]
	v_mfma_f32_16x16x32_bf16 v[20:23], v[168:171], v[202:205], v[20:23]
	v_mfma_f32_16x16x32_bf16 v[16:19], v[176:179], v[202:205], v[16:19]
	v_mfma_f32_16x16x32_bf16 v[4:7], v[168:171], v[210:213], v[4:7]
	v_mfma_f32_16x16x32_bf16 v[0:3], v[176:179], v[210:213], v[0:3]
	v_mfma_f32_16x16x32_bf16 v[52:55], v[172:175], v[188:191], v[52:55]
	v_mfma_f32_16x16x32_bf16 v[48:51], v[180:183], v[188:191], v[48:51]
	v_mfma_f32_16x16x32_bf16 v[36:39], v[172:175], v[198:201], v[36:39]
	v_mfma_f32_16x16x32_bf16 v[32:35], v[180:183], v[198:201], v[32:35]
	v_mfma_f32_16x16x32_bf16 v[20:23], v[172:175], v[206:209], v[20:23]
	v_mfma_f32_16x16x32_bf16 v[16:19], v[180:183], v[206:209], v[16:19]
	v_mfma_f32_16x16x32_bf16 v[4:7], v[172:175], v[214:217], v[4:7]
	v_mfma_f32_16x16x32_bf16 v[0:3], v[180:183], v[214:217], v[0:3]
	s_barrier
	s_add_i32 s64, 0, 0x18000
	v_add_u32_e32 v155, s64, v150
	s_add_i32 s65, 0, 0x1c000
	ds_read_b128 v[144:147], v155
	ds_read_b128 v[156:159], v155 offset:1024
	ds_read_b128 v[160:163], v155 offset:2048
	ds_read_b128 v[164:167], v155 offset:3072
	v_add_u32_e32 v155, s65, v150
	ds_read_b128 v[168:171], v155
	ds_read_b128 v[172:175], v155 offset:1024
	ds_read_b128 v[176:179], v155 offset:2048
	ds_read_b128 v[180:183], v155 offset:3072
	s_add_u32 s48, s48, 0x40000
	s_addc_u32 s49, s49, 0
	s_mov_b32 m0, s52
	v_lshl_add_u64 v[224:225], s[48:49], 0, v[128:129]
	ds_read_b128 v[184:187], v153 offset:32768
	ds_read_b128 v[188:191], v153 offset:33792
	ds_read_b128 v[194:197], v153 offset:34816
	ds_read_b128 v[198:201], v153 offset:35840
	ds_read_b128 v[202:205], v153 offset:36864
	ds_read_b128 v[206:209], v153 offset:37888
	ds_read_b128 v[210:213], v153 offset:38912
	ds_read_b128 v[214:217], v153 offset:39936
	global_load_lds_dwordx4 v[224:225], off
	v_lshl_add_u64 v[224:225], s[48:49], 0, v[132:133]
	s_mov_b32 m0, s53
	s_nop 0
	global_load_lds_dwordx4 v[224:225], off
	s_waitcnt vmcnt(8)
	s_waitcnt lgkmcnt(0)
	s_barrier
	s_waitcnt lgkmcnt(0)
	v_mfma_f32_16x16x32_bf16 v[124:127], v[144:147], v[184:187], v[124:127]
	v_mfma_f32_16x16x32_bf16 v[120:123], v[160:163], v[184:187], v[120:123]
	v_mfma_f32_16x16x32_bf16 v[108:111], v[144:147], v[194:197], v[108:111]
	v_mfma_f32_16x16x32_bf16 v[104:107], v[160:163], v[194:197], v[104:107]
	v_mfma_f32_16x16x32_bf16 v[92:95], v[144:147], v[202:205], v[92:95]
	v_mfma_f32_16x16x32_bf16 v[88:91], v[160:163], v[202:205], v[88:91]
	v_mfma_f32_16x16x32_bf16 v[76:79], v[144:147], v[210:213], v[76:79]
	v_mfma_f32_16x16x32_bf16 v[72:75], v[160:163], v[210:213], v[72:75]
	v_mfma_f32_16x16x32_bf16 v[124:127], v[156:159], v[188:191], v[124:127]
	v_mfma_f32_16x16x32_bf16 v[120:123], v[164:167], v[188:191], v[120:123]
	v_mfma_f32_16x16x32_bf16 v[108:111], v[156:159], v[198:201], v[108:111]
	v_mfma_f32_16x16x32_bf16 v[104:107], v[164:167], v[198:201], v[104:107]
	v_mfma_f32_16x16x32_bf16 v[92:95], v[156:159], v[206:209], v[92:95]
	v_mfma_f32_16x16x32_bf16 v[88:91], v[164:167], v[206:209], v[88:91]
	v_mfma_f32_16x16x32_bf16 v[76:79], v[156:159], v[214:217], v[76:79]
	v_mfma_f32_16x16x32_bf16 v[72:75], v[164:167], v[214:217], v[72:75]
	v_mfma_f32_16x16x32_bf16 v[116:119], v[168:171], v[184:187], v[116:119]
	v_mfma_f32_16x16x32_bf16 v[112:115], v[176:179], v[184:187], v[112:115]
	v_mfma_f32_16x16x32_bf16 v[100:103], v[168:171], v[194:197], v[100:103]
	v_mfma_f32_16x16x32_bf16 v[96:99], v[176:179], v[194:197], v[96:99]
	v_mfma_f32_16x16x32_bf16 v[84:87], v[168:171], v[202:205], v[84:87]
	v_mfma_f32_16x16x32_bf16 v[80:83], v[176:179], v[202:205], v[80:83]
	v_mfma_f32_16x16x32_bf16 v[68:71], v[168:171], v[210:213], v[68:71]
	v_mfma_f32_16x16x32_bf16 v[64:67], v[176:179], v[210:213], v[64:67]
	v_mfma_f32_16x16x32_bf16 v[116:119], v[172:175], v[188:191], v[116:119]
	v_mfma_f32_16x16x32_bf16 v[112:115], v[180:183], v[188:191], v[112:115]
	v_mfma_f32_16x16x32_bf16 v[100:103], v[172:175], v[198:201], v[100:103]
	v_mfma_f32_16x16x32_bf16 v[96:99], v[180:183], v[198:201], v[96:99]
	v_mfma_f32_16x16x32_bf16 v[84:87], v[172:175], v[206:209], v[84:87]
	v_mfma_f32_16x16x32_bf16 v[80:83], v[180:183], v[206:209], v[80:83]
	v_mfma_f32_16x16x32_bf16 v[68:71], v[172:175], v[214:217], v[68:71]
	v_mfma_f32_16x16x32_bf16 v[64:67], v[180:183], v[214:217], v[64:67]
	s_barrier
; #define PG8_STAGE(bufoff, gbase, voff) do { _Pragma("unroll") for (int _i = 0; _i < 2; ++_i) \
;         __builtin_amdgcn_global_load_lds((const unsigned*)((const char*)(gbase) + (voff)[_i]), (PG8_LAS unsigned*)(lds + (bufoff) + ldsw + _i * 8192), 16, 0, 0); } while (0)
; #define PG8_LDA(dst, b, h) do { _Pragma("unroll") for (int m = 0; m < 4; ++m) _Pragma("unroll") for (int k = 0; k < 2; ++k) dst[m][k] = *(const PG8_LAS bf16x8*)(lds + PG8_SA(b, h) + aoff + m * 2048 + k * 1024); } while (0)
; #define PG8_MMA(ai, bj, At, Bt) do { __builtin_amdgcn_s_setprio(1); _Pragma("unroll") for (int m = 0; m < 4; ++m) _Pragma("unroll") for (int n = 0; n < 2; ++n) _Pragma("unroll") for (int k = 0; k < 2; ++k) \
;         acc[ai][bj][m][n] = __builtin_amdgcn_mfma_f32_16x16x32_bf16(Bt[n][k], At[m][k], acc[ai][bj][m][n], 0, 0, 0); __builtin_amdgcn_s_setprio(0); } while (0)
; #define PG8_WAIT_V(n) asm volatile("s_waitcnt vmcnt(" #n ")" ::: "memory")
; #define PG8_WAIT_L(n) asm volatile("s_waitcnt lgkmcnt(" #n ")" ::: "memory")
; #define PG8_BAR __builtin_amdgcn_s_barrier()
; #define PG8_SCHED __builtin_amdgcn_sched_barrier(0)
; template <class Epi, class Sched, bool ALIGN_EPI = false, bool SP2 = false>
; __device__ __forceinline__ void gemm_phase(PG8_LAS unsigned char* lds, const Gemm g, const Sched& S, const Epi& E) {
;     ...
;             PG8_LDA(At, 1, 1); PG8_STAGE(PG8_SB(1, 0), b3, voffB); PG8_STAGE(PG8_SB(1, 1), b3 + hstepB, voffB); PG8_STAGE(PG8_SA(1, 0), a3, voffA);
;             PG8_WAIT_V(8); PG8_WAIT_L(0); PG8_BAR; PG8_MMA(1, 0, At, B0); PG8_MMA(1, 1, At, B1); PG8_BAR; PG8_SCHED;
	s_add_i32 s48, s64, s50
	v_lshl_add_u64 v[192:193], v[192:193], 0, s[10:11]
	s_mov_b32 m0, s48
	ds_read_b128 v[184:187], v153 offset:49152
	ds_read_b128 v[188:191], v153 offset:50176
	ds_read_b128 v[194:197], v153 offset:51200
	ds_read_b128 v[198:201], v153 offset:52224
	ds_read_b128 v[202:205], v153 offset:53248
	ds_read_b128 v[206:209], v153 offset:54272
	ds_read_b128 v[210:213], v153 offset:55296
	ds_read_b128 v[214:217], v153 offset:56320
	global_load_lds_dwordx4 v[192:193], off
	s_add_i32 m0, s48, 0x2000
	s_add_u32 s44, s44, 0x40080
	v_lshl_add_u64 v[192:193], v[218:219], 0, s[10:11]
	s_addc_u32 s45, s45, 0
	s_add_i32 s48, s65, s50
	global_load_lds_dwordx4 v[192:193], off
	v_lshl_add_u64 v[192:193], s[44:45], 0, v[130:131]
	s_mov_b32 m0, s48
	s_nop 0
	global_load_lds_dwordx4 v[192:193], off
	v_lshl_add_u64 v[192:193], s[44:45], 0, v[134:135]
	s_add_i32 m0, s48, 0x2000
	s_nop 0
	global_load_lds_dwordx4 v[192:193], off
	v_lshl_add_u64 v[192:193], v[220:221], 0, s[10:11]
	s_mov_b32 m0, s57
	s_nop 0
	global_load_lds_dwordx4 v[192:193], off
	v_lshl_add_u64 v[192:193], v[222:223], 0, s[10:11]
	s_mov_b32 m0, s58
	s_nop 0
	global_load_lds_dwordx4 v[192:193], off
	s_waitcnt vmcnt(8)
	s_waitcnt lgkmcnt(0)
	s_barrier
	s_waitcnt lgkmcnt(0)
	v_mfma_f32_16x16x32_bf16 v[60:63], v[144:147], v[184:187], v[60:63]
	v_mfma_f32_16x16x32_bf16 v[56:59], v[160:163], v[184:187], v[56:59]
	v_mfma_f32_16x16x32_bf16 v[44:47], v[144:147], v[194:197], v[44:47]
	v_mfma_f32_16x16x32_bf16 v[40:43], v[160:163], v[194:197], v[40:43]
	v_mfma_f32_16x16x32_bf16 v[28:31], v[144:147], v[202:205], v[28:31]
	v_mfma_f32_16x16x32_bf16 v[24:27], v[160:163], v[202:205], v[24:27]
	v_mfma_f32_16x16x32_bf16 v[12:15], v[144:147], v[210:213], v[12:15]
	v_mfma_f32_16x16x32_bf16 v[8:11], v[160:163], v[210:213], v[8:11]
	v_mfma_f32_16x16x32_bf16 v[60:63], v[156:159], v[188:191], v[60:63]
	v_mfma_f32_16x16x32_bf16 v[56:59], v[164:167], v[188:191], v[56:59]
	v_mfma_f32_16x16x32_bf16 v[44:47], v[156:159], v[198:201], v[44:47]
	v_mfma_f32_16x16x32_bf16 v[40:43], v[164:167], v[198:201], v[40:43]
	v_mfma_f32_16x16x32_bf16 v[28:31], v[156:159], v[206:209], v[28:31]
	v_mfma_f32_16x16x32_bf16 v[24:27], v[164:167], v[206:209], v[24:27]
	v_mfma_f32_16x16x32_bf16 v[12:15], v[156:159], v[214:217], v[12:15]
	v_mfma_f32_16x16x32_bf16 v[8:11], v[164:167], v[214:217], v[8:11]
	v_mfma_f32_16x16x32_bf16 v[52:55], v[168:171], v[184:187], v[52:55]
	v_mfma_f32_16x16x32_bf16 v[48:51], v[176:179], v[184:187], v[48:51]
	v_mfma_f32_16x16x32_bf16 v[36:39], v[168:171], v[194:197], v[36:39]
	v_mfma_f32_16x16x32_bf16 v[32:35], v[176:179], v[194:197], v[32:35]
	v_mfma_f32_16x16x32_bf16 v[20:23], v[168:171], v[202:205], v[20:23]
	v_mfma_f32_16x16x32_bf16 v[16:19], v[176:179], v[202:205], v[16:19]
	v_mfma_f32_16x16x32_bf16 v[4:7], v[168:171], v[210:213], v[4:7]
	v_mfma_f32_16x16x32_bf16 v[0:3], v[176:179], v[210:213], v[0:3]
	v_mfma_f32_16x16x32_bf16 v[52:55], v[172:175], v[188:191], v[52:55]
	v_mfma_f32_16x16x32_bf16 v[48:51], v[180:183], v[188:191], v[48:51]
	v_mfma_f32_16x16x32_bf16 v[36:39], v[172:175], v[198:201], v[36:39]
	v_mfma_f32_16x16x32_bf16 v[32:35], v[180:183], v[198:201], v[32:35]
	v_mfma_f32_16x16x32_bf16 v[20:23], v[172:175], v[206:209], v[20:23]
	v_mfma_f32_16x16x32_bf16 v[16:19], v[180:183], v[206:209], v[16:19]
	v_mfma_f32_16x16x32_bf16 v[4:7], v[172:175], v[214:217], v[4:7]
	v_mfma_f32_16x16x32_bf16 v[0:3], v[180:183], v[214:217], v[0:3]
	s_barrier
	s_add_i32 s63, s63, 2
	s_add_u32 s40, s40, 0x100
	s_addc_u32 s41, s41, 0
	s_add_u32 s42, s42, 0x100
	s_addc_u32 s62, s62, 0
	s_cmp_gt_u32 s63, 13
	s_cbranch_scc0 .LBB0_724
	s_and_b64 vcc, exec, s[12:13]
	s_cbranch_vccz .LBB0_727
	s_barrier
